# GEMM K-loops: merged phase pairs, 8 barriers per 2 K-tiles instead of 16
# speedup vs baseline: 1.0098x; 1.0098x over previous
.LBB0_98:
	v_and_b32_e32 v0, 48, v134
	s_lshl_b32 s15, s15, 5
	v_lshlrev_b32_e32 v1, 6, v134
	s_movk_i32 s28, 0x3c0
	v_and_or_b32 v0, v1, s28, v0
	v_lshlrev_b32_e32 v1, 2, v134
	s_and_b32 s64, s15, 0x60
	s_lshl_b32 s63, s14, 6
	v_and_b32_e32 v1, 32, v1
	s_lshl_b32 s14, s14, 13
	s_lshl_b32 s15, s64, 7
	s_waitcnt vmcnt(8)
	s_barrier
	s_waitcnt vmcnt(6)
	v_bitop3_b32 v2, v0, s14, v1 bitop3:0xde
	v_bitop3_b32 v135, s15, v0, v1 bitop3:0xf6
	v_mov_b32_e32 v0, 0
	s_mov_b32 s34, 0
	s_mov_b64 s[14:15], -1
	s_mov_b64 s[28:29], 0
	v_add_u32_e32 v136, 0, v2
	v_mov_b32_e32 v1, v0
	v_mov_b32_e32 v2, v0
	v_mov_b32_e32 v3, v0
	v_mov_b32_e32 v4, v0
	v_mov_b32_e32 v5, v0
	v_mov_b32_e32 v6, v0
	v_mov_b32_e32 v7, v0
	v_mov_b32_e32 v8, v0
	v_mov_b32_e32 v9, v0
	v_mov_b32_e32 v10, v0
	v_mov_b32_e32 v11, v0
	v_mov_b32_e32 v16, v0
	v_mov_b32_e32 v17, v0
	v_mov_b32_e32 v18, v0
	v_mov_b32_e32 v19, v0
	v_mov_b32_e32 v24, v0
	v_mov_b32_e32 v25, v0
	v_mov_b32_e32 v26, v0
	v_mov_b32_e32 v27, v0
	v_mov_b32_e32 v32, v0
	v_mov_b32_e32 v33, v0
	v_mov_b32_e32 v34, v0
	v_mov_b32_e32 v35, v0
	v_mov_b32_e32 v40, v0
	v_mov_b32_e32 v41, v0
	v_mov_b32_e32 v42, v0
	v_mov_b32_e32 v43, v0
	v_mov_b32_e32 v48, v0
	v_mov_b32_e32 v49, v0
	v_mov_b32_e32 v50, v0
	v_mov_b32_e32 v51, v0
	v_mov_b32_e32 v12, v0
	v_mov_b32_e32 v13, v0
	v_mov_b32_e32 v14, v0
	v_mov_b32_e32 v15, v0
	v_mov_b32_e32 v20, v0
	v_mov_b32_e32 v21, v0
	v_mov_b32_e32 v22, v0
	v_mov_b32_e32 v23, v0
	v_mov_b32_e32 v28, v0
	v_mov_b32_e32 v29, v0
	v_mov_b32_e32 v30, v0
	v_mov_b32_e32 v31, v0
	v_mov_b32_e32 v36, v0
	v_mov_b32_e32 v37, v0
	v_mov_b32_e32 v38, v0
	v_mov_b32_e32 v39, v0
	v_mov_b32_e32 v44, v0
	v_mov_b32_e32 v45, v0
	v_mov_b32_e32 v46, v0
	v_mov_b32_e32 v47, v0
	v_mov_b32_e32 v52, v0
	v_mov_b32_e32 v53, v0
	v_mov_b32_e32 v54, v0
	v_mov_b32_e32 v55, v0
	v_mov_b32_e32 v56, v0
	v_mov_b32_e32 v57, v0
	v_mov_b32_e32 v58, v0
	v_mov_b32_e32 v59, v0
	v_mov_b32_e32 v60, v0
	v_mov_b32_e32 v61, v0
	v_mov_b32_e32 v62, v0
	v_mov_b32_e32 v63, v0
	v_mov_b32_e32 v64, v0
	v_mov_b32_e32 v65, v0
	v_mov_b32_e32 v66, v0
	v_mov_b32_e32 v67, v0
	v_mov_b32_e32 v68, v0
	v_mov_b32_e32 v69, v0
	v_mov_b32_e32 v70, v0
	v_mov_b32_e32 v71, v0
	v_mov_b32_e32 v72, v0
	v_mov_b32_e32 v73, v0
	v_mov_b32_e32 v74, v0
	v_mov_b32_e32 v75, v0
	v_mov_b32_e32 v80, v0
	v_mov_b32_e32 v81, v0
	v_mov_b32_e32 v82, v0
	v_mov_b32_e32 v83, v0
	v_mov_b32_e32 v88, v0
	v_mov_b32_e32 v89, v0
	v_mov_b32_e32 v90, v0
	v_mov_b32_e32 v91, v0
	v_mov_b32_e32 v96, v0
	v_mov_b32_e32 v97, v0
	v_mov_b32_e32 v98, v0
	v_mov_b32_e32 v99, v0
	v_mov_b32_e32 v104, v0
	v_mov_b32_e32 v105, v0
	v_mov_b32_e32 v106, v0
	v_mov_b32_e32 v107, v0
	v_mov_b32_e32 v112, v0
	v_mov_b32_e32 v113, v0
	v_mov_b32_e32 v114, v0
	v_mov_b32_e32 v115, v0
	v_mov_b32_e32 v76, v0
	v_mov_b32_e32 v77, v0
	v_mov_b32_e32 v78, v0
	v_mov_b32_e32 v79, v0
	v_mov_b32_e32 v84, v0
	v_mov_b32_e32 v85, v0
	v_mov_b32_e32 v86, v0
	v_mov_b32_e32 v87, v0
	v_mov_b32_e32 v92, v0
	v_mov_b32_e32 v93, v0
	v_mov_b32_e32 v94, v0
	v_mov_b32_e32 v95, v0
	v_mov_b32_e32 v100, v0
	v_mov_b32_e32 v101, v0
	v_mov_b32_e32 v102, v0
	v_mov_b32_e32 v103, v0
	v_mov_b32_e32 v108, v0
	v_mov_b32_e32 v109, v0
	v_mov_b32_e32 v110, v0
	v_mov_b32_e32 v111, v0
	v_mov_b32_e32 v116, v0
	v_mov_b32_e32 v117, v0
	v_mov_b32_e32 v118, v0
	v_mov_b32_e32 v119, v0
	v_mov_b32_e32 v120, v0
	v_mov_b32_e32 v121, v0
	v_mov_b32_e32 v122, v0
	v_mov_b32_e32 v123, v0
	v_mov_b32_e32 v124, v0
	v_mov_b32_e32 v125, v0
	v_mov_b32_e32 v126, v0
	v_mov_b32_e32 v127, v0
	s_barrier
.LBB0_99:
	s_add_i32 s35, s34, 0x100
	s_and_b64 s[28:29], s[28:29], exec
	s_cselect_b32 s29, 0, s35
	s_cselect_b32 s28, 0, 0
	s_add_u32 s38, s12, s29
	s_addc_u32 s39, s13, s28
	s_add_i32 s47, 0, 0x10000
	s_add_u32 s40, s2, s29
	s_addc_u32 s41, s3, s28
	s_add_u32 s48, s4, s34
	s_addc_u32 s49, s5, 0
	s_add_i32 vcc_lo, s47, s52
	s_add_i32 m0, s9, 0xc000
	s_add_i32 s53, s9, 0xe000
	s_add_i32 vcc_hi, 0, 0x14000
	s_add_i32 s46, vcc_lo, 0x2000
	s_add_u32 s36, s40, 0x28000
	s_addc_u32 s37, s41, 0
	s_add_i32 s75, vcc_hi, s52
	s_add_i32 s74, s75, 0x2000
	s_add_i32 s71, 0, 0x18000
	s_add_u32 s34, s38, 0x10000
	s_addc_u32 s35, s39, 0
	s_add_i32 s69, s71, s52
	s_add_i32 s67, 0, 0x1c000
	s_add_i32 s66, s69, 0x2000
	s_add_u32 s28, s40, 0x28080
	s_addc_u32 s29, s41, 0
	s_add_i32 s79, s67, s52
	s_add_i32 s78, s79, 0x2000
	v_lshl_add_u64 v[186:187], s[48:49], 0, v[128:129]
	v_lshl_add_u64 v[186:187], v[186:187], 0, s[72:73]
	global_load_lds_dwordx4 v[186:187], off
	v_lshl_add_u64 v[186:187], s[48:49], 0, v[130:131]
	v_lshl_add_u64 v[186:187], v[186:187], 0, s[72:73]
	s_mov_b32 m0, s53
	s_nop 0
	global_load_lds_dwordx4 v[186:187], off
	v_add_u32_e32 v137, 0x10000, v135
	ds_read_b128 v[138:141], v137
	ds_read_b128 v[142:145], v137 offset:1024
	ds_read_b128 v[146:149], v137 offset:2048
	ds_read_b128 v[150:153], v137 offset:3072
	ds_read_b128 v[154:157], v136
	ds_read_b128 v[158:161], v136 offset:1024
	ds_read_b128 v[162:165], v136 offset:2048
	ds_read_b128 v[166:169], v136 offset:3072
	ds_read_b128 v[170:173], v136 offset:4096
	ds_read_b128 v[174:177], v136 offset:5120
	ds_read_b128 v[178:181], v136 offset:6144
	ds_read_b128 v[182:185], v136 offset:7168
	v_add_u32_e32 v137, 0x14000, v135
	ds_read_b128 v[186:189], v137
	ds_read_b128 v[194:197], v137 offset:1024
	ds_read_b128 v[198:201], v137 offset:2048
	ds_read_b128 v[202:205], v137 offset:3072
	s_waitcnt vmcnt(8)
	s_waitcnt lgkmcnt(0)
	s_barrier
	s_setprio 1
	v_mfma_f32_16x16x32_bf16 v[124:127], v[138:141], v[154:157], v[124:127]
	v_mfma_f32_16x16x32_bf16 v[120:123], v[146:149], v[154:157], v[120:123]
	v_mfma_f32_16x16x32_bf16 v[116:119], v[138:141], v[162:165], v[116:119]
	v_mfma_f32_16x16x32_bf16 v[108:111], v[146:149], v[162:165], v[108:111]
	v_mfma_f32_16x16x32_bf16 v[100:103], v[138:141], v[170:173], v[100:103]
	v_mfma_f32_16x16x32_bf16 v[92:95], v[146:149], v[170:173], v[92:95]
	v_mfma_f32_16x16x32_bf16 v[84:87], v[138:141], v[178:181], v[84:87]
	v_mfma_f32_16x16x32_bf16 v[76:79], v[146:149], v[178:181], v[76:79]
	v_mfma_f32_16x16x32_bf16 v[124:127], v[142:145], v[158:161], v[124:127]
	v_mfma_f32_16x16x32_bf16 v[120:123], v[150:153], v[158:161], v[120:123]
	v_mfma_f32_16x16x32_bf16 v[116:119], v[142:145], v[166:169], v[116:119]
	v_mfma_f32_16x16x32_bf16 v[108:111], v[150:153], v[166:169], v[108:111]
	v_mfma_f32_16x16x32_bf16 v[100:103], v[142:145], v[174:177], v[100:103]
	v_mfma_f32_16x16x32_bf16 v[92:95], v[150:153], v[174:177], v[92:95]
	v_mfma_f32_16x16x32_bf16 v[84:87], v[142:145], v[182:185], v[84:87]
	v_mfma_f32_16x16x32_bf16 v[76:79], v[150:153], v[182:185], v[76:79]
	v_mfma_f32_16x16x32_bf16 v[112:115], v[186:189], v[154:157], v[112:115]
	v_mfma_f32_16x16x32_bf16 v[104:107], v[198:201], v[154:157], v[104:107]
	v_mfma_f32_16x16x32_bf16 v[96:99], v[186:189], v[162:165], v[96:99]
	v_mfma_f32_16x16x32_bf16 v[88:91], v[198:201], v[162:165], v[88:91]
	v_mfma_f32_16x16x32_bf16 v[80:83], v[186:189], v[170:173], v[80:83]
	v_mfma_f32_16x16x32_bf16 v[72:75], v[198:201], v[170:173], v[72:75]
	v_mfma_f32_16x16x32_bf16 v[68:71], v[186:189], v[178:181], v[68:71]
	v_mfma_f32_16x16x32_bf16 v[64:67], v[198:201], v[178:181], v[64:67]
	v_mfma_f32_16x16x32_bf16 v[112:115], v[194:197], v[158:161], v[112:115]
	v_mfma_f32_16x16x32_bf16 v[104:107], v[202:205], v[158:161], v[104:107]
	v_mfma_f32_16x16x32_bf16 v[96:99], v[194:197], v[166:169], v[96:99]
	v_mfma_f32_16x16x32_bf16 v[88:91], v[202:205], v[166:169], v[88:91]
	v_mfma_f32_16x16x32_bf16 v[80:83], v[194:197], v[174:177], v[80:83]
	v_mfma_f32_16x16x32_bf16 v[72:75], v[202:205], v[174:177], v[72:75]
	v_mfma_f32_16x16x32_bf16 v[68:71], v[194:197], v[182:185], v[68:71]
	v_mfma_f32_16x16x32_bf16 v[64:67], v[202:205], v[182:185], v[64:67]
	s_setprio 0
	s_barrier
	s_mov_b32 m0, vcc_lo
	v_lshl_add_u64 v[190:191], s[40:41], 0, v[192:193]
	global_load_lds_dwordx4 v[190:191], off
	v_lshl_add_u64 v[206:207], s[40:41], 0, v[132:133]
	s_mov_b32 m0, s46
	s_nop 0
	global_load_lds_dwordx4 v[206:207], off
	s_mov_b32 m0, s9
	v_lshl_add_u64 v[208:209], s[38:39], 0, v[128:129]
	global_load_lds_dwordx4 v[208:209], off
	v_lshl_add_u64 v[210:211], s[38:39], 0, v[130:131]
	s_mov_b32 m0, s54
	s_nop 0
	global_load_lds_dwordx4 v[210:211], off
	s_mov_b32 m0, s75
	v_lshl_add_u64 v[154:155], s[36:37], 0, v[192:193]
	global_load_lds_dwordx4 v[154:155], off
	v_lshl_add_u64 v[156:157], s[36:37], 0, v[132:133]
	s_mov_b32 m0, s74
	s_nop 0
	global_load_lds_dwordx4 v[156:157], off
	ds_read_b128 v[154:157], v136 offset:16384
	ds_read_b128 v[158:161], v136 offset:17408
	ds_read_b128 v[162:165], v136 offset:18432
	ds_read_b128 v[166:169], v136 offset:19456
	ds_read_b128 v[170:173], v136 offset:20480
	ds_read_b128 v[174:177], v136 offset:21504
	ds_read_b128 v[178:181], v136 offset:22528
	ds_read_b128 v[182:185], v136 offset:23552
	s_waitcnt vmcnt(8)
	s_waitcnt lgkmcnt(0)
	s_barrier
	s_setprio 1
	v_mfma_f32_16x16x32_bf16 v[60:63], v[138:141], v[154:157], v[60:63]
	v_mfma_f32_16x16x32_bf16 v[56:59], v[146:149], v[154:157], v[56:59]
	v_mfma_f32_16x16x32_bf16 v[52:55], v[138:141], v[162:165], v[52:55]
	v_mfma_f32_16x16x32_bf16 v[44:47], v[146:149], v[162:165], v[44:47]
	v_mfma_f32_16x16x32_bf16 v[36:39], v[138:141], v[170:173], v[36:39]
	v_mfma_f32_16x16x32_bf16 v[28:31], v[146:149], v[170:173], v[28:31]
	v_mfma_f32_16x16x32_bf16 v[20:23], v[138:141], v[178:181], v[20:23]
	v_mfma_f32_16x16x32_bf16 v[12:15], v[146:149], v[178:181], v[12:15]
	v_mfma_f32_16x16x32_bf16 v[60:63], v[142:145], v[158:161], v[60:63]
	v_mfma_f32_16x16x32_bf16 v[56:59], v[150:153], v[158:161], v[56:59]
	v_mfma_f32_16x16x32_bf16 v[52:55], v[142:145], v[166:169], v[52:55]
	v_mfma_f32_16x16x32_bf16 v[44:47], v[150:153], v[166:169], v[44:47]
	v_mfma_f32_16x16x32_bf16 v[36:39], v[142:145], v[174:177], v[36:39]
	v_mfma_f32_16x16x32_bf16 v[28:31], v[150:153], v[174:177], v[28:31]
	v_mfma_f32_16x16x32_bf16 v[20:23], v[142:145], v[182:185], v[20:23]
	v_mfma_f32_16x16x32_bf16 v[12:15], v[150:153], v[182:185], v[12:15]
	v_mfma_f32_16x16x32_bf16 v[48:51], v[186:189], v[154:157], v[48:51]
	v_mfma_f32_16x16x32_bf16 v[40:43], v[198:201], v[154:157], v[40:43]
	v_mfma_f32_16x16x32_bf16 v[32:35], v[186:189], v[162:165], v[32:35]
	v_mfma_f32_16x16x32_bf16 v[24:27], v[198:201], v[162:165], v[24:27]
	v_mfma_f32_16x16x32_bf16 v[16:19], v[186:189], v[170:173], v[16:19]
	v_mfma_f32_16x16x32_bf16 v[8:11], v[198:201], v[170:173], v[8:11]
	v_mfma_f32_16x16x32_bf16 v[4:7], v[186:189], v[178:181], v[4:7]
	v_mfma_f32_16x16x32_bf16 v[0:3], v[198:201], v[178:181], v[0:3]
	v_mfma_f32_16x16x32_bf16 v[48:51], v[194:197], v[158:161], v[48:51]
	v_mfma_f32_16x16x32_bf16 v[40:43], v[202:205], v[158:161], v[40:43]
	v_mfma_f32_16x16x32_bf16 v[32:35], v[194:197], v[166:169], v[32:35]
	v_mfma_f32_16x16x32_bf16 v[24:27], v[202:205], v[166:169], v[24:27]
	v_mfma_f32_16x16x32_bf16 v[16:19], v[194:197], v[174:177], v[16:19]
	v_mfma_f32_16x16x32_bf16 v[8:11], v[202:205], v[174:177], v[8:11]
	v_mfma_f32_16x16x32_bf16 v[4:7], v[194:197], v[182:185], v[4:7]
	v_mfma_f32_16x16x32_bf16 v[0:3], v[202:205], v[182:185], v[0:3]
	s_setprio 0
	s_barrier
	s_mov_b32 m0, s55
	v_lshl_add_u64 v[186:187], s[34:35], 0, v[128:129]
	global_load_lds_dwordx4 v[186:187], off
	v_lshl_add_u64 v[186:187], s[34:35], 0, v[130:131]
	s_mov_b32 m0, s58
	s_nop 0
	global_load_lds_dwordx4 v[186:187], off
	v_add_u32_e32 v137, 0x18000, v135
	ds_read_b128 v[138:141], v137
	ds_read_b128 v[142:145], v137 offset:1024
	ds_read_b128 v[146:149], v137 offset:2048
	ds_read_b128 v[150:153], v137 offset:3072
	ds_read_b128 v[154:157], v136 offset:32768
	ds_read_b128 v[158:161], v136 offset:33792
	ds_read_b128 v[162:165], v136 offset:34816
	ds_read_b128 v[166:169], v136 offset:35840
	ds_read_b128 v[170:173], v136 offset:36864
	ds_read_b128 v[174:177], v136 offset:37888
	ds_read_b128 v[178:181], v136 offset:38912
	ds_read_b128 v[182:185], v136 offset:39936
	v_add_u32_e32 v137, 0x1c000, v135
	ds_read_b128 v[186:189], v137
	ds_read_b128 v[194:197], v137 offset:1024
	ds_read_b128 v[198:201], v137 offset:2048
	ds_read_b128 v[202:205], v137 offset:3072
	s_waitcnt vmcnt(8)
	s_waitcnt lgkmcnt(0)
	s_barrier
	s_setprio 1
	v_mfma_f32_16x16x32_bf16 v[124:127], v[138:141], v[154:157], v[124:127]
	v_mfma_f32_16x16x32_bf16 v[120:123], v[146:149], v[154:157], v[120:123]
	v_mfma_f32_16x16x32_bf16 v[116:119], v[138:141], v[162:165], v[116:119]
	v_mfma_f32_16x16x32_bf16 v[108:111], v[146:149], v[162:165], v[108:111]
	v_mfma_f32_16x16x32_bf16 v[100:103], v[138:141], v[170:173], v[100:103]
	v_mfma_f32_16x16x32_bf16 v[92:95], v[146:149], v[170:173], v[92:95]
	v_mfma_f32_16x16x32_bf16 v[84:87], v[138:141], v[178:181], v[84:87]
	v_mfma_f32_16x16x32_bf16 v[76:79], v[146:149], v[178:181], v[76:79]
	v_mfma_f32_16x16x32_bf16 v[124:127], v[142:145], v[158:161], v[124:127]
	v_mfma_f32_16x16x32_bf16 v[120:123], v[150:153], v[158:161], v[120:123]
	v_mfma_f32_16x16x32_bf16 v[116:119], v[142:145], v[166:169], v[116:119]
	v_mfma_f32_16x16x32_bf16 v[108:111], v[150:153], v[166:169], v[108:111]
	v_mfma_f32_16x16x32_bf16 v[100:103], v[142:145], v[174:177], v[100:103]
	v_mfma_f32_16x16x32_bf16 v[92:95], v[150:153], v[174:177], v[92:95]
	v_mfma_f32_16x16x32_bf16 v[84:87], v[142:145], v[182:185], v[84:87]
	v_mfma_f32_16x16x32_bf16 v[76:79], v[150:153], v[182:185], v[76:79]
	v_mfma_f32_16x16x32_bf16 v[112:115], v[186:189], v[154:157], v[112:115]
	v_mfma_f32_16x16x32_bf16 v[104:107], v[198:201], v[154:157], v[104:107]
	v_mfma_f32_16x16x32_bf16 v[96:99], v[186:189], v[162:165], v[96:99]
	v_mfma_f32_16x16x32_bf16 v[88:91], v[198:201], v[162:165], v[88:91]
	v_mfma_f32_16x16x32_bf16 v[80:83], v[186:189], v[170:173], v[80:83]
	v_mfma_f32_16x16x32_bf16 v[72:75], v[198:201], v[170:173], v[72:75]
	v_mfma_f32_16x16x32_bf16 v[68:71], v[186:189], v[178:181], v[68:71]
	v_mfma_f32_16x16x32_bf16 v[64:67], v[198:201], v[178:181], v[64:67]
	v_mfma_f32_16x16x32_bf16 v[112:115], v[194:197], v[158:161], v[112:115]
	v_mfma_f32_16x16x32_bf16 v[104:107], v[202:205], v[158:161], v[104:107]
	v_mfma_f32_16x16x32_bf16 v[96:99], v[194:197], v[166:169], v[96:99]
	v_mfma_f32_16x16x32_bf16 v[88:91], v[202:205], v[166:169], v[88:91]
	v_mfma_f32_16x16x32_bf16 v[80:83], v[194:197], v[174:177], v[80:83]
	v_mfma_f32_16x16x32_bf16 v[72:75], v[202:205], v[174:177], v[72:75]
	v_mfma_f32_16x16x32_bf16 v[68:71], v[194:197], v[182:185], v[68:71]
	v_mfma_f32_16x16x32_bf16 v[64:67], v[202:205], v[182:185], v[64:67]
	s_setprio 0
	s_barrier
	s_mov_b32 m0, s69
	v_lshl_add_u64 v[190:191], v[190:191], 0, s[72:73]
	global_load_lds_dwordx4 v[190:191], off
	v_lshl_add_u64 v[190:191], v[206:207], 0, s[72:73]
	s_mov_b32 m0, s66
	s_nop 0
	global_load_lds_dwordx4 v[190:191], off
	s_mov_b32 m0, s59
	v_lshl_add_u64 v[190:191], v[208:209], 0, s[72:73]
	global_load_lds_dwordx4 v[190:191], off
	v_lshl_add_u64 v[190:191], v[210:211], 0, s[72:73]
	s_mov_b32 m0, s62
	s_nop 0
	global_load_lds_dwordx4 v[190:191], off
	s_mov_b32 m0, s79
	v_lshl_add_u64 v[154:155], s[28:29], 0, v[192:193]
	global_load_lds_dwordx4 v[154:155], off
	v_lshl_add_u64 v[156:157], s[28:29], 0, v[132:133]
	s_mov_b32 m0, s78
	s_nop 0
	global_load_lds_dwordx4 v[156:157], off
	ds_read_b128 v[154:157], v136 offset:49152
	ds_read_b128 v[158:161], v136 offset:50176
	ds_read_b128 v[162:165], v136 offset:51200
	ds_read_b128 v[166:169], v136 offset:52224
	ds_read_b128 v[170:173], v136 offset:53248
	ds_read_b128 v[174:177], v136 offset:54272
	ds_read_b128 v[178:181], v136 offset:55296
	ds_read_b128 v[182:185], v136 offset:56320
	s_waitcnt vmcnt(8)
	s_waitcnt lgkmcnt(0)
	s_barrier
	s_setprio 1
	v_mfma_f32_16x16x32_bf16 v[60:63], v[138:141], v[154:157], v[60:63]
	v_mfma_f32_16x16x32_bf16 v[56:59], v[146:149], v[154:157], v[56:59]
	v_mfma_f32_16x16x32_bf16 v[52:55], v[138:141], v[162:165], v[52:55]
	v_mfma_f32_16x16x32_bf16 v[44:47], v[146:149], v[162:165], v[44:47]
	v_mfma_f32_16x16x32_bf16 v[36:39], v[138:141], v[170:173], v[36:39]
	v_mfma_f32_16x16x32_bf16 v[28:31], v[146:149], v[170:173], v[28:31]
	v_mfma_f32_16x16x32_bf16 v[20:23], v[138:141], v[178:181], v[20:23]
	v_mfma_f32_16x16x32_bf16 v[12:15], v[146:149], v[178:181], v[12:15]
	v_mfma_f32_16x16x32_bf16 v[60:63], v[142:145], v[158:161], v[60:63]
	v_mfma_f32_16x16x32_bf16 v[56:59], v[150:153], v[158:161], v[56:59]
	v_mfma_f32_16x16x32_bf16 v[52:55], v[142:145], v[166:169], v[52:55]
	v_mfma_f32_16x16x32_bf16 v[44:47], v[150:153], v[166:169], v[44:47]
	v_mfma_f32_16x16x32_bf16 v[36:39], v[142:145], v[174:177], v[36:39]
	v_mfma_f32_16x16x32_bf16 v[28:31], v[150:153], v[174:177], v[28:31]
	v_mfma_f32_16x16x32_bf16 v[20:23], v[142:145], v[182:185], v[20:23]
	v_mfma_f32_16x16x32_bf16 v[12:15], v[150:153], v[182:185], v[12:15]
	v_mfma_f32_16x16x32_bf16 v[48:51], v[186:189], v[154:157], v[48:51]
	v_mfma_f32_16x16x32_bf16 v[40:43], v[198:201], v[154:157], v[40:43]
	v_mfma_f32_16x16x32_bf16 v[32:35], v[186:189], v[162:165], v[32:35]
	v_mfma_f32_16x16x32_bf16 v[24:27], v[198:201], v[162:165], v[24:27]
	v_mfma_f32_16x16x32_bf16 v[16:19], v[186:189], v[170:173], v[16:19]
	v_mfma_f32_16x16x32_bf16 v[8:11], v[198:201], v[170:173], v[8:11]
	v_mfma_f32_16x16x32_bf16 v[4:7], v[186:189], v[178:181], v[4:7]
	v_mfma_f32_16x16x32_bf16 v[0:3], v[198:201], v[178:181], v[0:3]
	v_mfma_f32_16x16x32_bf16 v[48:51], v[194:197], v[158:161], v[48:51]
	v_mfma_f32_16x16x32_bf16 v[40:43], v[202:205], v[158:161], v[40:43]
	v_mfma_f32_16x16x32_bf16 v[32:35], v[194:197], v[166:169], v[32:35]
	v_mfma_f32_16x16x32_bf16 v[24:27], v[202:205], v[166:169], v[24:27]
	v_mfma_f32_16x16x32_bf16 v[16:19], v[194:197], v[174:177], v[16:19]
	v_mfma_f32_16x16x32_bf16 v[8:11], v[202:205], v[174:177], v[8:11]
	v_mfma_f32_16x16x32_bf16 v[4:7], v[194:197], v[182:185], v[4:7]
	v_mfma_f32_16x16x32_bf16 v[0:3], v[202:205], v[182:185], v[0:3]
	s_setprio 0
	s_andn2_b64 vcc, exec, s[14:15]
	s_mov_b64 s[28:29], -1
	s_mov_b64 s[14:15], 0
	s_movk_i32 s34, 0x100
	s_barrier
	s_cbranch_vccz .LBB0_99
	s_mul_i32 s2, s10, 0x1400000
	s_mul_hi_i32 s3, s10, 0x1400000
	s_add_u32 s2, s26, s2
	v_and_b32_e32 v128, 63, v134
	s_addc_u32 s3, s27, s3
	v_mov_b32 v128, v128
	s_add_i32 s63, s63, s51
	v_and_or_b32 v130, v128, 15, s63
	s_lshl_b32 s4, s50, 8
	v_ashrrev_i32_e32 v128, 1, v128
	s_or_b32 s4, s64, s4
	v_and_b32_e32 v128, -8, v128
	v_add_u32_e32 v128, s4, v128
	v_ashrrev_i32_e32 v131, 31, v130
	v_ashrrev_i32_e32 v129, 31, v128
	v_lshlrev_b64 v[132:133], 12, v[130:131]
	v_lshl_add_u64 v[132:133], s[2:3], 0, v[132:133]
	v_lshlrev_b64 v[134:135], 1, v[128:129]
	v_lshl_add_u64 v[128:129], v[132:133], 0, v[134:135]
	v_cvt_pk_bf16_f32 v124, v124, v125
	v_cvt_pk_bf16_f32 v125, v126, v127
	v_cvt_pk_bf16_f32 v126, v120, v121
	v_cvt_pk_bf16_f32 v127, v122, v123
	global_store_dwordx4 v[128:129], v[124:127], off
	v_cvt_pk_bf16_f32 v112, v112, v113
	v_cvt_pk_bf16_f32 v113, v114, v115
	v_cvt_pk_bf16_f32 v114, v104, v105
	v_or_b32_e32 v104, 16, v130
	v_ashrrev_i32_e32 v105, 31, v104
	v_lshlrev_b64 v[104:105], 12, v[104:105]
	v_lshl_add_u64 v[104:105], s[2:3], 0, v[104:105]
	v_cvt_pk_bf16_f32 v115, v106, v107
	global_store_dwordx4 v[128:129], v[112:115], off offset:256
	s_cmpk_lt_u32 s11, 0x100
	s_nop 0
	v_lshl_add_u64 v[112:113], v[104:105], 0, v[134:135]
	v_cvt_pk_bf16_f32 v104, v116, v117
	v_cvt_pk_bf16_f32 v105, v118, v119
	v_cvt_pk_bf16_f32 v106, v108, v109
	v_cvt_pk_bf16_f32 v107, v110, v111
	global_store_dwordx4 v[112:113], v[104:107], off
	v_cvt_pk_bf16_f32 v96, v96, v97
	v_cvt_pk_bf16_f32 v97, v98, v99
	v_cvt_pk_bf16_f32 v98, v88, v89
	v_or_b32_e32 v88, 32, v130
	v_ashrrev_i32_e32 v89, 31, v88
	v_lshlrev_b64 v[88:89], 12, v[88:89]
	v_lshl_add_u64 v[88:89], s[2:3], 0, v[88:89]
	v_cvt_pk_bf16_f32 v99, v90, v91
	global_store_dwordx4 v[112:113], v[96:99], off offset:256
	s_nop 1
	v_lshl_add_u64 v[96:97], v[88:89], 0, v[134:135]
	v_cvt_pk_bf16_f32 v88, v100, v101
	v_cvt_pk_bf16_f32 v89, v102, v103
	v_cvt_pk_bf16_f32 v90, v92, v93
	v_cvt_pk_bf16_f32 v91, v94, v95
	global_store_dwordx4 v[96:97], v[88:91], off
	v_cvt_pk_bf16_f32 v80, v80, v81
	v_cvt_pk_bf16_f32 v81, v82, v83
	v_cvt_pk_bf16_f32 v82, v72, v73
	v_or_b32_e32 v72, 48, v130
	v_ashrrev_i32_e32 v73, 31, v72
	v_lshlrev_b64 v[72:73], 12, v[72:73]
	v_lshl_add_u64 v[72:73], s[2:3], 0, v[72:73]
	v_cvt_pk_bf16_f32 v83, v74, v75
	global_store_dwordx4 v[96:97], v[80:83], off offset:256
	s_mov_b64 s[2:3], 0x80000
	s_nop 0
	v_lshl_add_u64 v[80:81], v[72:73], 0, v[134:135]
	v_cvt_pk_bf16_f32 v72, v84, v85
	v_cvt_pk_bf16_f32 v73, v86, v87
	v_cvt_pk_bf16_f32 v74, v76, v77
	v_cvt_pk_bf16_f32 v75, v78, v79
	global_store_dwordx4 v[80:81], v[72:75], off
	v_cvt_pk_bf16_f32 v68, v68, v69
	v_cvt_pk_bf16_f32 v69, v70, v71
	v_cvt_pk_bf16_f32 v70, v64, v65
	v_lshl_add_u64 v[64:65], v[128:129], 0, s[2:3]
	s_mov_b32 s2, 0x80000
	v_cvt_pk_bf16_f32 v71, v66, v67
	global_store_dwordx4 v[80:81], v[68:71], off offset:256
	v_cvt_pk_bf16_f32 v60, v60, v61
	v_cvt_pk_bf16_f32 v61, v62, v63
	v_cvt_pk_bf16_f32 v62, v56, v57
	v_add_co_u32_e32 v56, vcc, s2, v128
	v_cvt_pk_bf16_f32 v63, v58, v59
	s_mov_b64 s[2:3], 0x90000
	s_nop 0
	v_addc_co_u32_e32 v57, vcc, 0, v129, vcc
	global_store_dwordx4 v[56:57], v[60:63], off
	v_cvt_pk_bf16_f32 v48, v48, v49
	v_cvt_pk_bf16_f32 v49, v50, v51
	v_cvt_pk_bf16_f32 v50, v40, v41
	v_cvt_pk_bf16_f32 v51, v42, v43
	global_store_dwordx4 v[64:65], v[48:51], off offset:256
	v_cvt_pk_bf16_f32 v40, v52, v53
	v_cvt_pk_bf16_f32 v41, v54, v55
	v_cvt_pk_bf16_f32 v42, v44, v45
	v_cvt_pk_bf16_f32 v43, v46, v47
	s_nop 1
	v_lshl_add_u64 v[48:49], v[128:129], 0, s[2:3]
	s_mov_b32 s2, 0x90000
	v_add_co_u32_e32 v44, vcc, s2, v128
	s_mov_b64 s[2:3], 0xa0000
	s_nop 0
	v_addc_co_u32_e32 v45, vcc, 0, v129, vcc
	global_store_dwordx4 v[44:45], v[40:43], off
	v_cvt_pk_bf16_f32 v32, v32, v33
	v_cvt_pk_bf16_f32 v33, v34, v35
	v_cvt_pk_bf16_f32 v34, v24, v25
	v_cvt_pk_bf16_f32 v35, v26, v27
	global_store_dwordx4 v[48:49], v[32:35], off offset:256
	v_cvt_pk_bf16_f32 v24, v36, v37
	v_cvt_pk_bf16_f32 v25, v38, v39
	v_cvt_pk_bf16_f32 v26, v28, v29
	v_cvt_pk_bf16_f32 v27, v30, v31
	s_nop 1
	v_lshl_add_u64 v[32:33], v[128:129], 0, s[2:3]
	s_mov_b32 s2, 0xa0000
	v_add_co_u32_e32 v28, vcc, s2, v128
	s_mov_b64 s[2:3], 0xb0000
	s_nop 0
	v_addc_co_u32_e32 v29, vcc, 0, v129, vcc
	global_store_dwordx4 v[28:29], v[24:27], off
	v_cvt_pk_bf16_f32 v16, v16, v17
	v_cvt_pk_bf16_f32 v17, v18, v19
	v_cvt_pk_bf16_f32 v18, v8, v9
	v_cvt_pk_bf16_f32 v19, v10, v11
	global_store_dwordx4 v[32:33], v[16:19], off offset:256
	v_cvt_pk_bf16_f32 v8, v20, v21
	v_cvt_pk_bf16_f32 v9, v22, v23
	v_cvt_pk_bf16_f32 v10, v12, v13
	v_cvt_pk_bf16_f32 v11, v14, v15
	s_nop 1
	v_lshl_add_u64 v[16:17], v[128:129], 0, s[2:3]
	s_mov_b32 s2, 0xb0000
	v_add_co_u32_e32 v12, vcc, s2, v128
	s_nop 1
	v_addc_co_u32_e32 v13, vcc, 0, v129, vcc
	global_store_dwordx4 v[12:13], v[8:11], off
	v_cvt_pk_bf16_f32 v4, v4, v5
	v_cvt_pk_bf16_f32 v5, v6, v7
	v_cvt_pk_bf16_f32 v6, v0, v1
	v_cvt_pk_bf16_f32 v7, v2, v3
	global_store_dwordx4 v[16:17], v[4:7], off offset:256
	s_waitcnt vmcnt(0)
	s_cbranch_scc0 .LBB0_95
	s_barrier
	s_branch .LBB0_95

.LBB0_105:
	v_and_b32_e32 v6, 48, v138
	s_lshl_b32 s5, s5, 5
	v_lshlrev_b32_e32 v7, 6, v138
	s_movk_i32 s28, 0x3c0
	s_lshr_b32 s9, s31, 1
	v_and_or_b32 v6, v7, s28, v6
	v_lshlrev_b32_e32 v7, 2, v138
	s_and_b32 s53, s5, 0x60
	s_and_b32 s9, s9, 7
	s_lshl_b32 s52, s4, 6
	v_and_b32_e32 v7, 32, v7
	s_lshl_b32 s4, s4, 13
	s_lshl_b32 s5, s53, 7
	s_lshl_b32 s9, s9, 18
	v_bitop3_b32 v8, v6, s4, v7 bitop3:0xde
	v_bitop3_b32 v139, s5, v6, v7 bitop3:0xf6
	v_lshlrev_b32_e32 v6, 13, v0
	s_add_u32 s2, s2, s9
	v_and_b32_e32 v6, 0xffffc000, v6
	s_addc_u32 s3, s3, 0
	v_lshl_add_u32 v1, v1, 10, v6
	v_and_b32_e32 v0, 1, v0
	v_readlane_b32 s4, v253, 38
	v_lshl_or_b32 v0, v0, 6, v1
	s_add_u32 s2, s4, s2
	v_readlane_b32 s4, v253, 39
	v_lshl_add_u32 v0, v2, 1, v0
	v_mov_b32_e32 v1, v193
	s_addc_u32 s3, s4, s3
	v_lshl_add_u64 v[134:135], s[2:3], 0, v[0:1]
	v_lshlrev_b32_e32 v0, 13, v3
	v_and_b32_e32 v0, 0xffffc000, v0
	v_lshl_add_u32 v0, v4, 10, v0
	v_and_b32_e32 v1, 1, v3
	v_lshl_or_b32 v0, v1, 6, v0
	s_waitcnt vmcnt(8)
	s_barrier
	s_waitcnt vmcnt(6)
	v_lshl_add_u32 v0, v5, 1, v0
	v_mov_b32_e32 v1, v193
	v_lshl_add_u64 v[136:137], s[2:3], 0, v[0:1]
	v_mov_b32_e32 v0, 0
	s_mov_b32 s54, -2
	s_mov_b64 s[2:3], 0
	v_add_u32_e32 v140, 0, v8
	v_mov_b32_e32 v1, v0
	v_mov_b32_e32 v2, v0
	v_mov_b32_e32 v3, v0
	v_mov_b32_e32 v4, v0
	v_mov_b32_e32 v5, v0
	v_mov_b32_e32 v6, v0
	v_mov_b32_e32 v7, v0
	v_mov_b32_e32 v8, v0
	v_mov_b32_e32 v9, v0
	v_mov_b32_e32 v10, v0
	v_mov_b32_e32 v11, v0
	v_mov_b32_e32 v16, v0
	v_mov_b32_e32 v17, v0
	v_mov_b32_e32 v18, v0
	v_mov_b32_e32 v19, v0
	v_mov_b32_e32 v24, v0
	v_mov_b32_e32 v25, v0
	v_mov_b32_e32 v26, v0
	v_mov_b32_e32 v27, v0
	v_mov_b32_e32 v32, v0
	v_mov_b32_e32 v33, v0
	v_mov_b32_e32 v34, v0
	v_mov_b32_e32 v35, v0
	v_mov_b32_e32 v40, v0
	v_mov_b32_e32 v41, v0
	v_mov_b32_e32 v42, v0
	v_mov_b32_e32 v43, v0
	v_mov_b32_e32 v48, v0
	v_mov_b32_e32 v49, v0
	v_mov_b32_e32 v50, v0
	v_mov_b32_e32 v51, v0
	v_mov_b32_e32 v12, v0
	v_mov_b32_e32 v13, v0
	v_mov_b32_e32 v14, v0
	v_mov_b32_e32 v15, v0
	v_mov_b32_e32 v20, v0
	v_mov_b32_e32 v21, v0
	v_mov_b32_e32 v22, v0
	v_mov_b32_e32 v23, v0
	v_mov_b32_e32 v28, v0
	v_mov_b32_e32 v29, v0
	v_mov_b32_e32 v30, v0
	v_mov_b32_e32 v31, v0
	v_mov_b32_e32 v36, v0
	v_mov_b32_e32 v37, v0
	v_mov_b32_e32 v38, v0
	v_mov_b32_e32 v39, v0
	v_mov_b32_e32 v44, v0
	v_mov_b32_e32 v45, v0
	v_mov_b32_e32 v46, v0
	v_mov_b32_e32 v47, v0
	v_mov_b32_e32 v52, v0
	v_mov_b32_e32 v53, v0
	v_mov_b32_e32 v54, v0
	v_mov_b32_e32 v55, v0
	v_mov_b32_e32 v56, v0
	v_mov_b32_e32 v57, v0
	v_mov_b32_e32 v58, v0
	v_mov_b32_e32 v59, v0
	v_mov_b32_e32 v60, v0
	v_mov_b32_e32 v61, v0
	v_mov_b32_e32 v62, v0
	v_mov_b32_e32 v63, v0
	v_mov_b32_e32 v64, v0
	v_mov_b32_e32 v65, v0
	v_mov_b32_e32 v66, v0
	v_mov_b32_e32 v67, v0
	v_mov_b32_e32 v68, v0
	v_mov_b32_e32 v69, v0
	v_mov_b32_e32 v70, v0
	v_mov_b32_e32 v71, v0
	v_mov_b32_e32 v72, v0
	v_mov_b32_e32 v73, v0
	v_mov_b32_e32 v74, v0
	v_mov_b32_e32 v75, v0
	v_mov_b32_e32 v80, v0
	v_mov_b32_e32 v81, v0
	v_mov_b32_e32 v82, v0
	v_mov_b32_e32 v83, v0
	v_mov_b32_e32 v88, v0
	v_mov_b32_e32 v89, v0
	v_mov_b32_e32 v90, v0
	v_mov_b32_e32 v91, v0
	v_mov_b32_e32 v96, v0
	v_mov_b32_e32 v97, v0
	v_mov_b32_e32 v98, v0
	v_mov_b32_e32 v99, v0
	v_mov_b32_e32 v104, v0
	v_mov_b32_e32 v105, v0
	v_mov_b32_e32 v106, v0
	v_mov_b32_e32 v107, v0
	v_mov_b32_e32 v112, v0
	v_mov_b32_e32 v113, v0
	v_mov_b32_e32 v114, v0
	v_mov_b32_e32 v115, v0
	v_mov_b32_e32 v76, v0
	v_mov_b32_e32 v77, v0
	v_mov_b32_e32 v78, v0
	v_mov_b32_e32 v79, v0
	v_mov_b32_e32 v84, v0
	v_mov_b32_e32 v85, v0
	v_mov_b32_e32 v86, v0
	v_mov_b32_e32 v87, v0
	v_mov_b32_e32 v92, v0
	v_mov_b32_e32 v93, v0
	v_mov_b32_e32 v94, v0
	v_mov_b32_e32 v95, v0
	v_mov_b32_e32 v100, v0
	v_mov_b32_e32 v101, v0
	v_mov_b32_e32 v102, v0
	v_mov_b32_e32 v103, v0
	v_mov_b32_e32 v108, v0
	v_mov_b32_e32 v109, v0
	v_mov_b32_e32 v110, v0
	v_mov_b32_e32 v111, v0
	v_mov_b32_e32 v116, v0
	v_mov_b32_e32 v117, v0
	v_mov_b32_e32 v118, v0
	v_mov_b32_e32 v119, v0
	v_mov_b32_e32 v120, v0
	v_mov_b32_e32 v121, v0
	v_mov_b32_e32 v122, v0
	v_mov_b32_e32 v123, v0
	v_mov_b32_e32 v124, v0
	v_mov_b32_e32 v125, v0
	v_mov_b32_e32 v126, v0
	v_mov_b32_e32 v127, v0
	s_barrier
.LBB0_106:
	s_add_u32 s4, s2, 0x100
	s_addc_u32 s5, s3, 0
	s_cmp_lg_u32 s54, 4
	s_cselect_b32 s28, s4, 0
	s_cselect_b32 s9, s5, 0
	s_add_u32 s34, s12, s28
	s_addc_u32 s35, s13, s9
	s_add_i32 s46, 0, 0x10000
	s_add_u32 s28, s14, s28
	s_addc_u32 s29, s15, s9
	v_lshl_add_u64 v[190:191], v[134:135], 0, s[2:3]
	s_add_i32 m0, s40, 0xc000
	s_nop 0
	global_load_lds_dwordx4 v[190:191], off
	v_lshl_add_u64 v[190:191], v[136:137], 0, s[2:3]
	s_add_i32 m0, s40, 0xe000
	s_nop 0
	global_load_lds_dwordx4 v[190:191], off
	v_add_u32_e32 v141, 0x10000, v139
	ds_read_b128 v[142:145], v141
	ds_read_b128 v[146:149], v141 offset:1024
	ds_read_b128 v[150:153], v141 offset:2048
	ds_read_b128 v[154:157], v141 offset:3072
	ds_read_b128 v[158:161], v140
	ds_read_b128 v[162:165], v140 offset:1024
	ds_read_b128 v[166:169], v140 offset:2048
	ds_read_b128 v[170:173], v140 offset:3072
	ds_read_b128 v[174:177], v140 offset:4096
	ds_read_b128 v[178:181], v140 offset:5120
	ds_read_b128 v[182:185], v140 offset:6144
	ds_read_b128 v[186:189], v140 offset:7168
	v_add_u32_e32 v141, 0x14000, v139
	ds_read_b128 v[194:197], v141
	ds_read_b128 v[198:201], v141 offset:1024
	ds_read_b128 v[202:205], v141 offset:2048
	ds_read_b128 v[206:209], v141 offset:3072
	s_waitcnt vmcnt(8)
	s_waitcnt lgkmcnt(0)
	s_barrier
	s_setprio 1
	v_mfma_f32_16x16x32_bf16 v[124:127], v[142:145], v[158:161], v[124:127]
	v_mfma_f32_16x16x32_bf16 v[120:123], v[150:153], v[158:161], v[120:123]
	v_mfma_f32_16x16x32_bf16 v[116:119], v[142:145], v[166:169], v[116:119]
	v_mfma_f32_16x16x32_bf16 v[108:111], v[150:153], v[166:169], v[108:111]
	v_mfma_f32_16x16x32_bf16 v[100:103], v[142:145], v[174:177], v[100:103]
	v_mfma_f32_16x16x32_bf16 v[92:95], v[150:153], v[174:177], v[92:95]
	v_mfma_f32_16x16x32_bf16 v[84:87], v[142:145], v[182:185], v[84:87]
	v_mfma_f32_16x16x32_bf16 v[76:79], v[150:153], v[182:185], v[76:79]
	v_mfma_f32_16x16x32_bf16 v[124:127], v[146:149], v[162:165], v[124:127]
	v_mfma_f32_16x16x32_bf16 v[120:123], v[154:157], v[162:165], v[120:123]
	v_mfma_f32_16x16x32_bf16 v[116:119], v[146:149], v[170:173], v[116:119]
	v_mfma_f32_16x16x32_bf16 v[108:111], v[154:157], v[170:173], v[108:111]
	v_mfma_f32_16x16x32_bf16 v[100:103], v[146:149], v[178:181], v[100:103]
	v_mfma_f32_16x16x32_bf16 v[92:95], v[154:157], v[178:181], v[92:95]
	v_mfma_f32_16x16x32_bf16 v[84:87], v[146:149], v[186:189], v[84:87]
	v_mfma_f32_16x16x32_bf16 v[76:79], v[154:157], v[186:189], v[76:79]
	v_mfma_f32_16x16x32_bf16 v[112:115], v[194:197], v[158:161], v[112:115]
	v_mfma_f32_16x16x32_bf16 v[104:107], v[202:205], v[158:161], v[104:107]
	v_mfma_f32_16x16x32_bf16 v[96:99], v[194:197], v[166:169], v[96:99]
	v_mfma_f32_16x16x32_bf16 v[88:91], v[202:205], v[166:169], v[88:91]
	v_mfma_f32_16x16x32_bf16 v[80:83], v[194:197], v[174:177], v[80:83]
	v_mfma_f32_16x16x32_bf16 v[72:75], v[202:205], v[174:177], v[72:75]
	v_mfma_f32_16x16x32_bf16 v[68:71], v[194:197], v[182:185], v[68:71]
	v_mfma_f32_16x16x32_bf16 v[64:67], v[202:205], v[182:185], v[64:67]
	v_mfma_f32_16x16x32_bf16 v[112:115], v[198:201], v[162:165], v[112:115]
	v_mfma_f32_16x16x32_bf16 v[104:107], v[206:209], v[162:165], v[104:107]
	v_mfma_f32_16x16x32_bf16 v[96:99], v[198:201], v[170:173], v[96:99]
	v_mfma_f32_16x16x32_bf16 v[88:91], v[206:209], v[170:173], v[88:91]
	v_mfma_f32_16x16x32_bf16 v[80:83], v[198:201], v[178:181], v[80:83]
	v_mfma_f32_16x16x32_bf16 v[72:75], v[206:209], v[178:181], v[72:75]
	v_mfma_f32_16x16x32_bf16 v[68:71], v[198:201], v[186:189], v[68:71]
	v_mfma_f32_16x16x32_bf16 v[64:67], v[206:209], v[186:189], v[64:67]
	s_setprio 0
	s_barrier
	s_add_i32 s9, 0, 0x14000
	s_add_i32 s2, s46, s39
	v_lshl_add_u64 v[190:191], s[28:29], 0, v[192:193]
	s_mov_b32 m0, s2
	s_nop 0
	global_load_lds_dwordx4 v[190:191], off
	v_lshl_add_u64 v[210:211], s[28:29], 0, v[132:133]
	s_add_i32 m0, s2, 0x2000
	s_nop 0
	global_load_lds_dwordx4 v[210:211], off
	s_mov_b32 m0, s40
	v_lshl_add_u64 v[212:213], s[34:35], 0, v[128:129]
	global_load_lds_dwordx4 v[212:213], off
	v_lshl_add_u64 v[214:215], s[34:35], 0, v[130:131]
	s_mov_b32 m0, s41
	s_nop 0
	global_load_lds_dwordx4 v[214:215], off
	s_add_u32 s2, s28, 0x20000
	s_addc_u32 s3, s29, 0
	s_add_i32 s9, s9, s39
	v_lshl_add_u64 v[158:159], s[2:3], 0, v[192:193]
	s_mov_b32 m0, s9
	s_nop 0
	global_load_lds_dwordx4 v[158:159], off
	v_lshl_add_u64 v[160:161], s[2:3], 0, v[132:133]
	s_add_i32 m0, s9, 0x2000
	s_nop 0
	global_load_lds_dwordx4 v[160:161], off
	ds_read_b128 v[158:161], v140 offset:16384
	ds_read_b128 v[162:165], v140 offset:17408
	ds_read_b128 v[166:169], v140 offset:18432
	ds_read_b128 v[170:173], v140 offset:19456
	ds_read_b128 v[174:177], v140 offset:20480
	ds_read_b128 v[178:181], v140 offset:21504
	ds_read_b128 v[182:185], v140 offset:22528
	ds_read_b128 v[186:189], v140 offset:23552
	s_waitcnt vmcnt(8)
	s_waitcnt lgkmcnt(0)
	s_barrier
	s_setprio 1
	v_mfma_f32_16x16x32_bf16 v[60:63], v[142:145], v[158:161], v[60:63]
	v_mfma_f32_16x16x32_bf16 v[56:59], v[150:153], v[158:161], v[56:59]
	v_mfma_f32_16x16x32_bf16 v[52:55], v[142:145], v[166:169], v[52:55]
	v_mfma_f32_16x16x32_bf16 v[44:47], v[150:153], v[166:169], v[44:47]
	v_mfma_f32_16x16x32_bf16 v[36:39], v[142:145], v[174:177], v[36:39]
	v_mfma_f32_16x16x32_bf16 v[28:31], v[150:153], v[174:177], v[28:31]
	v_mfma_f32_16x16x32_bf16 v[20:23], v[142:145], v[182:185], v[20:23]
	v_mfma_f32_16x16x32_bf16 v[12:15], v[150:153], v[182:185], v[12:15]
	v_mfma_f32_16x16x32_bf16 v[60:63], v[146:149], v[162:165], v[60:63]
	v_mfma_f32_16x16x32_bf16 v[56:59], v[154:157], v[162:165], v[56:59]
	v_mfma_f32_16x16x32_bf16 v[52:55], v[146:149], v[170:173], v[52:55]
	v_mfma_f32_16x16x32_bf16 v[44:47], v[154:157], v[170:173], v[44:47]
	v_mfma_f32_16x16x32_bf16 v[36:39], v[146:149], v[178:181], v[36:39]
	v_mfma_f32_16x16x32_bf16 v[28:31], v[154:157], v[178:181], v[28:31]
	v_mfma_f32_16x16x32_bf16 v[20:23], v[146:149], v[186:189], v[20:23]
	v_mfma_f32_16x16x32_bf16 v[12:15], v[154:157], v[186:189], v[12:15]
	v_mfma_f32_16x16x32_bf16 v[48:51], v[194:197], v[158:161], v[48:51]
	v_mfma_f32_16x16x32_bf16 v[40:43], v[202:205], v[158:161], v[40:43]
	v_mfma_f32_16x16x32_bf16 v[32:35], v[194:197], v[166:169], v[32:35]
	v_mfma_f32_16x16x32_bf16 v[24:27], v[202:205], v[166:169], v[24:27]
	v_mfma_f32_16x16x32_bf16 v[16:19], v[194:197], v[174:177], v[16:19]
	v_mfma_f32_16x16x32_bf16 v[8:11], v[202:205], v[174:177], v[8:11]
	v_mfma_f32_16x16x32_bf16 v[4:7], v[194:197], v[182:185], v[4:7]
	v_mfma_f32_16x16x32_bf16 v[0:3], v[202:205], v[182:185], v[0:3]
	v_mfma_f32_16x16x32_bf16 v[48:51], v[198:201], v[162:165], v[48:51]
	v_mfma_f32_16x16x32_bf16 v[40:43], v[206:209], v[162:165], v[40:43]
	v_mfma_f32_16x16x32_bf16 v[32:35], v[198:201], v[170:173], v[32:35]
	v_mfma_f32_16x16x32_bf16 v[24:27], v[206:209], v[170:173], v[24:27]
	v_mfma_f32_16x16x32_bf16 v[16:19], v[198:201], v[178:181], v[16:19]
	v_mfma_f32_16x16x32_bf16 v[8:11], v[206:209], v[178:181], v[8:11]
	v_mfma_f32_16x16x32_bf16 v[4:7], v[198:201], v[186:189], v[4:7]
	v_mfma_f32_16x16x32_bf16 v[0:3], v[206:209], v[186:189], v[0:3]
	s_setprio 0
	s_barrier
	s_add_i32 s9, 0, 0x18000
	s_add_u32 s2, s34, 0x20000
	s_addc_u32 s3, s35, 0
	s_mov_b32 m0, s48
	v_lshl_add_u64 v[194:195], s[2:3], 0, v[128:129]
	global_load_lds_dwordx4 v[194:195], off
	v_lshl_add_u64 v[194:195], s[2:3], 0, v[130:131]
	s_mov_b32 m0, s49
	s_nop 0
	global_load_lds_dwordx4 v[194:195], off
	v_add_u32_e32 v141, 0x18000, v139
	ds_read_b128 v[142:145], v141
	ds_read_b128 v[146:149], v141 offset:1024
	ds_read_b128 v[150:153], v141 offset:2048
	ds_read_b128 v[154:157], v141 offset:3072
	ds_read_b128 v[158:161], v140 offset:32768
	ds_read_b128 v[162:165], v140 offset:33792
	ds_read_b128 v[166:169], v140 offset:34816
	ds_read_b128 v[170:173], v140 offset:35840
	ds_read_b128 v[174:177], v140 offset:36864
	ds_read_b128 v[178:181], v140 offset:37888
	ds_read_b128 v[182:185], v140 offset:38912
	ds_read_b128 v[186:189], v140 offset:39936
	v_add_u32_e32 v141, 0x1c000, v139
	ds_read_b128 v[194:197], v141
	ds_read_b128 v[198:201], v141 offset:1024
	ds_read_b128 v[202:205], v141 offset:2048
	ds_read_b128 v[206:209], v141 offset:3072
	s_waitcnt vmcnt(8)
	s_waitcnt lgkmcnt(0)
	s_barrier
	s_setprio 1
	v_mfma_f32_16x16x32_bf16 v[124:127], v[142:145], v[158:161], v[124:127]
	v_mfma_f32_16x16x32_bf16 v[120:123], v[150:153], v[158:161], v[120:123]
	v_mfma_f32_16x16x32_bf16 v[116:119], v[142:145], v[166:169], v[116:119]
	v_mfma_f32_16x16x32_bf16 v[108:111], v[150:153], v[166:169], v[108:111]
	v_mfma_f32_16x16x32_bf16 v[100:103], v[142:145], v[174:177], v[100:103]
	v_mfma_f32_16x16x32_bf16 v[92:95], v[150:153], v[174:177], v[92:95]
	v_mfma_f32_16x16x32_bf16 v[84:87], v[142:145], v[182:185], v[84:87]
	v_mfma_f32_16x16x32_bf16 v[76:79], v[150:153], v[182:185], v[76:79]
	v_mfma_f32_16x16x32_bf16 v[124:127], v[146:149], v[162:165], v[124:127]
	v_mfma_f32_16x16x32_bf16 v[120:123], v[154:157], v[162:165], v[120:123]
	v_mfma_f32_16x16x32_bf16 v[116:119], v[146:149], v[170:173], v[116:119]
	v_mfma_f32_16x16x32_bf16 v[108:111], v[154:157], v[170:173], v[108:111]
	v_mfma_f32_16x16x32_bf16 v[100:103], v[146:149], v[178:181], v[100:103]
	v_mfma_f32_16x16x32_bf16 v[92:95], v[154:157], v[178:181], v[92:95]
	v_mfma_f32_16x16x32_bf16 v[84:87], v[146:149], v[186:189], v[84:87]
	v_mfma_f32_16x16x32_bf16 v[76:79], v[154:157], v[186:189], v[76:79]
	v_mfma_f32_16x16x32_bf16 v[112:115], v[194:197], v[158:161], v[112:115]
	v_mfma_f32_16x16x32_bf16 v[104:107], v[202:205], v[158:161], v[104:107]
	v_mfma_f32_16x16x32_bf16 v[96:99], v[194:197], v[166:169], v[96:99]
	v_mfma_f32_16x16x32_bf16 v[88:91], v[202:205], v[166:169], v[88:91]
	v_mfma_f32_16x16x32_bf16 v[80:83], v[194:197], v[174:177], v[80:83]
	v_mfma_f32_16x16x32_bf16 v[72:75], v[202:205], v[174:177], v[72:75]
	v_mfma_f32_16x16x32_bf16 v[68:71], v[194:197], v[182:185], v[68:71]
	v_mfma_f32_16x16x32_bf16 v[64:67], v[202:205], v[182:185], v[64:67]
	v_mfma_f32_16x16x32_bf16 v[112:115], v[198:201], v[162:165], v[112:115]
	v_mfma_f32_16x16x32_bf16 v[104:107], v[206:209], v[162:165], v[104:107]
	v_mfma_f32_16x16x32_bf16 v[96:99], v[198:201], v[170:173], v[96:99]
	v_mfma_f32_16x16x32_bf16 v[88:91], v[206:209], v[170:173], v[88:91]
	v_mfma_f32_16x16x32_bf16 v[80:83], v[198:201], v[178:181], v[80:83]
	v_mfma_f32_16x16x32_bf16 v[72:75], v[206:209], v[178:181], v[72:75]
	v_mfma_f32_16x16x32_bf16 v[68:71], v[198:201], v[186:189], v[68:71]
	v_mfma_f32_16x16x32_bf16 v[64:67], v[206:209], v[186:189], v[64:67]
	s_setprio 0
	s_barrier
	s_add_i32 s34, 0, 0x1c000
	s_add_i32 s2, s9, s39
	v_lshl_add_u64 v[190:191], v[190:191], 0, s[72:73]
	s_mov_b32 m0, s2
	s_nop 0
	global_load_lds_dwordx4 v[190:191], off
	v_lshl_add_u64 v[190:191], v[210:211], 0, s[72:73]
	s_add_i32 m0, s2, 0x2000
	s_nop 0
	global_load_lds_dwordx4 v[190:191], off
	s_mov_b32 m0, s50
	v_lshl_add_u64 v[190:191], v[212:213], 0, s[72:73]
	global_load_lds_dwordx4 v[190:191], off
	v_lshl_add_u64 v[190:191], v[214:215], 0, s[72:73]
	s_mov_b32 m0, s51
	s_nop 0
	global_load_lds_dwordx4 v[190:191], off
	s_add_u32 s2, s28, 0x20080
	s_addc_u32 s3, s29, 0
	s_add_i32 s9, s34, s39
	v_lshl_add_u64 v[158:159], s[2:3], 0, v[192:193]
	s_mov_b32 m0, s9
	s_nop 0
	global_load_lds_dwordx4 v[158:159], off
	v_lshl_add_u64 v[160:161], s[2:3], 0, v[132:133]
	s_add_i32 m0, s9, 0x2000
	s_nop 0
	global_load_lds_dwordx4 v[160:161], off
	ds_read_b128 v[158:161], v140 offset:49152
	ds_read_b128 v[162:165], v140 offset:50176
	ds_read_b128 v[166:169], v140 offset:51200
	ds_read_b128 v[170:173], v140 offset:52224
	ds_read_b128 v[174:177], v140 offset:53248
	ds_read_b128 v[178:181], v140 offset:54272
	ds_read_b128 v[182:185], v140 offset:55296
	ds_read_b128 v[186:189], v140 offset:56320
	s_waitcnt vmcnt(8)
	s_waitcnt lgkmcnt(0)
	s_barrier
	s_setprio 1
	v_mfma_f32_16x16x32_bf16 v[60:63], v[142:145], v[158:161], v[60:63]
	v_mfma_f32_16x16x32_bf16 v[56:59], v[150:153], v[158:161], v[56:59]
	v_mfma_f32_16x16x32_bf16 v[52:55], v[142:145], v[166:169], v[52:55]
	v_mfma_f32_16x16x32_bf16 v[44:47], v[150:153], v[166:169], v[44:47]
	v_mfma_f32_16x16x32_bf16 v[36:39], v[142:145], v[174:177], v[36:39]
	v_mfma_f32_16x16x32_bf16 v[28:31], v[150:153], v[174:177], v[28:31]
	v_mfma_f32_16x16x32_bf16 v[20:23], v[142:145], v[182:185], v[20:23]
	v_mfma_f32_16x16x32_bf16 v[12:15], v[150:153], v[182:185], v[12:15]
	v_mfma_f32_16x16x32_bf16 v[60:63], v[146:149], v[162:165], v[60:63]
	v_mfma_f32_16x16x32_bf16 v[56:59], v[154:157], v[162:165], v[56:59]
	v_mfma_f32_16x16x32_bf16 v[52:55], v[146:149], v[170:173], v[52:55]
	v_mfma_f32_16x16x32_bf16 v[44:47], v[154:157], v[170:173], v[44:47]
	v_mfma_f32_16x16x32_bf16 v[36:39], v[146:149], v[178:181], v[36:39]
	v_mfma_f32_16x16x32_bf16 v[28:31], v[154:157], v[178:181], v[28:31]
	v_mfma_f32_16x16x32_bf16 v[20:23], v[146:149], v[186:189], v[20:23]
	v_mfma_f32_16x16x32_bf16 v[12:15], v[154:157], v[186:189], v[12:15]
	v_mfma_f32_16x16x32_bf16 v[48:51], v[194:197], v[158:161], v[48:51]
	v_mfma_f32_16x16x32_bf16 v[40:43], v[202:205], v[158:161], v[40:43]
	v_mfma_f32_16x16x32_bf16 v[32:35], v[194:197], v[166:169], v[32:35]
	v_mfma_f32_16x16x32_bf16 v[24:27], v[202:205], v[166:169], v[24:27]
	v_mfma_f32_16x16x32_bf16 v[16:19], v[194:197], v[174:177], v[16:19]
	v_mfma_f32_16x16x32_bf16 v[8:11], v[202:205], v[174:177], v[8:11]
	v_mfma_f32_16x16x32_bf16 v[4:7], v[194:197], v[182:185], v[4:7]
	v_mfma_f32_16x16x32_bf16 v[0:3], v[202:205], v[182:185], v[0:3]
	v_mfma_f32_16x16x32_bf16 v[48:51], v[198:201], v[162:165], v[48:51]
	v_mfma_f32_16x16x32_bf16 v[40:43], v[206:209], v[162:165], v[40:43]
	v_mfma_f32_16x16x32_bf16 v[32:35], v[198:201], v[170:173], v[32:35]
	v_mfma_f32_16x16x32_bf16 v[24:27], v[206:209], v[170:173], v[24:27]
	v_mfma_f32_16x16x32_bf16 v[16:19], v[198:201], v[178:181], v[16:19]
	v_mfma_f32_16x16x32_bf16 v[8:11], v[206:209], v[178:181], v[8:11]
	v_mfma_f32_16x16x32_bf16 v[4:7], v[198:201], v[186:189], v[4:7]
	v_mfma_f32_16x16x32_bf16 v[0:3], v[206:209], v[186:189], v[0:3]
	s_setprio 0
	s_add_i32 s54, s54, 2
	s_cmp_gt_u32 s54, 5
	s_mov_b64 s[2:3], s[4:5]
	s_barrier
	s_cbranch_scc0 .LBB0_106
	s_lshl_b64 s[2:3], s[10:11], 23
	s_add_u32 s2, s26, s2
	s_addc_u32 s3, s27, s3
	s_add_u32 s2, s2, 0x2e00400
	s_addc_u32 s3, s3, 0
	v_and_b32_e32 v128, 63, v138
	s_lshl_b32 s4, s38, 8
	v_mov_b32 v128, v128
	s_add_i32 s52, s52, s4
	v_and_or_b32 v130, v128, 15, s52
	s_lshl_b32 s4, s37, 8
	v_ashrrev_i32_e32 v128, 1, v128
	s_or_b32 s4, s53, s4
	v_and_b32_e32 v128, -8, v128
	v_add_u32_e32 v128, s4, v128
	v_ashrrev_i32_e32 v131, 31, v130
	v_ashrrev_i32_e32 v129, 31, v128
	v_lshlrev_b64 v[132:133], 12, v[130:131]
	v_lshl_add_u64 v[132:133], s[2:3], 0, v[132:133]
	v_lshlrev_b64 v[134:135], 1, v[128:129]
	v_lshl_add_u64 v[128:129], v[132:133], 0, v[134:135]
	v_cvt_pk_bf16_f32 v124, v124, v125
	v_cvt_pk_bf16_f32 v125, v126, v127
	v_cvt_pk_bf16_f32 v126, v120, v121
	v_cvt_pk_bf16_f32 v127, v122, v123
	global_store_dwordx4 v[128:129], v[124:127], off
	v_cvt_pk_bf16_f32 v112, v112, v113
	v_cvt_pk_bf16_f32 v113, v114, v115
	v_cvt_pk_bf16_f32 v114, v104, v105
	v_or_b32_e32 v104, 16, v130
	v_ashrrev_i32_e32 v105, 31, v104
	v_lshlrev_b64 v[104:105], 12, v[104:105]
	v_lshl_add_u64 v[104:105], s[2:3], 0, v[104:105]
	v_cvt_pk_bf16_f32 v115, v106, v107
	global_store_dwordx4 v[128:129], v[112:115], off offset:256
	s_cmpk_lt_u32 s36, 0x100
	s_nop 0
	v_lshl_add_u64 v[112:113], v[104:105], 0, v[134:135]
	v_cvt_pk_bf16_f32 v104, v116, v117
	v_cvt_pk_bf16_f32 v105, v118, v119
	v_cvt_pk_bf16_f32 v106, v108, v109
	v_cvt_pk_bf16_f32 v107, v110, v111
	global_store_dwordx4 v[112:113], v[104:107], off
	v_cvt_pk_bf16_f32 v96, v96, v97
	v_cvt_pk_bf16_f32 v97, v98, v99
	v_cvt_pk_bf16_f32 v98, v88, v89
	v_or_b32_e32 v88, 32, v130
	v_ashrrev_i32_e32 v89, 31, v88
	v_lshlrev_b64 v[88:89], 12, v[88:89]
	v_lshl_add_u64 v[88:89], s[2:3], 0, v[88:89]
	v_cvt_pk_bf16_f32 v99, v90, v91
	global_store_dwordx4 v[112:113], v[96:99], off offset:256
	s_nop 1
	v_lshl_add_u64 v[96:97], v[88:89], 0, v[134:135]
	v_cvt_pk_bf16_f32 v88, v100, v101
	v_cvt_pk_bf16_f32 v89, v102, v103
	v_cvt_pk_bf16_f32 v90, v92, v93
	v_cvt_pk_bf16_f32 v91, v94, v95
	global_store_dwordx4 v[96:97], v[88:91], off
	v_cvt_pk_bf16_f32 v80, v80, v81
	v_cvt_pk_bf16_f32 v81, v82, v83
	v_cvt_pk_bf16_f32 v82, v72, v73
	v_or_b32_e32 v72, 48, v130
	v_ashrrev_i32_e32 v73, 31, v72
	v_lshlrev_b64 v[72:73], 12, v[72:73]
	v_lshl_add_u64 v[72:73], s[2:3], 0, v[72:73]
	v_cvt_pk_bf16_f32 v83, v74, v75
	global_store_dwordx4 v[96:97], v[80:83], off offset:256
	s_mov_b64 s[2:3], 0x80000
	s_nop 0
	v_lshl_add_u64 v[80:81], v[72:73], 0, v[134:135]
	v_cvt_pk_bf16_f32 v72, v84, v85
	v_cvt_pk_bf16_f32 v73, v86, v87
	v_cvt_pk_bf16_f32 v74, v76, v77
	v_cvt_pk_bf16_f32 v75, v78, v79
	global_store_dwordx4 v[80:81], v[72:75], off
	v_cvt_pk_bf16_f32 v68, v68, v69
	v_cvt_pk_bf16_f32 v69, v70, v71
	v_cvt_pk_bf16_f32 v70, v64, v65
	v_lshl_add_u64 v[64:65], v[128:129], 0, s[2:3]
	s_mov_b32 s2, 0x80000
	v_cvt_pk_bf16_f32 v71, v66, v67
	global_store_dwordx4 v[80:81], v[68:71], off offset:256
	v_cvt_pk_bf16_f32 v60, v60, v61
	v_cvt_pk_bf16_f32 v61, v62, v63
	v_cvt_pk_bf16_f32 v62, v56, v57
	v_add_co_u32_e32 v56, vcc, s2, v128
	v_cvt_pk_bf16_f32 v63, v58, v59
	s_mov_b64 s[2:3], 0x90000
	s_nop 0
	v_addc_co_u32_e32 v57, vcc, 0, v129, vcc
	global_store_dwordx4 v[56:57], v[60:63], off
	v_cvt_pk_bf16_f32 v48, v48, v49
	v_cvt_pk_bf16_f32 v49, v50, v51
	v_cvt_pk_bf16_f32 v50, v40, v41
	v_cvt_pk_bf16_f32 v51, v42, v43
	global_store_dwordx4 v[64:65], v[48:51], off offset:256
	v_cvt_pk_bf16_f32 v40, v52, v53
	v_cvt_pk_bf16_f32 v41, v54, v55
	v_cvt_pk_bf16_f32 v42, v44, v45
	v_cvt_pk_bf16_f32 v43, v46, v47
	s_nop 1
	v_lshl_add_u64 v[48:49], v[128:129], 0, s[2:3]
	s_mov_b32 s2, 0x90000
	v_add_co_u32_e32 v44, vcc, s2, v128
	s_mov_b64 s[2:3], 0xa0000
	s_nop 0
	v_addc_co_u32_e32 v45, vcc, 0, v129, vcc
	global_store_dwordx4 v[44:45], v[40:43], off
	v_cvt_pk_bf16_f32 v32, v32, v33
	v_cvt_pk_bf16_f32 v33, v34, v35
	v_cvt_pk_bf16_f32 v34, v24, v25
	v_cvt_pk_bf16_f32 v35, v26, v27
	global_store_dwordx4 v[48:49], v[32:35], off offset:256
	v_cvt_pk_bf16_f32 v24, v36, v37
	v_cvt_pk_bf16_f32 v25, v38, v39
	v_cvt_pk_bf16_f32 v26, v28, v29
	v_cvt_pk_bf16_f32 v27, v30, v31
	s_nop 1
	v_lshl_add_u64 v[32:33], v[128:129], 0, s[2:3]
	s_mov_b32 s2, 0xa0000
	v_add_co_u32_e32 v28, vcc, s2, v128
	s_mov_b64 s[2:3], 0xb0000
	s_nop 0
	v_addc_co_u32_e32 v29, vcc, 0, v129, vcc
	global_store_dwordx4 v[28:29], v[24:27], off
	v_cvt_pk_bf16_f32 v16, v16, v17
	v_cvt_pk_bf16_f32 v17, v18, v19
	v_cvt_pk_bf16_f32 v18, v8, v9
	v_cvt_pk_bf16_f32 v19, v10, v11
	global_store_dwordx4 v[32:33], v[16:19], off offset:256
	v_cvt_pk_bf16_f32 v8, v20, v21
	v_cvt_pk_bf16_f32 v9, v22, v23
	v_cvt_pk_bf16_f32 v10, v12, v13
	v_cvt_pk_bf16_f32 v11, v14, v15
	s_nop 1
	v_lshl_add_u64 v[16:17], v[128:129], 0, s[2:3]
	s_mov_b32 s2, 0xb0000
	v_add_co_u32_e32 v12, vcc, s2, v128
	s_nop 1
	v_addc_co_u32_e32 v13, vcc, 0, v129, vcc
	global_store_dwordx4 v[12:13], v[8:11], off
	v_cvt_pk_bf16_f32 v4, v4, v5
	v_cvt_pk_bf16_f32 v5, v6, v7
	v_cvt_pk_bf16_f32 v6, v0, v1
	v_cvt_pk_bf16_f32 v7, v2, v3
	global_store_dwordx4 v[16:17], v[4:7], off offset:256
	s_waitcnt vmcnt(0)
	s_cbranch_scc0 .LBB0_102
	s_barrier
	s_branch .LBB0_102

.LBB0_121:
	s_lshl_b32 s0, s0, 5
	v_and_b32_e32 v140, 63, v0
	v_and_b32_e32 v7, 48, v0
	v_lshlrev_b32_e32 v8, 6, v0
	s_movk_i32 s9, 0x3c0
	v_lshlrev_b32_e32 v0, 2, v0
	s_and_b32 s53, s0, 0x60
	s_lshl_b32 s52, s1, 6
	s_lshl_b32 s1, s1, 13
	v_and_or_b32 v7, v8, s9, v7
	v_and_b32_e32 v0, 32, v0
	s_lshl_b32 s0, s53, 7
	v_bitop3_b32 v8, v7, s1, v0 bitop3:0xde
	v_bitop3_b32 v141, s0, v7, v0 bitop3:0xf6
	v_lshlrev_b32_e32 v0, 15, v1
	v_and_b32_e32 v0, 0xffff0000, v0
	v_lshl_add_u32 v0, v2, 12, v0
	v_and_b32_e32 v1, 1, v1
	v_lshl_or_b32 v0, v1, 6, v0
	v_lshl_add_u32 v134, v3, 1, v0
	v_lshlrev_b32_e32 v0, 15, v4
	v_and_b32_e32 v0, 0xffff0000, v0
	s_waitcnt vmcnt(8)
	s_barrier
	s_waitcnt vmcnt(6)
	v_lshl_add_u32 v0, v5, 12, v0
	v_and_b32_e32 v1, 1, v4
	v_lshl_or_b32 v0, v1, 6, v0
	v_mov_b32_e32 v135, v193
	v_lshl_add_u32 v136, v6, 1, v0
	v_mov_b32_e32 v137, v193
	s_mov_b32 s54, 0
	v_add_u32_e32 v142, 0, v8
	s_mov_b64 s[28:29], s[4:5]
	s_mov_b64 s[12:13], s[2:3]
	s_barrier

.LBB0_132:
	s_add_i32 s71, s4, 2
	s_add_u32 s5, s2, 0xfff80080
	s_addc_u32 s9, s3, -1
	s_add_i32 s46, 0, 0x10000
	s_cmp_eq_u32 s64, s4
	s_cselect_b32 s4, s28, s67
	s_cselect_b32 s35, s13, s9
	s_cselect_b32 s34, s12, s5
	s_cselect_b32 s5, s29, s69
	v_lshl_add_u64 v[138:139], s[2:3], 0, v[134:135]
	s_add_i32 m0, s40, 0xc000
	s_nop 0
	global_load_lds_dwordx4 v[138:139], off
	v_lshl_add_u64 v[138:139], s[2:3], 0, v[136:137]
	s_add_i32 m0, s40, 0xe000
	s_nop 0
	global_load_lds_dwordx4 v[138:139], off
	v_add_u32_e32 v138, 0x10000, v141
	ds_read_b128 v[144:147], v138
	ds_read_b128 v[148:151], v138 offset:1024
	ds_read_b128 v[152:155], v138 offset:2048
	ds_read_b128 v[156:159], v138 offset:3072
	ds_read_b128 v[160:163], v142
	ds_read_b128 v[164:167], v142 offset:1024
	ds_read_b128 v[168:171], v142 offset:2048
	ds_read_b128 v[172:175], v142 offset:3072
	ds_read_b128 v[176:179], v142 offset:4096
	ds_read_b128 v[180:183], v142 offset:5120
	ds_read_b128 v[184:187], v142 offset:6144
	ds_read_b128 v[188:191], v142 offset:7168
	v_add_u32_e32 v138, 0x14000, v141
	ds_read_b128 v[194:197], v138
	ds_read_b128 v[198:201], v138 offset:1024
	ds_read_b128 v[202:205], v138 offset:2048
	ds_read_b128 v[206:209], v138 offset:3072
	s_waitcnt vmcnt(8)
	s_waitcnt lgkmcnt(0)
	s_barrier
	s_setprio 1
	v_mfma_f32_16x16x32_bf16 v[124:127], v[144:147], v[160:163], v[124:127]
	v_mfma_f32_16x16x32_bf16 v[120:123], v[152:155], v[160:163], v[120:123]
	v_mfma_f32_16x16x32_bf16 v[116:119], v[144:147], v[168:171], v[116:119]
	v_mfma_f32_16x16x32_bf16 v[108:111], v[152:155], v[168:171], v[108:111]
	v_mfma_f32_16x16x32_bf16 v[100:103], v[144:147], v[176:179], v[100:103]
	v_mfma_f32_16x16x32_bf16 v[92:95], v[152:155], v[176:179], v[92:95]
	v_mfma_f32_16x16x32_bf16 v[84:87], v[144:147], v[184:187], v[84:87]
	v_mfma_f32_16x16x32_bf16 v[76:79], v[152:155], v[184:187], v[76:79]
	v_mfma_f32_16x16x32_bf16 v[124:127], v[148:151], v[164:167], v[124:127]
	v_mfma_f32_16x16x32_bf16 v[120:123], v[156:159], v[164:167], v[120:123]
	v_mfma_f32_16x16x32_bf16 v[116:119], v[148:151], v[172:175], v[116:119]
	v_mfma_f32_16x16x32_bf16 v[108:111], v[156:159], v[172:175], v[108:111]
	v_mfma_f32_16x16x32_bf16 v[100:103], v[148:151], v[180:183], v[100:103]
	v_mfma_f32_16x16x32_bf16 v[92:95], v[156:159], v[180:183], v[92:95]
	v_mfma_f32_16x16x32_bf16 v[84:87], v[148:151], v[188:191], v[84:87]
	v_mfma_f32_16x16x32_bf16 v[76:79], v[156:159], v[188:191], v[76:79]
	v_mfma_f32_16x16x32_bf16 v[112:115], v[194:197], v[160:163], v[112:115]
	v_mfma_f32_16x16x32_bf16 v[104:107], v[202:205], v[160:163], v[104:107]
	v_mfma_f32_16x16x32_bf16 v[96:99], v[194:197], v[168:171], v[96:99]
	v_mfma_f32_16x16x32_bf16 v[88:91], v[202:205], v[168:171], v[88:91]
	v_mfma_f32_16x16x32_bf16 v[80:83], v[194:197], v[176:179], v[80:83]
	v_mfma_f32_16x16x32_bf16 v[72:75], v[202:205], v[176:179], v[72:75]
	v_mfma_f32_16x16x32_bf16 v[68:71], v[194:197], v[184:187], v[68:71]
	v_mfma_f32_16x16x32_bf16 v[64:67], v[202:205], v[184:187], v[64:67]
	v_mfma_f32_16x16x32_bf16 v[112:115], v[198:201], v[164:167], v[112:115]
	v_mfma_f32_16x16x32_bf16 v[104:107], v[206:209], v[164:167], v[104:107]
	v_mfma_f32_16x16x32_bf16 v[96:99], v[198:201], v[172:175], v[96:99]
	v_mfma_f32_16x16x32_bf16 v[88:91], v[206:209], v[172:175], v[88:91]
	v_mfma_f32_16x16x32_bf16 v[80:83], v[198:201], v[180:183], v[80:83]
	v_mfma_f32_16x16x32_bf16 v[72:75], v[206:209], v[180:183], v[72:75]
	v_mfma_f32_16x16x32_bf16 v[68:71], v[198:201], v[188:191], v[68:71]
	v_mfma_f32_16x16x32_bf16 v[64:67], v[206:209], v[188:191], v[64:67]
	s_setprio 0
	s_barrier
	s_add_i32 s9, 0, 0x14000
	s_add_i32 s46, s46, s39
	v_lshl_add_u64 v[138:139], s[4:5], 0, v[192:193]
	s_mov_b32 m0, s46
	v_lshl_add_u64 v[210:211], s[4:5], 0, v[132:133]
	global_load_lds_dwordx4 v[138:139], off
	s_add_i32 m0, s46, 0x2000
	s_nop 0
	global_load_lds_dwordx4 v[210:211], off
	s_mov_b32 m0, s40
	v_lshl_add_u64 v[212:213], s[34:35], 0, v[128:129]
	global_load_lds_dwordx4 v[212:213], off
	v_lshl_add_u64 v[214:215], s[34:35], 0, v[130:131]
	s_mov_b32 m0, s41
	s_nop 0
	global_load_lds_dwordx4 v[214:215], off
	s_add_u32 s46, s4, 0x80000
	s_addc_u32 s47, s5, 0
	s_add_i32 s9, s9, s39
	v_lshl_add_u64 v[160:161], s[46:47], 0, v[192:193]
	s_mov_b32 m0, s9
	s_nop 0
	global_load_lds_dwordx4 v[160:161], off
	v_lshl_add_u64 v[162:163], s[46:47], 0, v[132:133]
	s_add_i32 m0, s9, 0x2000
	s_nop 0
	global_load_lds_dwordx4 v[162:163], off
	ds_read_b128 v[160:163], v142 offset:16384
	ds_read_b128 v[164:167], v142 offset:17408
	ds_read_b128 v[168:171], v142 offset:18432
	ds_read_b128 v[172:175], v142 offset:19456
	ds_read_b128 v[176:179], v142 offset:20480
	ds_read_b128 v[180:183], v142 offset:21504
	ds_read_b128 v[184:187], v142 offset:22528
	ds_read_b128 v[188:191], v142 offset:23552
	s_waitcnt vmcnt(8)
	s_waitcnt lgkmcnt(0)
	s_barrier
	s_setprio 1
	v_mfma_f32_16x16x32_bf16 v[60:63], v[144:147], v[160:163], v[60:63]
	v_mfma_f32_16x16x32_bf16 v[56:59], v[152:155], v[160:163], v[56:59]
	v_mfma_f32_16x16x32_bf16 v[52:55], v[144:147], v[168:171], v[52:55]
	v_mfma_f32_16x16x32_bf16 v[44:47], v[152:155], v[168:171], v[44:47]
	v_mfma_f32_16x16x32_bf16 v[36:39], v[144:147], v[176:179], v[36:39]
	v_mfma_f32_16x16x32_bf16 v[28:31], v[152:155], v[176:179], v[28:31]
	v_mfma_f32_16x16x32_bf16 v[20:23], v[144:147], v[184:187], v[20:23]
	v_mfma_f32_16x16x32_bf16 v[12:15], v[152:155], v[184:187], v[12:15]
	v_mfma_f32_16x16x32_bf16 v[60:63], v[148:151], v[164:167], v[60:63]
	v_mfma_f32_16x16x32_bf16 v[56:59], v[156:159], v[164:167], v[56:59]
	v_mfma_f32_16x16x32_bf16 v[52:55], v[148:151], v[172:175], v[52:55]
	v_mfma_f32_16x16x32_bf16 v[44:47], v[156:159], v[172:175], v[44:47]
	v_mfma_f32_16x16x32_bf16 v[36:39], v[148:151], v[180:183], v[36:39]
	v_mfma_f32_16x16x32_bf16 v[28:31], v[156:159], v[180:183], v[28:31]
	v_mfma_f32_16x16x32_bf16 v[20:23], v[148:151], v[188:191], v[20:23]
	v_mfma_f32_16x16x32_bf16 v[12:15], v[156:159], v[188:191], v[12:15]
	v_mfma_f32_16x16x32_bf16 v[48:51], v[194:197], v[160:163], v[48:51]
	v_mfma_f32_16x16x32_bf16 v[40:43], v[202:205], v[160:163], v[40:43]
	v_mfma_f32_16x16x32_bf16 v[32:35], v[194:197], v[168:171], v[32:35]
	v_mfma_f32_16x16x32_bf16 v[24:27], v[202:205], v[168:171], v[24:27]
	v_mfma_f32_16x16x32_bf16 v[16:19], v[194:197], v[176:179], v[16:19]
	v_mfma_f32_16x16x32_bf16 v[8:11], v[202:205], v[176:179], v[8:11]
	v_mfma_f32_16x16x32_bf16 v[4:7], v[194:197], v[184:187], v[4:7]
	v_mfma_f32_16x16x32_bf16 v[0:3], v[202:205], v[184:187], v[0:3]
	v_mfma_f32_16x16x32_bf16 v[48:51], v[198:201], v[164:167], v[48:51]
	v_mfma_f32_16x16x32_bf16 v[40:43], v[206:209], v[164:167], v[40:43]
	v_mfma_f32_16x16x32_bf16 v[32:35], v[198:201], v[172:175], v[32:35]
	v_mfma_f32_16x16x32_bf16 v[24:27], v[206:209], v[172:175], v[24:27]
	v_mfma_f32_16x16x32_bf16 v[16:19], v[198:201], v[180:183], v[16:19]
	v_mfma_f32_16x16x32_bf16 v[8:11], v[206:209], v[180:183], v[8:11]
	v_mfma_f32_16x16x32_bf16 v[4:7], v[198:201], v[188:191], v[4:7]
	v_mfma_f32_16x16x32_bf16 v[0:3], v[206:209], v[188:191], v[0:3]
	s_setprio 0
	s_barrier
	s_add_i32 s9, 0, 0x18000
	s_add_u32 s34, s34, 0x80000
	s_addc_u32 s35, s35, 0
	s_mov_b32 m0, s48
	v_lshl_add_u64 v[194:195], s[34:35], 0, v[128:129]
	global_load_lds_dwordx4 v[194:195], off
	v_lshl_add_u64 v[194:195], s[34:35], 0, v[130:131]
	s_mov_b32 m0, s49
	s_nop 0
	global_load_lds_dwordx4 v[194:195], off
	v_add_u32_e32 v143, 0x18000, v141
	ds_read_b128 v[144:147], v143
	ds_read_b128 v[148:151], v143 offset:1024
	ds_read_b128 v[152:155], v143 offset:2048
	ds_read_b128 v[156:159], v143 offset:3072
	ds_read_b128 v[160:163], v142 offset:32768
	ds_read_b128 v[164:167], v142 offset:33792
	ds_read_b128 v[168:171], v142 offset:34816
	ds_read_b128 v[172:175], v142 offset:35840
	ds_read_b128 v[176:179], v142 offset:36864
	ds_read_b128 v[180:183], v142 offset:37888
	ds_read_b128 v[184:187], v142 offset:38912
	ds_read_b128 v[188:191], v142 offset:39936
	v_add_u32_e32 v143, 0x1c000, v141
	ds_read_b128 v[194:197], v143
	ds_read_b128 v[198:201], v143 offset:1024
	ds_read_b128 v[202:205], v143 offset:2048
	ds_read_b128 v[206:209], v143 offset:3072
	s_waitcnt vmcnt(8)
	s_waitcnt lgkmcnt(0)
	s_barrier
	s_setprio 1
	v_mfma_f32_16x16x32_bf16 v[124:127], v[144:147], v[160:163], v[124:127]
	v_mfma_f32_16x16x32_bf16 v[120:123], v[152:155], v[160:163], v[120:123]
	v_mfma_f32_16x16x32_bf16 v[116:119], v[144:147], v[168:171], v[116:119]
	v_mfma_f32_16x16x32_bf16 v[108:111], v[152:155], v[168:171], v[108:111]
	v_mfma_f32_16x16x32_bf16 v[100:103], v[144:147], v[176:179], v[100:103]
	v_mfma_f32_16x16x32_bf16 v[92:95], v[152:155], v[176:179], v[92:95]
	v_mfma_f32_16x16x32_bf16 v[84:87], v[144:147], v[184:187], v[84:87]
	v_mfma_f32_16x16x32_bf16 v[76:79], v[152:155], v[184:187], v[76:79]
	v_mfma_f32_16x16x32_bf16 v[124:127], v[148:151], v[164:167], v[124:127]
	v_mfma_f32_16x16x32_bf16 v[120:123], v[156:159], v[164:167], v[120:123]
	v_mfma_f32_16x16x32_bf16 v[116:119], v[148:151], v[172:175], v[116:119]
	v_mfma_f32_16x16x32_bf16 v[108:111], v[156:159], v[172:175], v[108:111]
	v_mfma_f32_16x16x32_bf16 v[100:103], v[148:151], v[180:183], v[100:103]
	v_mfma_f32_16x16x32_bf16 v[92:95], v[156:159], v[180:183], v[92:95]
	v_mfma_f32_16x16x32_bf16 v[84:87], v[148:151], v[188:191], v[84:87]
	v_mfma_f32_16x16x32_bf16 v[76:79], v[156:159], v[188:191], v[76:79]
	v_mfma_f32_16x16x32_bf16 v[112:115], v[194:197], v[160:163], v[112:115]
	v_mfma_f32_16x16x32_bf16 v[104:107], v[202:205], v[160:163], v[104:107]
	v_mfma_f32_16x16x32_bf16 v[96:99], v[194:197], v[168:171], v[96:99]
	v_mfma_f32_16x16x32_bf16 v[88:91], v[202:205], v[168:171], v[88:91]
	v_mfma_f32_16x16x32_bf16 v[80:83], v[194:197], v[176:179], v[80:83]
	v_mfma_f32_16x16x32_bf16 v[72:75], v[202:205], v[176:179], v[72:75]
	v_mfma_f32_16x16x32_bf16 v[68:71], v[194:197], v[184:187], v[68:71]
	v_mfma_f32_16x16x32_bf16 v[64:67], v[202:205], v[184:187], v[64:67]
	v_mfma_f32_16x16x32_bf16 v[112:115], v[198:201], v[164:167], v[112:115]
	v_mfma_f32_16x16x32_bf16 v[104:107], v[206:209], v[164:167], v[104:107]
	v_mfma_f32_16x16x32_bf16 v[96:99], v[198:201], v[172:175], v[96:99]
	v_mfma_f32_16x16x32_bf16 v[88:91], v[206:209], v[172:175], v[88:91]
	v_mfma_f32_16x16x32_bf16 v[80:83], v[198:201], v[180:183], v[80:83]
	v_mfma_f32_16x16x32_bf16 v[72:75], v[206:209], v[180:183], v[72:75]
	v_mfma_f32_16x16x32_bf16 v[68:71], v[198:201], v[188:191], v[68:71]
	v_mfma_f32_16x16x32_bf16 v[64:67], v[206:209], v[188:191], v[64:67]
	s_setprio 0
	s_barrier
	s_add_i32 s34, 0, 0x1c000
	s_add_i32 s9, s9, s39
	v_lshl_add_u64 v[138:139], v[138:139], 0, s[72:73]
	s_mov_b32 m0, s9
	s_nop 0
	global_load_lds_dwordx4 v[138:139], off
	v_lshl_add_u64 v[138:139], v[210:211], 0, s[72:73]
	s_add_i32 m0, s9, 0x2000
	s_nop 0
	global_load_lds_dwordx4 v[138:139], off
	s_mov_b32 m0, s50
	v_lshl_add_u64 v[138:139], v[212:213], 0, s[72:73]
	global_load_lds_dwordx4 v[138:139], off
	v_lshl_add_u64 v[138:139], v[214:215], 0, s[72:73]
	s_mov_b32 m0, s51
	s_nop 0
	global_load_lds_dwordx4 v[138:139], off
	s_add_u32 s4, s4, 0x80080
	s_addc_u32 s5, s5, 0
	s_add_i32 s9, s34, s39
	v_lshl_add_u64 v[138:139], s[4:5], 0, v[192:193]
	s_mov_b32 m0, s9
	s_nop 0
	global_load_lds_dwordx4 v[138:139], off
	v_lshl_add_u64 v[138:139], s[4:5], 0, v[132:133]
	s_add_i32 m0, s9, 0x2000
	s_nop 0
	global_load_lds_dwordx4 v[138:139], off
	ds_read_b128 v[160:163], v142 offset:49152
	ds_read_b128 v[164:167], v142 offset:50176
	ds_read_b128 v[168:171], v142 offset:51200
	ds_read_b128 v[172:175], v142 offset:52224
	ds_read_b128 v[176:179], v142 offset:53248
	ds_read_b128 v[180:183], v142 offset:54272
	ds_read_b128 v[184:187], v142 offset:55296
	ds_read_b128 v[188:191], v142 offset:56320
	s_waitcnt vmcnt(8)
	s_waitcnt lgkmcnt(0)
	s_barrier
	s_setprio 1
	v_mfma_f32_16x16x32_bf16 v[60:63], v[144:147], v[160:163], v[60:63]
	v_mfma_f32_16x16x32_bf16 v[56:59], v[152:155], v[160:163], v[56:59]
	v_mfma_f32_16x16x32_bf16 v[52:55], v[144:147], v[168:171], v[52:55]
	v_mfma_f32_16x16x32_bf16 v[44:47], v[152:155], v[168:171], v[44:47]
	v_mfma_f32_16x16x32_bf16 v[36:39], v[144:147], v[176:179], v[36:39]
	v_mfma_f32_16x16x32_bf16 v[28:31], v[152:155], v[176:179], v[28:31]
	v_mfma_f32_16x16x32_bf16 v[20:23], v[144:147], v[184:187], v[20:23]
	v_mfma_f32_16x16x32_bf16 v[12:15], v[152:155], v[184:187], v[12:15]
	v_mfma_f32_16x16x32_bf16 v[60:63], v[148:151], v[164:167], v[60:63]
	v_mfma_f32_16x16x32_bf16 v[56:59], v[156:159], v[164:167], v[56:59]
	v_mfma_f32_16x16x32_bf16 v[52:55], v[148:151], v[172:175], v[52:55]
	v_mfma_f32_16x16x32_bf16 v[44:47], v[156:159], v[172:175], v[44:47]
	v_mfma_f32_16x16x32_bf16 v[36:39], v[148:151], v[180:183], v[36:39]
	v_mfma_f32_16x16x32_bf16 v[28:31], v[156:159], v[180:183], v[28:31]
	v_mfma_f32_16x16x32_bf16 v[20:23], v[148:151], v[188:191], v[20:23]
	v_mfma_f32_16x16x32_bf16 v[12:15], v[156:159], v[188:191], v[12:15]
	v_mfma_f32_16x16x32_bf16 v[48:51], v[194:197], v[160:163], v[48:51]
	v_mfma_f32_16x16x32_bf16 v[40:43], v[202:205], v[160:163], v[40:43]
	v_mfma_f32_16x16x32_bf16 v[32:35], v[194:197], v[168:171], v[32:35]
	v_mfma_f32_16x16x32_bf16 v[24:27], v[202:205], v[168:171], v[24:27]
	v_mfma_f32_16x16x32_bf16 v[16:19], v[194:197], v[176:179], v[16:19]
	v_mfma_f32_16x16x32_bf16 v[8:11], v[202:205], v[176:179], v[8:11]
	v_mfma_f32_16x16x32_bf16 v[4:7], v[194:197], v[184:187], v[4:7]
	v_mfma_f32_16x16x32_bf16 v[0:3], v[202:205], v[184:187], v[0:3]
	v_mfma_f32_16x16x32_bf16 v[48:51], v[198:201], v[164:167], v[48:51]
	v_mfma_f32_16x16x32_bf16 v[40:43], v[206:209], v[164:167], v[40:43]
	v_mfma_f32_16x16x32_bf16 v[32:35], v[198:201], v[172:175], v[32:35]
	v_mfma_f32_16x16x32_bf16 v[24:27], v[206:209], v[172:175], v[24:27]
	v_mfma_f32_16x16x32_bf16 v[16:19], v[198:201], v[180:183], v[16:19]
	v_mfma_f32_16x16x32_bf16 v[8:11], v[206:209], v[180:183], v[8:11]
	v_mfma_f32_16x16x32_bf16 v[4:7], v[198:201], v[188:191], v[4:7]
	v_mfma_f32_16x16x32_bf16 v[0:3], v[206:209], v[188:191], v[0:3]
	s_setprio 0
	s_add_u32 s2, s2, 0x100
	s_addc_u32 s3, s3, 0
	s_add_u32 s67, s67, 0x100
	s_addc_u32 s69, s69, 0
	s_cmp_ge_i32 s71, s63
	s_mov_b32 s4, s71
	s_barrier
	s_cbranch_scc0 .LBB0_132
	v_sub_co_u32_e64 v138, s[2:3], s66, 1
	s_nop 0
	v_readfirstlane_b32 s64, v138
	s_lshl_b64 s[4:5], s[64:65], 22
	v_readlane_b32 s34, v252, 9
	v_readlane_b32 s35, v252, 10
	s_add_u32 s4, s34, s4
	s_addc_u32 s5, s35, s5
	s_sub_i32 s9, s62, 32
	s_and_b64 s[2:3], s[2:3], exec
	v_readlane_b32 s34, v252, 7
	s_cselect_b32 s2, s62, s9
	v_readlane_b32 s35, v252, 8
	s_cselect_b32 s5, s35, s5
	s_cselect_b32 s4, s34, s4
	s_ashr_i32 s3, s2, 31
	s_lshl_b64 s[2:3], s[2:3], 20
	s_add_u32 s2, s4, s2
	v_mov_b32 v139, v140
	s_addc_u32 s3, s5, s3
	v_ashrrev_i32_e32 v138, 1, v139
	s_lshl_b32 s4, s58, 8
	v_and_b32_e32 v138, -8, v138
	s_or_b32 s4, s4, s53
	v_add_u32_e32 v138, s4, v138
	v_and_or_b32 v144, v139, 15, s52
	v_ashrrev_i32_e32 v139, 31, v138
	v_ashrrev_i32_e32 v145, 31, v144
	v_lshl_add_u64 v[146:147], v[138:139], 1, s[2:3]
	v_lshlrev_b64 v[138:139], 12, v[144:145]
	v_lshl_add_u64 v[138:139], v[146:147], 0, v[138:139]
	v_cvt_pk_bf16_f32 v124, v124, v125
	v_cvt_pk_bf16_f32 v125, v126, v127
	v_cvt_pk_bf16_f32 v126, v120, v121
	v_cvt_pk_bf16_f32 v127, v122, v123
	global_store_dwordx4 v[138:139], v[124:127], off
	v_cvt_pk_bf16_f32 v112, v112, v113
	v_cvt_pk_bf16_f32 v113, v114, v115
	v_cvt_pk_bf16_f32 v114, v104, v105
	v_or_b32_e32 v104, 16, v144
	v_ashrrev_i32_e32 v105, 31, v104
	v_lshlrev_b64 v[104:105], 12, v[104:105]
	v_cvt_pk_bf16_f32 v115, v106, v107
	global_store_dwordx4 v[138:139], v[112:115], off offset:256
	s_mov_b64 s[2:3], 0x80000
	s_mov_b32 s58, s55
	v_lshl_add_u64 v[112:113], v[146:147], 0, v[104:105]
	v_cvt_pk_bf16_f32 v104, v116, v117
	v_cvt_pk_bf16_f32 v105, v118, v119
	v_cvt_pk_bf16_f32 v106, v108, v109
	v_cvt_pk_bf16_f32 v107, v110, v111
	global_store_dwordx4 v[112:113], v[104:107], off
	v_cvt_pk_bf16_f32 v96, v96, v97
	v_cvt_pk_bf16_f32 v97, v98, v99
	v_cvt_pk_bf16_f32 v98, v88, v89
	v_or_b32_e32 v88, 32, v144
	v_ashrrev_i32_e32 v89, 31, v88
	v_lshlrev_b64 v[88:89], 12, v[88:89]
	v_cvt_pk_bf16_f32 v99, v90, v91
	global_store_dwordx4 v[112:113], v[96:99], off offset:256
	s_mov_b32 s62, s14
	s_mov_b32 s66, s15
	v_lshl_add_u64 v[96:97], v[146:147], 0, v[88:89]
	v_cvt_pk_bf16_f32 v88, v100, v101
	v_cvt_pk_bf16_f32 v89, v102, v103
	v_cvt_pk_bf16_f32 v90, v92, v93
	v_cvt_pk_bf16_f32 v91, v94, v95
	global_store_dwordx4 v[96:97], v[88:91], off
	v_cvt_pk_bf16_f32 v80, v80, v81
	v_cvt_pk_bf16_f32 v81, v82, v83
	v_cvt_pk_bf16_f32 v82, v72, v73
	v_or_b32_e32 v72, 48, v144
	v_ashrrev_i32_e32 v73, 31, v72
	v_lshlrev_b64 v[72:73], 12, v[72:73]
	v_cvt_pk_bf16_f32 v83, v74, v75
	global_store_dwordx4 v[96:97], v[80:83], off offset:256
	s_mov_b32 s63, s59
	s_mov_b64 s[4:5], s[28:29]
	v_lshl_add_u64 v[80:81], v[146:147], 0, v[72:73]
	v_cvt_pk_bf16_f32 v72, v84, v85
	v_cvt_pk_bf16_f32 v73, v86, v87
	v_cvt_pk_bf16_f32 v74, v76, v77
	v_cvt_pk_bf16_f32 v75, v78, v79
	global_store_dwordx4 v[80:81], v[72:75], off
	v_cvt_pk_bf16_f32 v68, v68, v69
	v_cvt_pk_bf16_f32 v69, v70, v71
	v_cvt_pk_bf16_f32 v70, v64, v65
	v_lshl_add_u64 v[64:65], v[138:139], 0, s[2:3]
	s_mov_b32 s2, 0x80000
	v_cvt_pk_bf16_f32 v71, v66, v67
	global_store_dwordx4 v[80:81], v[68:71], off offset:256
	v_cvt_pk_bf16_f32 v60, v60, v61
	v_cvt_pk_bf16_f32 v61, v62, v63
	v_cvt_pk_bf16_f32 v62, v56, v57
	v_add_co_u32_e32 v56, vcc, s2, v138
	v_cvt_pk_bf16_f32 v63, v58, v59
	s_mov_b64 s[2:3], 0x90000
	s_nop 0
	v_addc_co_u32_e32 v57, vcc, 0, v139, vcc
	global_store_dwordx4 v[56:57], v[60:63], off
	v_cvt_pk_bf16_f32 v48, v48, v49
	v_cvt_pk_bf16_f32 v49, v50, v51
	v_cvt_pk_bf16_f32 v50, v40, v41
	v_cvt_pk_bf16_f32 v51, v42, v43
	global_store_dwordx4 v[64:65], v[48:51], off offset:256
	v_cvt_pk_bf16_f32 v40, v52, v53
	v_cvt_pk_bf16_f32 v41, v54, v55
	v_cvt_pk_bf16_f32 v42, v44, v45
	v_cvt_pk_bf16_f32 v43, v46, v47
	s_nop 1
	v_lshl_add_u64 v[48:49], v[138:139], 0, s[2:3]
	s_mov_b32 s2, 0x90000
	v_add_co_u32_e32 v44, vcc, s2, v138
	s_mov_b64 s[2:3], 0xa0000
	s_nop 0
	v_addc_co_u32_e32 v45, vcc, 0, v139, vcc
	global_store_dwordx4 v[44:45], v[40:43], off
	v_cvt_pk_bf16_f32 v32, v32, v33
	v_cvt_pk_bf16_f32 v33, v34, v35
	v_cvt_pk_bf16_f32 v34, v24, v25
	v_cvt_pk_bf16_f32 v35, v26, v27
	global_store_dwordx4 v[48:49], v[32:35], off offset:256
	v_cvt_pk_bf16_f32 v24, v36, v37
	v_cvt_pk_bf16_f32 v25, v38, v39
	v_cvt_pk_bf16_f32 v26, v28, v29
	v_cvt_pk_bf16_f32 v27, v30, v31
	s_nop 1
	v_lshl_add_u64 v[32:33], v[138:139], 0, s[2:3]
	s_mov_b32 s2, 0xa0000
	v_add_co_u32_e32 v28, vcc, s2, v138
	s_mov_b64 s[2:3], 0xb0000
	s_nop 0
	v_addc_co_u32_e32 v29, vcc, 0, v139, vcc
	global_store_dwordx4 v[28:29], v[24:27], off
	v_cvt_pk_bf16_f32 v16, v16, v17
	v_cvt_pk_bf16_f32 v17, v18, v19
	v_cvt_pk_bf16_f32 v18, v8, v9
	v_cvt_pk_bf16_f32 v19, v10, v11
	global_store_dwordx4 v[32:33], v[16:19], off offset:256
	v_cvt_pk_bf16_f32 v8, v20, v21
	v_cvt_pk_bf16_f32 v9, v22, v23
	v_cvt_pk_bf16_f32 v10, v12, v13
	v_cvt_pk_bf16_f32 v11, v14, v15
	s_nop 1
	v_lshl_add_u64 v[16:17], v[138:139], 0, s[2:3]
	s_mov_b32 s2, 0xb0000
	v_add_co_u32_e32 v12, vcc, s2, v138
	s_mov_b64 s[2:3], s[12:13]
	s_nop 0
	v_addc_co_u32_e32 v13, vcc, 0, v139, vcc
	s_and_b64 vcc, exec, s[0:1]
	global_store_dwordx4 v[12:13], v[8:11], off
	v_cvt_pk_bf16_f32 v4, v4, v5
	v_cvt_pk_bf16_f32 v5, v6, v7
	v_cvt_pk_bf16_f32 v6, v0, v1
	v_cvt_pk_bf16_f32 v7, v2, v3
	global_store_dwordx4 v[16:17], v[4:7], off offset:256
	s_cbranch_vccz .LBB0_122
	s_waitcnt vmcnt(0)
	s_cmpk_gt_u32 s36, 0xff
	s_cbranch_scc1 .LBB0_136
	s_barrier

.LBB0_197:
	v_and_b32_e32 v6, 48, v138
	s_lshl_b32 s0, s0, 5
	v_lshlrev_b32_e32 v7, 6, v138
	s_movk_i32 s2, 0x3c0
	v_and_or_b32 v6, v7, s2, v6
	v_lshlrev_b32_e32 v7, 2, v138
	s_and_b32 s74, s0, 0x60
	s_lshl_b32 s71, s1, 6
	v_and_b32_e32 v7, 32, v7
	s_lshl_b32 s1, s1, 13
	s_lshl_b32 s0, s74, 7
	v_bitop3_b32 v8, v6, s1, v7 bitop3:0xde
	v_bitop3_b32 v139, s0, v6, v7 bitop3:0xf6
	v_lshlrev_b32_e32 v6, 13, v0
	v_and_b32_e32 v6, 0xffffc000, v6
	v_lshl_add_u32 v1, v1, 10, v6
	v_and_b32_e32 v0, 1, v0
	v_lshl_or_b32 v0, v0, 6, v1
	v_lshl_add_u32 v0, v2, 1, v0
	v_mov_b32_e32 v1, v193
	v_lshl_add_u64 v[134:135], s[26:27], 0, v[0:1]
	v_lshlrev_b32_e32 v0, 13, v3
	v_and_b32_e32 v0, 0xffffc000, v0
	v_lshl_add_u32 v0, v4, 10, v0
	v_and_b32_e32 v1, 1, v3
	v_lshl_or_b32 v0, v1, 6, v0
	s_waitcnt vmcnt(8)
	s_barrier
	s_waitcnt vmcnt(6)
	v_lshl_add_u32 v0, v5, 1, v0
	v_mov_b32_e32 v1, v193
	v_lshl_add_u64 v[136:137], s[26:27], 0, v[0:1]
	v_mov_b32_e32 v0, 0
	v_mov_b32_e32 v129, v193
	v_mov_b32_e32 v131, v193
	s_mov_b32 vcc_lo, -2
	s_mov_b64 s[0:1], 0xd320080
	v_add_u32_e32 v140, 0, v8
	v_mov_b32_e32 v1, v0
	v_mov_b32_e32 v2, v0
	v_mov_b32_e32 v3, v0
	v_mov_b32_e32 v4, v0
	v_mov_b32_e32 v5, v0
	v_mov_b32_e32 v6, v0
	v_mov_b32_e32 v7, v0
	v_mov_b32_e32 v8, v0
	v_mov_b32_e32 v9, v0
	v_mov_b32_e32 v10, v0
	v_mov_b32_e32 v11, v0
	v_mov_b32_e32 v16, v0
	v_mov_b32_e32 v17, v0
	v_mov_b32_e32 v18, v0
	v_mov_b32_e32 v19, v0
	v_mov_b32_e32 v24, v0
	v_mov_b32_e32 v25, v0
	v_mov_b32_e32 v26, v0
	v_mov_b32_e32 v27, v0
	v_mov_b32_e32 v32, v0
	v_mov_b32_e32 v33, v0
	v_mov_b32_e32 v34, v0
	v_mov_b32_e32 v35, v0
	v_mov_b32_e32 v40, v0
	v_mov_b32_e32 v41, v0
	v_mov_b32_e32 v42, v0
	v_mov_b32_e32 v43, v0
	v_mov_b32_e32 v48, v0
	v_mov_b32_e32 v49, v0
	v_mov_b32_e32 v50, v0
	v_mov_b32_e32 v51, v0
	v_mov_b32_e32 v12, v0
	v_mov_b32_e32 v13, v0
	v_mov_b32_e32 v14, v0
	v_mov_b32_e32 v15, v0
	v_mov_b32_e32 v20, v0
	v_mov_b32_e32 v21, v0
	v_mov_b32_e32 v22, v0
	v_mov_b32_e32 v23, v0
	v_mov_b32_e32 v28, v0
	v_mov_b32_e32 v29, v0
	v_mov_b32_e32 v30, v0
	v_mov_b32_e32 v31, v0
	v_mov_b32_e32 v36, v0
	v_mov_b32_e32 v37, v0
	v_mov_b32_e32 v38, v0
	v_mov_b32_e32 v39, v0
	v_mov_b32_e32 v44, v0
	v_mov_b32_e32 v45, v0
	v_mov_b32_e32 v46, v0
	v_mov_b32_e32 v47, v0
	v_mov_b32_e32 v52, v0
	v_mov_b32_e32 v53, v0
	v_mov_b32_e32 v54, v0
	v_mov_b32_e32 v55, v0
	v_mov_b32_e32 v56, v0
	v_mov_b32_e32 v57, v0
	v_mov_b32_e32 v58, v0
	v_mov_b32_e32 v59, v0
	v_mov_b32_e32 v60, v0
	v_mov_b32_e32 v61, v0
	v_mov_b32_e32 v62, v0
	v_mov_b32_e32 v63, v0
	v_mov_b32_e32 v64, v0
	v_mov_b32_e32 v65, v0
	v_mov_b32_e32 v66, v0
	v_mov_b32_e32 v67, v0
	v_mov_b32_e32 v68, v0
	v_mov_b32_e32 v69, v0
	v_mov_b32_e32 v70, v0
	v_mov_b32_e32 v71, v0
	v_mov_b32_e32 v72, v0
	v_mov_b32_e32 v73, v0
	v_mov_b32_e32 v74, v0
	v_mov_b32_e32 v75, v0
	v_mov_b32_e32 v80, v0
	v_mov_b32_e32 v81, v0
	v_mov_b32_e32 v82, v0
	v_mov_b32_e32 v83, v0
	v_mov_b32_e32 v88, v0
	v_mov_b32_e32 v89, v0
	v_mov_b32_e32 v90, v0
	v_mov_b32_e32 v91, v0
	v_mov_b32_e32 v96, v0
	v_mov_b32_e32 v97, v0
	v_mov_b32_e32 v98, v0
	v_mov_b32_e32 v99, v0
	v_mov_b32_e32 v104, v0
	v_mov_b32_e32 v105, v0
	v_mov_b32_e32 v106, v0
	v_mov_b32_e32 v107, v0
	v_mov_b32_e32 v112, v0
	v_mov_b32_e32 v113, v0
	v_mov_b32_e32 v114, v0
	v_mov_b32_e32 v115, v0
	v_mov_b32_e32 v76, v0
	v_mov_b32_e32 v77, v0
	v_mov_b32_e32 v78, v0
	v_mov_b32_e32 v79, v0
	v_mov_b32_e32 v84, v0
	v_mov_b32_e32 v85, v0
	v_mov_b32_e32 v86, v0
	v_mov_b32_e32 v87, v0
	v_mov_b32_e32 v92, v0
	v_mov_b32_e32 v93, v0
	v_mov_b32_e32 v94, v0
	v_mov_b32_e32 v95, v0
	v_mov_b32_e32 v100, v0
	v_mov_b32_e32 v101, v0
	v_mov_b32_e32 v102, v0
	v_mov_b32_e32 v103, v0
	v_mov_b32_e32 v108, v0
	v_mov_b32_e32 v109, v0
	v_mov_b32_e32 v110, v0
	v_mov_b32_e32 v111, v0
	v_mov_b32_e32 v116, v0
	v_mov_b32_e32 v117, v0
	v_mov_b32_e32 v118, v0
	v_mov_b32_e32 v119, v0
	v_mov_b32_e32 v120, v0
	v_mov_b32_e32 v121, v0
	v_mov_b32_e32 v122, v0
	v_mov_b32_e32 v123, v0
	v_mov_b32_e32 v124, v0
	v_mov_b32_e32 v125, v0
	v_mov_b32_e32 v126, v0
	v_mov_b32_e32 v127, v0
	s_barrier
.LBB0_198:
	s_add_u32 s2, s0, 0xf2ce0080
	s_addc_u32 s3, s1, -1
	s_cmp_lg_u32 vcc_lo, 4
	s_cselect_b32 s2, s2, 0
	s_cselect_b32 s3, s3, 0
	s_add_u32 s4, s16, s2
	s_addc_u32 s5, s17, s3
	s_add_i32 s9, 0, 0x10000
	s_add_u32 s2, s10, s2
	s_addc_u32 s3, s11, s3
	v_lshl_add_u64 v[194:195], v[134:135], 0, s[0:1]
	s_add_i32 m0, s49, 0xc000
	s_nop 0
	global_load_lds_dwordx4 v[194:195], off
	v_lshl_add_u64 v[194:195], v[136:137], 0, s[0:1]
	s_add_i32 m0, s49, 0xe000
	s_nop 0
	global_load_lds_dwordx4 v[194:195], off
	v_add_u32_e32 v141, 0x10000, v139
	ds_read_b128 v[142:145], v141
	ds_read_b128 v[146:149], v141 offset:1024
	ds_read_b128 v[150:153], v141 offset:2048
	ds_read_b128 v[154:157], v141 offset:3072
	ds_read_b128 v[158:161], v140
	ds_read_b128 v[164:167], v140 offset:1024
	ds_read_b128 v[168:171], v140 offset:2048
	ds_read_b128 v[172:175], v140 offset:3072
	ds_read_b128 v[176:179], v140 offset:4096
	ds_read_b128 v[180:183], v140 offset:5120
	ds_read_b128 v[184:187], v140 offset:6144
	ds_read_b128 v[188:191], v140 offset:7168
	v_add_u32_e32 v141, 0x14000, v139
	ds_read_b128 v[194:197], v141
	ds_read_b128 v[198:201], v141 offset:1024
	ds_read_b128 v[202:205], v141 offset:2048
	ds_read_b128 v[206:209], v141 offset:3072
	s_waitcnt vmcnt(8)
	s_waitcnt lgkmcnt(0)
	s_barrier
	s_setprio 1
	v_mfma_f32_16x16x32_bf16 v[124:127], v[142:145], v[158:161], v[124:127]
	v_mfma_f32_16x16x32_bf16 v[120:123], v[150:153], v[158:161], v[120:123]
	v_mfma_f32_16x16x32_bf16 v[116:119], v[142:145], v[168:171], v[116:119]
	v_mfma_f32_16x16x32_bf16 v[108:111], v[150:153], v[168:171], v[108:111]
	v_mfma_f32_16x16x32_bf16 v[100:103], v[142:145], v[176:179], v[100:103]
	v_mfma_f32_16x16x32_bf16 v[92:95], v[150:153], v[176:179], v[92:95]
	v_mfma_f32_16x16x32_bf16 v[84:87], v[142:145], v[184:187], v[84:87]
	v_mfma_f32_16x16x32_bf16 v[76:79], v[150:153], v[184:187], v[76:79]
	v_mfma_f32_16x16x32_bf16 v[124:127], v[146:149], v[164:167], v[124:127]
	v_mfma_f32_16x16x32_bf16 v[120:123], v[154:157], v[164:167], v[120:123]
	v_mfma_f32_16x16x32_bf16 v[116:119], v[146:149], v[172:175], v[116:119]
	v_mfma_f32_16x16x32_bf16 v[108:111], v[154:157], v[172:175], v[108:111]
	v_mfma_f32_16x16x32_bf16 v[100:103], v[146:149], v[180:183], v[100:103]
	v_mfma_f32_16x16x32_bf16 v[92:95], v[154:157], v[180:183], v[92:95]
	v_mfma_f32_16x16x32_bf16 v[84:87], v[146:149], v[188:191], v[84:87]
	v_mfma_f32_16x16x32_bf16 v[76:79], v[154:157], v[188:191], v[76:79]
	v_mfma_f32_16x16x32_bf16 v[112:115], v[194:197], v[158:161], v[112:115]
	v_mfma_f32_16x16x32_bf16 v[104:107], v[202:205], v[158:161], v[104:107]
	v_mfma_f32_16x16x32_bf16 v[96:99], v[194:197], v[168:171], v[96:99]
	v_mfma_f32_16x16x32_bf16 v[88:91], v[202:205], v[168:171], v[88:91]
	v_mfma_f32_16x16x32_bf16 v[80:83], v[194:197], v[176:179], v[80:83]
	v_mfma_f32_16x16x32_bf16 v[72:75], v[202:205], v[176:179], v[72:75]
	v_mfma_f32_16x16x32_bf16 v[68:71], v[194:197], v[184:187], v[68:71]
	v_mfma_f32_16x16x32_bf16 v[64:67], v[202:205], v[184:187], v[64:67]
	v_mfma_f32_16x16x32_bf16 v[112:115], v[198:201], v[164:167], v[112:115]
	v_mfma_f32_16x16x32_bf16 v[104:107], v[206:209], v[164:167], v[104:107]
	v_mfma_f32_16x16x32_bf16 v[96:99], v[198:201], v[172:175], v[96:99]
	v_mfma_f32_16x16x32_bf16 v[88:91], v[206:209], v[172:175], v[88:91]
	v_mfma_f32_16x16x32_bf16 v[80:83], v[198:201], v[180:183], v[80:83]
	v_mfma_f32_16x16x32_bf16 v[72:75], v[206:209], v[180:183], v[72:75]
	v_mfma_f32_16x16x32_bf16 v[68:71], v[198:201], v[188:191], v[68:71]
	v_mfma_f32_16x16x32_bf16 v[64:67], v[206:209], v[188:191], v[64:67]
	s_setprio 0
	s_barrier
	s_add_i32 vcc_hi, 0, 0x14000
	s_add_i32 s9, s9, s48
	v_lshl_add_u64 v[210:211], s[2:3], 0, v[192:193]
	s_mov_b32 m0, s9
	s_nop 0
	global_load_lds_dwordx4 v[210:211], off
	v_lshl_add_u64 v[212:213], s[2:3], 0, v[132:133]
	s_add_i32 m0, s9, 0x2000
	s_nop 0
	global_load_lds_dwordx4 v[212:213], off
	s_mov_b32 m0, s49
	v_lshl_add_u64 v[214:215], s[4:5], 0, v[128:129]
	global_load_lds_dwordx4 v[214:215], off
	v_lshl_add_u64 v[216:217], s[4:5], 0, v[130:131]
	s_mov_b32 m0, s58
	s_nop 0
	global_load_lds_dwordx4 v[216:217], off
	s_add_u32 s46, s2, 0x80000
	s_addc_u32 s47, s3, 0
	s_add_i32 s9, vcc_hi, s48
	v_lshl_add_u64 v[158:159], s[46:47], 0, v[192:193]
	s_mov_b32 m0, s9
	s_nop 0
	global_load_lds_dwordx4 v[158:159], off
	v_lshl_add_u64 v[160:161], s[46:47], 0, v[132:133]
	s_add_i32 m0, s9, 0x2000
	s_nop 0
	global_load_lds_dwordx4 v[160:161], off
	ds_read_b128 v[158:161], v140 offset:16384
	ds_read_b128 v[164:167], v140 offset:17408
	ds_read_b128 v[168:171], v140 offset:18432
	ds_read_b128 v[172:175], v140 offset:19456
	ds_read_b128 v[176:179], v140 offset:20480
	ds_read_b128 v[180:183], v140 offset:21504
	ds_read_b128 v[184:187], v140 offset:22528
	ds_read_b128 v[188:191], v140 offset:23552
	s_waitcnt vmcnt(8)
	s_waitcnt lgkmcnt(0)
	s_barrier
	s_setprio 1
	v_mfma_f32_16x16x32_bf16 v[60:63], v[142:145], v[158:161], v[60:63]
	v_mfma_f32_16x16x32_bf16 v[56:59], v[150:153], v[158:161], v[56:59]
	v_mfma_f32_16x16x32_bf16 v[52:55], v[142:145], v[168:171], v[52:55]
	v_mfma_f32_16x16x32_bf16 v[44:47], v[150:153], v[168:171], v[44:47]
	v_mfma_f32_16x16x32_bf16 v[36:39], v[142:145], v[176:179], v[36:39]
	v_mfma_f32_16x16x32_bf16 v[28:31], v[150:153], v[176:179], v[28:31]
	v_mfma_f32_16x16x32_bf16 v[20:23], v[142:145], v[184:187], v[20:23]
	v_mfma_f32_16x16x32_bf16 v[12:15], v[150:153], v[184:187], v[12:15]
	v_mfma_f32_16x16x32_bf16 v[60:63], v[146:149], v[164:167], v[60:63]
	v_mfma_f32_16x16x32_bf16 v[56:59], v[154:157], v[164:167], v[56:59]
	v_mfma_f32_16x16x32_bf16 v[52:55], v[146:149], v[172:175], v[52:55]
	v_mfma_f32_16x16x32_bf16 v[44:47], v[154:157], v[172:175], v[44:47]
	v_mfma_f32_16x16x32_bf16 v[36:39], v[146:149], v[180:183], v[36:39]
	v_mfma_f32_16x16x32_bf16 v[28:31], v[154:157], v[180:183], v[28:31]
	v_mfma_f32_16x16x32_bf16 v[20:23], v[146:149], v[188:191], v[20:23]
	v_mfma_f32_16x16x32_bf16 v[12:15], v[154:157], v[188:191], v[12:15]
	v_mfma_f32_16x16x32_bf16 v[48:51], v[194:197], v[158:161], v[48:51]
	v_mfma_f32_16x16x32_bf16 v[40:43], v[202:205], v[158:161], v[40:43]
	v_mfma_f32_16x16x32_bf16 v[32:35], v[194:197], v[168:171], v[32:35]
	v_mfma_f32_16x16x32_bf16 v[24:27], v[202:205], v[168:171], v[24:27]
	v_mfma_f32_16x16x32_bf16 v[16:19], v[194:197], v[176:179], v[16:19]
	v_mfma_f32_16x16x32_bf16 v[8:11], v[202:205], v[176:179], v[8:11]
	v_mfma_f32_16x16x32_bf16 v[4:7], v[194:197], v[184:187], v[4:7]
	v_mfma_f32_16x16x32_bf16 v[0:3], v[202:205], v[184:187], v[0:3]
	v_mfma_f32_16x16x32_bf16 v[48:51], v[198:201], v[164:167], v[48:51]
	v_mfma_f32_16x16x32_bf16 v[40:43], v[206:209], v[164:167], v[40:43]
	v_mfma_f32_16x16x32_bf16 v[32:35], v[198:201], v[172:175], v[32:35]
	v_mfma_f32_16x16x32_bf16 v[24:27], v[206:209], v[172:175], v[24:27]
	v_mfma_f32_16x16x32_bf16 v[16:19], v[198:201], v[180:183], v[16:19]
	v_mfma_f32_16x16x32_bf16 v[8:11], v[206:209], v[180:183], v[8:11]
	v_mfma_f32_16x16x32_bf16 v[4:7], v[198:201], v[188:191], v[4:7]
	v_mfma_f32_16x16x32_bf16 v[0:3], v[206:209], v[188:191], v[0:3]
	s_setprio 0
	s_barrier
	s_add_i32 s9, 0, 0x18000
	s_add_u32 s4, s4, 0x20000
	s_addc_u32 s5, s5, 0
	s_mov_b32 m0, s59
	v_lshl_add_u64 v[194:195], s[4:5], 0, v[128:129]
	global_load_lds_dwordx4 v[194:195], off
	v_lshl_add_u64 v[194:195], s[4:5], 0, v[130:131]
	s_mov_b32 m0, s62
	s_nop 0
	global_load_lds_dwordx4 v[194:195], off
	v_add_u32_e32 v141, 0x18000, v139
	ds_read_b128 v[142:145], v141
	ds_read_b128 v[146:149], v141 offset:1024
	ds_read_b128 v[150:153], v141 offset:2048
	ds_read_b128 v[154:157], v141 offset:3072
	ds_read_b128 v[158:161], v140 offset:32768
	ds_read_b128 v[164:167], v140 offset:33792
	ds_read_b128 v[168:171], v140 offset:34816
	ds_read_b128 v[172:175], v140 offset:35840
	ds_read_b128 v[176:179], v140 offset:36864
	ds_read_b128 v[180:183], v140 offset:37888
	ds_read_b128 v[184:187], v140 offset:38912
	ds_read_b128 v[188:191], v140 offset:39936
	v_add_u32_e32 v141, 0x1c000, v139
	ds_read_b128 v[194:197], v141
	ds_read_b128 v[198:201], v141 offset:1024
	ds_read_b128 v[202:205], v141 offset:2048
	ds_read_b128 v[206:209], v141 offset:3072
	s_waitcnt vmcnt(8)
	s_waitcnt lgkmcnt(0)
	s_barrier
	s_setprio 1
	v_mfma_f32_16x16x32_bf16 v[124:127], v[142:145], v[158:161], v[124:127]
	v_mfma_f32_16x16x32_bf16 v[120:123], v[150:153], v[158:161], v[120:123]
	v_mfma_f32_16x16x32_bf16 v[116:119], v[142:145], v[168:171], v[116:119]
	v_mfma_f32_16x16x32_bf16 v[108:111], v[150:153], v[168:171], v[108:111]
	v_mfma_f32_16x16x32_bf16 v[100:103], v[142:145], v[176:179], v[100:103]
	v_mfma_f32_16x16x32_bf16 v[92:95], v[150:153], v[176:179], v[92:95]
	v_mfma_f32_16x16x32_bf16 v[84:87], v[142:145], v[184:187], v[84:87]
	v_mfma_f32_16x16x32_bf16 v[76:79], v[150:153], v[184:187], v[76:79]
	v_mfma_f32_16x16x32_bf16 v[124:127], v[146:149], v[164:167], v[124:127]
	v_mfma_f32_16x16x32_bf16 v[120:123], v[154:157], v[164:167], v[120:123]
	v_mfma_f32_16x16x32_bf16 v[116:119], v[146:149], v[172:175], v[116:119]
	v_mfma_f32_16x16x32_bf16 v[108:111], v[154:157], v[172:175], v[108:111]
	v_mfma_f32_16x16x32_bf16 v[100:103], v[146:149], v[180:183], v[100:103]
	v_mfma_f32_16x16x32_bf16 v[92:95], v[154:157], v[180:183], v[92:95]
	v_mfma_f32_16x16x32_bf16 v[84:87], v[146:149], v[188:191], v[84:87]
	v_mfma_f32_16x16x32_bf16 v[76:79], v[154:157], v[188:191], v[76:79]
	v_mfma_f32_16x16x32_bf16 v[112:115], v[194:197], v[158:161], v[112:115]
	v_mfma_f32_16x16x32_bf16 v[104:107], v[202:205], v[158:161], v[104:107]
	v_mfma_f32_16x16x32_bf16 v[96:99], v[194:197], v[168:171], v[96:99]
	v_mfma_f32_16x16x32_bf16 v[88:91], v[202:205], v[168:171], v[88:91]
	v_mfma_f32_16x16x32_bf16 v[80:83], v[194:197], v[176:179], v[80:83]
	v_mfma_f32_16x16x32_bf16 v[72:75], v[202:205], v[176:179], v[72:75]
	v_mfma_f32_16x16x32_bf16 v[68:71], v[194:197], v[184:187], v[68:71]
	v_mfma_f32_16x16x32_bf16 v[64:67], v[202:205], v[184:187], v[64:67]
	v_mfma_f32_16x16x32_bf16 v[112:115], v[198:201], v[164:167], v[112:115]
	v_mfma_f32_16x16x32_bf16 v[104:107], v[206:209], v[164:167], v[104:107]
	v_mfma_f32_16x16x32_bf16 v[96:99], v[198:201], v[172:175], v[96:99]
	v_mfma_f32_16x16x32_bf16 v[88:91], v[206:209], v[172:175], v[88:91]
	v_mfma_f32_16x16x32_bf16 v[80:83], v[198:201], v[180:183], v[80:83]
	v_mfma_f32_16x16x32_bf16 v[72:75], v[206:209], v[180:183], v[72:75]
	v_mfma_f32_16x16x32_bf16 v[68:71], v[198:201], v[188:191], v[68:71]
	v_mfma_f32_16x16x32_bf16 v[64:67], v[206:209], v[188:191], v[64:67]
	s_setprio 0
	s_barrier
	s_add_i32 s4, 0, 0x1c000
	s_add_i32 s5, s9, s48
	v_lshl_add_u64 v[210:211], v[210:211], 0, s[72:73]
	s_mov_b32 m0, s5
	s_nop 0
	global_load_lds_dwordx4 v[210:211], off
	v_lshl_add_u64 v[210:211], v[212:213], 0, s[72:73]
	s_add_i32 m0, s5, 0x2000
	s_nop 0
	global_load_lds_dwordx4 v[210:211], off
	s_mov_b32 m0, s63
	v_lshl_add_u64 v[210:211], v[214:215], 0, s[72:73]
	global_load_lds_dwordx4 v[210:211], off
	v_lshl_add_u64 v[210:211], v[216:217], 0, s[72:73]
	s_mov_b32 m0, s64
	s_nop 0
	global_load_lds_dwordx4 v[210:211], off
	s_add_u32 s2, s2, 0x80080
	s_addc_u32 s3, s3, 0
	s_add_i32 s4, s4, s48
	v_lshl_add_u64 v[158:159], s[2:3], 0, v[192:193]
	s_mov_b32 m0, s4
	s_nop 0
	global_load_lds_dwordx4 v[158:159], off
	v_lshl_add_u64 v[160:161], s[2:3], 0, v[132:133]
	s_add_i32 m0, s4, 0x2000
	s_nop 0
	global_load_lds_dwordx4 v[160:161], off
	ds_read_b128 v[158:161], v140 offset:49152
	ds_read_b128 v[164:167], v140 offset:50176
	ds_read_b128 v[168:171], v140 offset:51200
	ds_read_b128 v[172:175], v140 offset:52224
	ds_read_b128 v[176:179], v140 offset:53248
	ds_read_b128 v[180:183], v140 offset:54272
	ds_read_b128 v[184:187], v140 offset:55296
	ds_read_b128 v[188:191], v140 offset:56320
	s_waitcnt vmcnt(8)
	s_waitcnt lgkmcnt(0)
	s_barrier
	s_setprio 1
	v_mfma_f32_16x16x32_bf16 v[60:63], v[142:145], v[158:161], v[60:63]
	v_mfma_f32_16x16x32_bf16 v[56:59], v[150:153], v[158:161], v[56:59]
	v_mfma_f32_16x16x32_bf16 v[52:55], v[142:145], v[168:171], v[52:55]
	v_mfma_f32_16x16x32_bf16 v[44:47], v[150:153], v[168:171], v[44:47]
	v_mfma_f32_16x16x32_bf16 v[36:39], v[142:145], v[176:179], v[36:39]
	v_mfma_f32_16x16x32_bf16 v[28:31], v[150:153], v[176:179], v[28:31]
	v_mfma_f32_16x16x32_bf16 v[20:23], v[142:145], v[184:187], v[20:23]
	v_mfma_f32_16x16x32_bf16 v[12:15], v[150:153], v[184:187], v[12:15]
	v_mfma_f32_16x16x32_bf16 v[60:63], v[146:149], v[164:167], v[60:63]
	v_mfma_f32_16x16x32_bf16 v[56:59], v[154:157], v[164:167], v[56:59]
	v_mfma_f32_16x16x32_bf16 v[52:55], v[146:149], v[172:175], v[52:55]
	v_mfma_f32_16x16x32_bf16 v[44:47], v[154:157], v[172:175], v[44:47]
	v_mfma_f32_16x16x32_bf16 v[36:39], v[146:149], v[180:183], v[36:39]
	v_mfma_f32_16x16x32_bf16 v[28:31], v[154:157], v[180:183], v[28:31]
	v_mfma_f32_16x16x32_bf16 v[20:23], v[146:149], v[188:191], v[20:23]
	v_mfma_f32_16x16x32_bf16 v[12:15], v[154:157], v[188:191], v[12:15]
	v_mfma_f32_16x16x32_bf16 v[48:51], v[194:197], v[158:161], v[48:51]
	v_mfma_f32_16x16x32_bf16 v[40:43], v[202:205], v[158:161], v[40:43]
	v_mfma_f32_16x16x32_bf16 v[32:35], v[194:197], v[168:171], v[32:35]
	v_mfma_f32_16x16x32_bf16 v[24:27], v[202:205], v[168:171], v[24:27]
	v_mfma_f32_16x16x32_bf16 v[16:19], v[194:197], v[176:179], v[16:19]
	v_mfma_f32_16x16x32_bf16 v[8:11], v[202:205], v[176:179], v[8:11]
	v_mfma_f32_16x16x32_bf16 v[4:7], v[194:197], v[184:187], v[4:7]
	v_mfma_f32_16x16x32_bf16 v[0:3], v[202:205], v[184:187], v[0:3]
	v_mfma_f32_16x16x32_bf16 v[48:51], v[198:201], v[164:167], v[48:51]
	v_mfma_f32_16x16x32_bf16 v[40:43], v[206:209], v[164:167], v[40:43]
	v_mfma_f32_16x16x32_bf16 v[32:35], v[198:201], v[172:175], v[32:35]
	v_mfma_f32_16x16x32_bf16 v[24:27], v[206:209], v[172:175], v[24:27]
	v_mfma_f32_16x16x32_bf16 v[16:19], v[198:201], v[180:183], v[16:19]
	v_mfma_f32_16x16x32_bf16 v[8:11], v[206:209], v[180:183], v[8:11]
	v_mfma_f32_16x16x32_bf16 v[4:7], v[198:201], v[188:191], v[4:7]
	v_mfma_f32_16x16x32_bf16 v[0:3], v[206:209], v[188:191], v[0:3]
	s_setprio 0
	s_add_i32 vcc_lo, vcc_lo, 2
	s_add_u32 s0, s0, 0x100
	s_addc_u32 s1, s1, 0
	s_cmp_gt_u32 vcc_lo, 5
	s_barrier
	s_cbranch_scc0 .LBB0_198
	v_and_b32_e32 v128, 63, v138
	v_mov_b32 v128, v128
	s_or_b32 s0, s74, s81
	v_and_or_b32 v130, v128, 15, s71
	v_ashrrev_i32_e32 v128, 1, v128
	v_and_b32_e32 v128, -8, v128
	v_add_u32_e32 v128, s0, v128
	v_ashrrev_i32_e32 v131, 31, v130
	v_ashrrev_i32_e32 v129, 31, v128
	v_lshlrev_b64 v[132:133], 12, v[130:131]
	v_lshl_add_u64 v[132:133], s[14:15], 0, v[132:133]
	v_lshlrev_b64 v[134:135], 1, v[128:129]
	v_lshl_add_u64 v[128:129], v[132:133], 0, v[134:135]
	v_cvt_pk_bf16_f32 v124, v124, v125
	v_cvt_pk_bf16_f32 v125, v126, v127
	v_cvt_pk_bf16_f32 v126, v120, v121
	v_cvt_pk_bf16_f32 v127, v122, v123
	global_store_dwordx4 v[128:129], v[124:127], off
	v_cvt_pk_bf16_f32 v112, v112, v113
	v_cvt_pk_bf16_f32 v113, v114, v115
	v_cvt_pk_bf16_f32 v114, v104, v105
	v_or_b32_e32 v104, 16, v130
	v_ashrrev_i32_e32 v105, 31, v104
	v_lshlrev_b64 v[104:105], 12, v[104:105]
	v_lshl_add_u64 v[104:105], s[14:15], 0, v[104:105]
	v_cvt_pk_bf16_f32 v115, v106, v107
	global_store_dwordx4 v[128:129], v[112:115], off offset:256
	s_mov_b64 s[0:1], 0x80000
	s_cmpk_lt_u32 s31, 0x100
	v_lshl_add_u64 v[112:113], v[104:105], 0, v[134:135]
	v_cvt_pk_bf16_f32 v104, v116, v117
	v_cvt_pk_bf16_f32 v105, v118, v119
	v_cvt_pk_bf16_f32 v106, v108, v109
	v_cvt_pk_bf16_f32 v107, v110, v111
	global_store_dwordx4 v[112:113], v[104:107], off
	v_cvt_pk_bf16_f32 v96, v96, v97
	v_cvt_pk_bf16_f32 v97, v98, v99
	v_cvt_pk_bf16_f32 v98, v88, v89
	v_or_b32_e32 v88, 32, v130
	v_ashrrev_i32_e32 v89, 31, v88
	v_lshlrev_b64 v[88:89], 12, v[88:89]
	v_lshl_add_u64 v[88:89], s[14:15], 0, v[88:89]
	v_cvt_pk_bf16_f32 v99, v90, v91
	global_store_dwordx4 v[112:113], v[96:99], off offset:256
	s_nop 1
	v_lshl_add_u64 v[96:97], v[88:89], 0, v[134:135]
	v_cvt_pk_bf16_f32 v88, v100, v101
	v_cvt_pk_bf16_f32 v89, v102, v103
	v_cvt_pk_bf16_f32 v90, v92, v93
	v_cvt_pk_bf16_f32 v91, v94, v95
	global_store_dwordx4 v[96:97], v[88:91], off
	v_cvt_pk_bf16_f32 v80, v80, v81
	v_cvt_pk_bf16_f32 v81, v82, v83
	v_cvt_pk_bf16_f32 v82, v72, v73
	v_or_b32_e32 v72, 48, v130
	v_ashrrev_i32_e32 v73, 31, v72
	v_lshlrev_b64 v[72:73], 12, v[72:73]
	v_lshl_add_u64 v[72:73], s[14:15], 0, v[72:73]
	v_cvt_pk_bf16_f32 v83, v74, v75
	global_store_dwordx4 v[96:97], v[80:83], off offset:256
	s_nop 1
	v_lshl_add_u64 v[80:81], v[72:73], 0, v[134:135]
	v_cvt_pk_bf16_f32 v72, v84, v85
	v_cvt_pk_bf16_f32 v73, v86, v87
	v_cvt_pk_bf16_f32 v74, v76, v77
	v_cvt_pk_bf16_f32 v75, v78, v79
	global_store_dwordx4 v[80:81], v[72:75], off
	v_cvt_pk_bf16_f32 v68, v68, v69
	v_cvt_pk_bf16_f32 v69, v70, v71
	v_cvt_pk_bf16_f32 v70, v64, v65
	v_lshl_add_u64 v[64:65], v[128:129], 0, s[0:1]
	s_mov_b32 s0, 0x80000
	v_cvt_pk_bf16_f32 v71, v66, v67
	global_store_dwordx4 v[80:81], v[68:71], off offset:256
	v_cvt_pk_bf16_f32 v60, v60, v61
	v_cvt_pk_bf16_f32 v61, v62, v63
	v_cvt_pk_bf16_f32 v62, v56, v57
	v_add_co_u32_e32 v56, vcc, s0, v128
	v_cvt_pk_bf16_f32 v63, v58, v59
	s_mov_b64 s[0:1], 0x90000
	s_nop 0
	v_addc_co_u32_e32 v57, vcc, 0, v129, vcc
	global_store_dwordx4 v[56:57], v[60:63], off
	v_cvt_pk_bf16_f32 v48, v48, v49
	v_cvt_pk_bf16_f32 v49, v50, v51
	v_cvt_pk_bf16_f32 v50, v40, v41
	v_cvt_pk_bf16_f32 v51, v42, v43
	global_store_dwordx4 v[64:65], v[48:51], off offset:256
	v_cvt_pk_bf16_f32 v40, v52, v53
	v_cvt_pk_bf16_f32 v41, v54, v55
	v_cvt_pk_bf16_f32 v42, v44, v45
	v_cvt_pk_bf16_f32 v43, v46, v47
	s_nop 1
	v_lshl_add_u64 v[48:49], v[128:129], 0, s[0:1]
	s_mov_b32 s0, 0x90000
	v_add_co_u32_e32 v44, vcc, s0, v128
	s_mov_b64 s[0:1], 0xa0000
	s_nop 0
	v_addc_co_u32_e32 v45, vcc, 0, v129, vcc
	global_store_dwordx4 v[44:45], v[40:43], off
	v_cvt_pk_bf16_f32 v32, v32, v33
	v_cvt_pk_bf16_f32 v33, v34, v35
	v_cvt_pk_bf16_f32 v34, v24, v25
	v_cvt_pk_bf16_f32 v35, v26, v27
	global_store_dwordx4 v[48:49], v[32:35], off offset:256
	v_cvt_pk_bf16_f32 v24, v36, v37
	v_cvt_pk_bf16_f32 v25, v38, v39
	v_cvt_pk_bf16_f32 v26, v28, v29
	v_cvt_pk_bf16_f32 v27, v30, v31
	s_nop 1
	v_lshl_add_u64 v[32:33], v[128:129], 0, s[0:1]
	s_mov_b32 s0, 0xa0000
	v_add_co_u32_e32 v28, vcc, s0, v128
	s_mov_b64 s[0:1], 0xb0000
	s_nop 0
	v_addc_co_u32_e32 v29, vcc, 0, v129, vcc
	global_store_dwordx4 v[28:29], v[24:27], off
	v_cvt_pk_bf16_f32 v16, v16, v17
	v_cvt_pk_bf16_f32 v17, v18, v19
	v_cvt_pk_bf16_f32 v18, v8, v9
	v_cvt_pk_bf16_f32 v19, v10, v11
	global_store_dwordx4 v[32:33], v[16:19], off offset:256
	v_cvt_pk_bf16_f32 v8, v20, v21
	v_cvt_pk_bf16_f32 v9, v22, v23
	v_cvt_pk_bf16_f32 v10, v12, v13
	v_cvt_pk_bf16_f32 v11, v14, v15
	s_nop 1
	v_lshl_add_u64 v[16:17], v[128:129], 0, s[0:1]
	s_mov_b32 s0, 0xb0000
	v_add_co_u32_e32 v12, vcc, s0, v128
	s_nop 1
	v_addc_co_u32_e32 v13, vcc, 0, v129, vcc
	global_store_dwordx4 v[12:13], v[8:11], off
	v_cvt_pk_bf16_f32 v4, v4, v5
	v_cvt_pk_bf16_f32 v5, v6, v7
	v_cvt_pk_bf16_f32 v6, v0, v1
	v_cvt_pk_bf16_f32 v7, v2, v3
	global_store_dwordx4 v[16:17], v[4:7], off offset:256
	s_waitcnt vmcnt(0)
	s_cbranch_scc0 .LBB0_201
	s_barrier

.LBB0_231:
	v_and_b32_e32 v140, 63, v0
	s_lshl_b32 s58, s15, 6
	v_and_b32_e32 v7, 48, v0
	s_lshl_b32 s9, s15, 13
	v_lshlrev_b32_e32 v8, 6, v0
	s_movk_i32 s15, 0x3c0
	v_lshlrev_b32_e32 v0, 2, v0
	v_and_or_b32 v7, v8, s15, v7
	v_and_b32_e32 v0, 32, v0
	v_bitop3_b32 v8, v7, s9, v0 bitop3:0xde
	s_lshl_b32 s9, s14, 5
	s_and_b32 s59, s9, 0x60
	s_lshl_b32 s9, s59, 7
	v_bitop3_b32 v141, s9, v7, v0 bitop3:0xf6
	v_lshlrev_b32_e32 v0, 17, v1
	v_and_b32_e32 v0, 0xfffc0000, v0
	v_lshl_add_u32 v0, v2, 14, v0
	v_and_b32_e32 v1, 1, v1
	v_lshl_or_b32 v0, v1, 6, v0
	v_lshl_add_u32 v134, v3, 1, v0
	v_lshlrev_b32_e32 v0, 17, v4
	v_and_b32_e32 v0, 0xfffc0000, v0
	s_waitcnt vmcnt(8)
	s_barrier
	s_waitcnt vmcnt(6)
	v_lshl_add_u32 v0, v5, 14, v0
	v_and_b32_e32 v1, 1, v4
	v_lshl_or_b32 v0, v1, 6, v0
	v_mov_b32_e32 v135, v193
	v_lshl_add_u32 v136, v6, 1, v0
	v_mov_b32_e32 v137, v193
	s_mov_b32 s62, 0
	v_add_u32_e32 v142, 0, v8
	s_mov_b64 s[36:37], s[4:5]
	s_mov_b64 s[28:29], s[2:3]
	s_barrier

.LBB0_242:
	s_add_i32 s79, s4, 2
	s_add_u32 s5, s2, 0xffe00080
	s_addc_u32 s9, s3, -1
	s_add_i32 s46, 0, 0x10000
	s_cmp_eq_u32 s64, s4
	s_cselect_b32 s4, s36, s75
	s_cselect_b32 s39, s29, s9
	s_cselect_b32 s38, s28, s5
	s_cselect_b32 s5, s37, s78
	v_lshl_add_u64 v[138:139], s[2:3], 0, v[134:135]
	s_add_i32 m0, s50, 0xc000
	s_nop 0
	global_load_lds_dwordx4 v[138:139], off
	v_lshl_add_u64 v[138:139], s[2:3], 0, v[136:137]
	s_add_i32 m0, s50, 0xe000
	s_nop 0
	global_load_lds_dwordx4 v[138:139], off
	v_add_u32_e32 v138, 0x10000, v141
	ds_read_b128 v[144:147], v138
	ds_read_b128 v[148:151], v138 offset:1024
	ds_read_b128 v[152:155], v138 offset:2048
	ds_read_b128 v[156:159], v138 offset:3072
	ds_read_b128 v[160:163], v142
	ds_read_b128 v[164:167], v142 offset:1024
	ds_read_b128 v[168:171], v142 offset:2048
	ds_read_b128 v[172:175], v142 offset:3072
	ds_read_b128 v[176:179], v142 offset:4096
	ds_read_b128 v[180:183], v142 offset:5120
	ds_read_b128 v[184:187], v142 offset:6144
	ds_read_b128 v[188:191], v142 offset:7168
	v_add_u32_e32 v138, 0x14000, v141
	ds_read_b128 v[194:197], v138
	ds_read_b128 v[198:201], v138 offset:1024
	ds_read_b128 v[202:205], v138 offset:2048
	ds_read_b128 v[206:209], v138 offset:3072
	s_waitcnt vmcnt(8)
	s_waitcnt lgkmcnt(0)
	s_barrier
	s_setprio 1
	v_mfma_f32_16x16x32_bf16 v[124:127], v[144:147], v[160:163], v[124:127]
	v_mfma_f32_16x16x32_bf16 v[120:123], v[152:155], v[160:163], v[120:123]
	v_mfma_f32_16x16x32_bf16 v[116:119], v[144:147], v[168:171], v[116:119]
	v_mfma_f32_16x16x32_bf16 v[108:111], v[152:155], v[168:171], v[108:111]
	v_mfma_f32_16x16x32_bf16 v[100:103], v[144:147], v[176:179], v[100:103]
	v_mfma_f32_16x16x32_bf16 v[92:95], v[152:155], v[176:179], v[92:95]
	v_mfma_f32_16x16x32_bf16 v[84:87], v[144:147], v[184:187], v[84:87]
	v_mfma_f32_16x16x32_bf16 v[76:79], v[152:155], v[184:187], v[76:79]
	v_mfma_f32_16x16x32_bf16 v[124:127], v[148:151], v[164:167], v[124:127]
	v_mfma_f32_16x16x32_bf16 v[120:123], v[156:159], v[164:167], v[120:123]
	v_mfma_f32_16x16x32_bf16 v[116:119], v[148:151], v[172:175], v[116:119]
	v_mfma_f32_16x16x32_bf16 v[108:111], v[156:159], v[172:175], v[108:111]
	v_mfma_f32_16x16x32_bf16 v[100:103], v[148:151], v[180:183], v[100:103]
	v_mfma_f32_16x16x32_bf16 v[92:95], v[156:159], v[180:183], v[92:95]
	v_mfma_f32_16x16x32_bf16 v[84:87], v[148:151], v[188:191], v[84:87]
	v_mfma_f32_16x16x32_bf16 v[76:79], v[156:159], v[188:191], v[76:79]
	v_mfma_f32_16x16x32_bf16 v[112:115], v[194:197], v[160:163], v[112:115]
	v_mfma_f32_16x16x32_bf16 v[104:107], v[202:205], v[160:163], v[104:107]
	v_mfma_f32_16x16x32_bf16 v[96:99], v[194:197], v[168:171], v[96:99]
	v_mfma_f32_16x16x32_bf16 v[88:91], v[202:205], v[168:171], v[88:91]
	v_mfma_f32_16x16x32_bf16 v[80:83], v[194:197], v[176:179], v[80:83]
	v_mfma_f32_16x16x32_bf16 v[72:75], v[202:205], v[176:179], v[72:75]
	v_mfma_f32_16x16x32_bf16 v[68:71], v[194:197], v[184:187], v[68:71]
	v_mfma_f32_16x16x32_bf16 v[64:67], v[202:205], v[184:187], v[64:67]
	v_mfma_f32_16x16x32_bf16 v[112:115], v[198:201], v[164:167], v[112:115]
	v_mfma_f32_16x16x32_bf16 v[104:107], v[206:209], v[164:167], v[104:107]
	v_mfma_f32_16x16x32_bf16 v[96:99], v[198:201], v[172:175], v[96:99]
	v_mfma_f32_16x16x32_bf16 v[88:91], v[206:209], v[172:175], v[88:91]
	v_mfma_f32_16x16x32_bf16 v[80:83], v[198:201], v[180:183], v[80:83]
	v_mfma_f32_16x16x32_bf16 v[72:75], v[206:209], v[180:183], v[72:75]
	v_mfma_f32_16x16x32_bf16 v[68:71], v[198:201], v[188:191], v[68:71]
	v_mfma_f32_16x16x32_bf16 v[64:67], v[206:209], v[188:191], v[64:67]
	s_setprio 0
	s_barrier
	s_add_i32 s9, 0, 0x14000
	s_add_i32 s46, s46, s49
	v_lshl_add_u64 v[138:139], s[4:5], 0, v[192:193]
	s_mov_b32 m0, s46
	v_lshl_add_u64 v[210:211], s[4:5], 0, v[132:133]
	global_load_lds_dwordx4 v[138:139], off
	s_add_i32 m0, s46, 0x2000
	s_nop 0
	global_load_lds_dwordx4 v[210:211], off
	s_mov_b32 m0, s50
	v_lshl_add_u64 v[212:213], s[38:39], 0, v[128:129]
	global_load_lds_dwordx4 v[212:213], off
	v_lshl_add_u64 v[214:215], s[38:39], 0, v[130:131]
	s_mov_b32 m0, s51
	s_nop 0
	global_load_lds_dwordx4 v[214:215], off
	s_add_u32 s46, s4, 0x200000
	s_addc_u32 s47, s5, 0
	s_add_i32 s9, s9, s49
	v_lshl_add_u64 v[160:161], s[46:47], 0, v[192:193]
	s_mov_b32 m0, s9
	s_nop 0
	global_load_lds_dwordx4 v[160:161], off
	v_lshl_add_u64 v[162:163], s[46:47], 0, v[132:133]
	s_add_i32 m0, s9, 0x2000
	s_nop 0
	global_load_lds_dwordx4 v[162:163], off
	ds_read_b128 v[160:163], v142 offset:16384
	ds_read_b128 v[164:167], v142 offset:17408
	ds_read_b128 v[168:171], v142 offset:18432
	ds_read_b128 v[172:175], v142 offset:19456
	ds_read_b128 v[176:179], v142 offset:20480
	ds_read_b128 v[180:183], v142 offset:21504
	ds_read_b128 v[184:187], v142 offset:22528
	ds_read_b128 v[188:191], v142 offset:23552
	s_waitcnt vmcnt(8)
	s_waitcnt lgkmcnt(0)
	s_barrier
	s_setprio 1
	v_mfma_f32_16x16x32_bf16 v[60:63], v[144:147], v[160:163], v[60:63]
	v_mfma_f32_16x16x32_bf16 v[56:59], v[152:155], v[160:163], v[56:59]
	v_mfma_f32_16x16x32_bf16 v[52:55], v[144:147], v[168:171], v[52:55]
	v_mfma_f32_16x16x32_bf16 v[44:47], v[152:155], v[168:171], v[44:47]
	v_mfma_f32_16x16x32_bf16 v[36:39], v[144:147], v[176:179], v[36:39]
	v_mfma_f32_16x16x32_bf16 v[28:31], v[152:155], v[176:179], v[28:31]
	v_mfma_f32_16x16x32_bf16 v[20:23], v[144:147], v[184:187], v[20:23]
	v_mfma_f32_16x16x32_bf16 v[12:15], v[152:155], v[184:187], v[12:15]
	v_mfma_f32_16x16x32_bf16 v[60:63], v[148:151], v[164:167], v[60:63]
	v_mfma_f32_16x16x32_bf16 v[56:59], v[156:159], v[164:167], v[56:59]
	v_mfma_f32_16x16x32_bf16 v[52:55], v[148:151], v[172:175], v[52:55]
	v_mfma_f32_16x16x32_bf16 v[44:47], v[156:159], v[172:175], v[44:47]
	v_mfma_f32_16x16x32_bf16 v[36:39], v[148:151], v[180:183], v[36:39]
	v_mfma_f32_16x16x32_bf16 v[28:31], v[156:159], v[180:183], v[28:31]
	v_mfma_f32_16x16x32_bf16 v[20:23], v[148:151], v[188:191], v[20:23]
	v_mfma_f32_16x16x32_bf16 v[12:15], v[156:159], v[188:191], v[12:15]
	v_mfma_f32_16x16x32_bf16 v[48:51], v[194:197], v[160:163], v[48:51]
	v_mfma_f32_16x16x32_bf16 v[40:43], v[202:205], v[160:163], v[40:43]
	v_mfma_f32_16x16x32_bf16 v[32:35], v[194:197], v[168:171], v[32:35]
	v_mfma_f32_16x16x32_bf16 v[24:27], v[202:205], v[168:171], v[24:27]
	v_mfma_f32_16x16x32_bf16 v[16:19], v[194:197], v[176:179], v[16:19]
	v_mfma_f32_16x16x32_bf16 v[8:11], v[202:205], v[176:179], v[8:11]
	v_mfma_f32_16x16x32_bf16 v[4:7], v[194:197], v[184:187], v[4:7]
	v_mfma_f32_16x16x32_bf16 v[0:3], v[202:205], v[184:187], v[0:3]
	v_mfma_f32_16x16x32_bf16 v[48:51], v[198:201], v[164:167], v[48:51]
	v_mfma_f32_16x16x32_bf16 v[40:43], v[206:209], v[164:167], v[40:43]
	v_mfma_f32_16x16x32_bf16 v[32:35], v[198:201], v[172:175], v[32:35]
	v_mfma_f32_16x16x32_bf16 v[24:27], v[206:209], v[172:175], v[24:27]
	v_mfma_f32_16x16x32_bf16 v[16:19], v[198:201], v[180:183], v[16:19]
	v_mfma_f32_16x16x32_bf16 v[8:11], v[206:209], v[180:183], v[8:11]
	v_mfma_f32_16x16x32_bf16 v[4:7], v[198:201], v[188:191], v[4:7]
	v_mfma_f32_16x16x32_bf16 v[0:3], v[206:209], v[188:191], v[0:3]
	s_setprio 0
	s_barrier
	s_add_i32 s9, 0, 0x18000
	s_add_u32 s38, s38, 0x200000
	s_addc_u32 s39, s39, 0
	s_mov_b32 m0, s52
	v_lshl_add_u64 v[194:195], s[38:39], 0, v[128:129]
	global_load_lds_dwordx4 v[194:195], off
	v_lshl_add_u64 v[194:195], s[38:39], 0, v[130:131]
	s_mov_b32 m0, s53
	s_nop 0
	global_load_lds_dwordx4 v[194:195], off
	v_add_u32_e32 v143, 0x18000, v141
	ds_read_b128 v[144:147], v143
	ds_read_b128 v[148:151], v143 offset:1024
	ds_read_b128 v[152:155], v143 offset:2048
	ds_read_b128 v[156:159], v143 offset:3072
	ds_read_b128 v[160:163], v142 offset:32768
	ds_read_b128 v[164:167], v142 offset:33792
	ds_read_b128 v[168:171], v142 offset:34816
	ds_read_b128 v[172:175], v142 offset:35840
	ds_read_b128 v[176:179], v142 offset:36864
	ds_read_b128 v[180:183], v142 offset:37888
	ds_read_b128 v[184:187], v142 offset:38912
	ds_read_b128 v[188:191], v142 offset:39936
	v_add_u32_e32 v143, 0x1c000, v141
	ds_read_b128 v[194:197], v143
	ds_read_b128 v[198:201], v143 offset:1024
	ds_read_b128 v[202:205], v143 offset:2048
	ds_read_b128 v[206:209], v143 offset:3072
	s_waitcnt vmcnt(8)
	s_waitcnt lgkmcnt(0)
	s_barrier
	s_setprio 1
	v_mfma_f32_16x16x32_bf16 v[124:127], v[144:147], v[160:163], v[124:127]
	v_mfma_f32_16x16x32_bf16 v[120:123], v[152:155], v[160:163], v[120:123]
	v_mfma_f32_16x16x32_bf16 v[116:119], v[144:147], v[168:171], v[116:119]
	v_mfma_f32_16x16x32_bf16 v[108:111], v[152:155], v[168:171], v[108:111]
	v_mfma_f32_16x16x32_bf16 v[100:103], v[144:147], v[176:179], v[100:103]
	v_mfma_f32_16x16x32_bf16 v[92:95], v[152:155], v[176:179], v[92:95]
	v_mfma_f32_16x16x32_bf16 v[84:87], v[144:147], v[184:187], v[84:87]
	v_mfma_f32_16x16x32_bf16 v[76:79], v[152:155], v[184:187], v[76:79]
	v_mfma_f32_16x16x32_bf16 v[124:127], v[148:151], v[164:167], v[124:127]
	v_mfma_f32_16x16x32_bf16 v[120:123], v[156:159], v[164:167], v[120:123]
	v_mfma_f32_16x16x32_bf16 v[116:119], v[148:151], v[172:175], v[116:119]
	v_mfma_f32_16x16x32_bf16 v[108:111], v[156:159], v[172:175], v[108:111]
	v_mfma_f32_16x16x32_bf16 v[100:103], v[148:151], v[180:183], v[100:103]
	v_mfma_f32_16x16x32_bf16 v[92:95], v[156:159], v[180:183], v[92:95]
	v_mfma_f32_16x16x32_bf16 v[84:87], v[148:151], v[188:191], v[84:87]
	v_mfma_f32_16x16x32_bf16 v[76:79], v[156:159], v[188:191], v[76:79]
	v_mfma_f32_16x16x32_bf16 v[112:115], v[194:197], v[160:163], v[112:115]
	v_mfma_f32_16x16x32_bf16 v[104:107], v[202:205], v[160:163], v[104:107]
	v_mfma_f32_16x16x32_bf16 v[96:99], v[194:197], v[168:171], v[96:99]
	v_mfma_f32_16x16x32_bf16 v[88:91], v[202:205], v[168:171], v[88:91]
	v_mfma_f32_16x16x32_bf16 v[80:83], v[194:197], v[176:179], v[80:83]
	v_mfma_f32_16x16x32_bf16 v[72:75], v[202:205], v[176:179], v[72:75]
	v_mfma_f32_16x16x32_bf16 v[68:71], v[194:197], v[184:187], v[68:71]
	v_mfma_f32_16x16x32_bf16 v[64:67], v[202:205], v[184:187], v[64:67]
	v_mfma_f32_16x16x32_bf16 v[112:115], v[198:201], v[164:167], v[112:115]
	v_mfma_f32_16x16x32_bf16 v[104:107], v[206:209], v[164:167], v[104:107]
	v_mfma_f32_16x16x32_bf16 v[96:99], v[198:201], v[172:175], v[96:99]
	v_mfma_f32_16x16x32_bf16 v[88:91], v[206:209], v[172:175], v[88:91]
	v_mfma_f32_16x16x32_bf16 v[80:83], v[198:201], v[180:183], v[80:83]
	v_mfma_f32_16x16x32_bf16 v[72:75], v[206:209], v[180:183], v[72:75]
	v_mfma_f32_16x16x32_bf16 v[68:71], v[198:201], v[188:191], v[68:71]
	v_mfma_f32_16x16x32_bf16 v[64:67], v[206:209], v[188:191], v[64:67]
	s_setprio 0
	s_barrier
	s_add_i32 s38, 0, 0x1c000
	s_add_i32 s9, s9, s49
	v_lshl_add_u64 v[138:139], v[138:139], 0, s[72:73]
	s_mov_b32 m0, s9
	s_nop 0
	global_load_lds_dwordx4 v[138:139], off
	v_lshl_add_u64 v[138:139], v[210:211], 0, s[72:73]
	s_add_i32 m0, s9, 0x2000
	s_nop 0
	global_load_lds_dwordx4 v[138:139], off
	s_mov_b32 m0, s54
	v_lshl_add_u64 v[138:139], v[212:213], 0, s[72:73]
	global_load_lds_dwordx4 v[138:139], off
	v_lshl_add_u64 v[138:139], v[214:215], 0, s[72:73]
	s_mov_b32 m0, s55
	s_nop 0
	global_load_lds_dwordx4 v[138:139], off
	s_add_u32 s4, s4, 0x200080
	s_addc_u32 s5, s5, 0
	s_add_i32 s9, s38, s49
	v_lshl_add_u64 v[138:139], s[4:5], 0, v[192:193]
	s_mov_b32 m0, s9
	s_nop 0
	global_load_lds_dwordx4 v[138:139], off
	v_lshl_add_u64 v[138:139], s[4:5], 0, v[132:133]
	s_add_i32 m0, s9, 0x2000
	s_nop 0
	global_load_lds_dwordx4 v[138:139], off
	ds_read_b128 v[160:163], v142 offset:49152
	ds_read_b128 v[164:167], v142 offset:50176
	ds_read_b128 v[168:171], v142 offset:51200
	ds_read_b128 v[172:175], v142 offset:52224
	ds_read_b128 v[176:179], v142 offset:53248
	ds_read_b128 v[180:183], v142 offset:54272
	ds_read_b128 v[184:187], v142 offset:55296
	ds_read_b128 v[188:191], v142 offset:56320
	s_waitcnt vmcnt(8)
	s_waitcnt lgkmcnt(0)
	s_barrier
	s_setprio 1
	v_mfma_f32_16x16x32_bf16 v[60:63], v[144:147], v[160:163], v[60:63]
	v_mfma_f32_16x16x32_bf16 v[56:59], v[152:155], v[160:163], v[56:59]
	v_mfma_f32_16x16x32_bf16 v[52:55], v[144:147], v[168:171], v[52:55]
	v_mfma_f32_16x16x32_bf16 v[44:47], v[152:155], v[168:171], v[44:47]
	v_mfma_f32_16x16x32_bf16 v[36:39], v[144:147], v[176:179], v[36:39]
	v_mfma_f32_16x16x32_bf16 v[28:31], v[152:155], v[176:179], v[28:31]
	v_mfma_f32_16x16x32_bf16 v[20:23], v[144:147], v[184:187], v[20:23]
	v_mfma_f32_16x16x32_bf16 v[12:15], v[152:155], v[184:187], v[12:15]
	v_mfma_f32_16x16x32_bf16 v[60:63], v[148:151], v[164:167], v[60:63]
	v_mfma_f32_16x16x32_bf16 v[56:59], v[156:159], v[164:167], v[56:59]
	v_mfma_f32_16x16x32_bf16 v[52:55], v[148:151], v[172:175], v[52:55]
	v_mfma_f32_16x16x32_bf16 v[44:47], v[156:159], v[172:175], v[44:47]
	v_mfma_f32_16x16x32_bf16 v[36:39], v[148:151], v[180:183], v[36:39]
	v_mfma_f32_16x16x32_bf16 v[28:31], v[156:159], v[180:183], v[28:31]
	v_mfma_f32_16x16x32_bf16 v[20:23], v[148:151], v[188:191], v[20:23]
	v_mfma_f32_16x16x32_bf16 v[12:15], v[156:159], v[188:191], v[12:15]
	v_mfma_f32_16x16x32_bf16 v[48:51], v[194:197], v[160:163], v[48:51]
	v_mfma_f32_16x16x32_bf16 v[40:43], v[202:205], v[160:163], v[40:43]
	v_mfma_f32_16x16x32_bf16 v[32:35], v[194:197], v[168:171], v[32:35]
	v_mfma_f32_16x16x32_bf16 v[24:27], v[202:205], v[168:171], v[24:27]
	v_mfma_f32_16x16x32_bf16 v[16:19], v[194:197], v[176:179], v[16:19]
	v_mfma_f32_16x16x32_bf16 v[8:11], v[202:205], v[176:179], v[8:11]
	v_mfma_f32_16x16x32_bf16 v[4:7], v[194:197], v[184:187], v[4:7]
	v_mfma_f32_16x16x32_bf16 v[0:3], v[202:205], v[184:187], v[0:3]
	v_mfma_f32_16x16x32_bf16 v[48:51], v[198:201], v[164:167], v[48:51]
	v_mfma_f32_16x16x32_bf16 v[40:43], v[206:209], v[164:167], v[40:43]
	v_mfma_f32_16x16x32_bf16 v[32:35], v[198:201], v[172:175], v[32:35]
	v_mfma_f32_16x16x32_bf16 v[24:27], v[206:209], v[172:175], v[24:27]
	v_mfma_f32_16x16x32_bf16 v[16:19], v[198:201], v[180:183], v[16:19]
	v_mfma_f32_16x16x32_bf16 v[8:11], v[206:209], v[180:183], v[8:11]
	v_mfma_f32_16x16x32_bf16 v[4:7], v[198:201], v[188:191], v[4:7]
	v_mfma_f32_16x16x32_bf16 v[0:3], v[206:209], v[188:191], v[0:3]
	s_setprio 0
	s_add_u32 s2, s2, 0x100
	s_addc_u32 s3, s3, 0
	s_add_u32 s75, s75, 0x100
	s_addc_u32 s78, s78, 0
	s_cmp_ge_i32 s79, s71
	s_mov_b32 s4, s79
	s_barrier
	s_cbranch_scc0 .LBB0_242
	v_sub_co_u32_e64 v138, s[2:3], s74, 1
	s_nop 0
	v_readfirstlane_b32 s64, v138
	s_lshl_b64 s[4:5], s[64:65], 22
	v_readlane_b32 s38, v252, 9
	v_readlane_b32 s39, v252, 10
	s_add_u32 s4, s38, s4
	s_addc_u32 s5, s39, s5
	s_sub_i32 s9, s69, 32
	s_and_b64 s[2:3], s[2:3], exec
	v_readlane_b32 s38, v252, 7
	s_cselect_b32 s2, s69, s9
	v_readlane_b32 s39, v252, 8
	s_cselect_b32 s5, s39, s5
	s_cselect_b32 s4, s38, s4
	s_ashr_i32 s3, s2, 31
	s_lshl_b64 s[2:3], s[2:3], 20
	s_add_u32 s2, s4, s2
	v_mov_b32 v139, v140
	s_addc_u32 s3, s5, s3
	v_ashrrev_i32_e32 v138, 1, v139
	s_lshl_b32 s4, s66, 8
	v_and_b32_e32 v138, -8, v138
	s_or_b32 s4, s4, s59
	v_add_u32_e32 v138, s4, v138
	v_and_or_b32 v144, v139, 15, s58
	v_ashrrev_i32_e32 v139, 31, v138
	v_ashrrev_i32_e32 v145, 31, v144
	v_lshl_add_u64 v[146:147], v[138:139], 1, s[2:3]
	v_lshlrev_b64 v[138:139], 12, v[144:145]
	v_lshl_add_u64 v[138:139], v[146:147], 0, v[138:139]
	v_cvt_pk_bf16_f32 v124, v124, v125
	v_cvt_pk_bf16_f32 v125, v126, v127
	v_cvt_pk_bf16_f32 v126, v120, v121
	v_cvt_pk_bf16_f32 v127, v122, v123
	global_store_dwordx4 v[138:139], v[124:127], off
	v_cvt_pk_bf16_f32 v112, v112, v113
	v_cvt_pk_bf16_f32 v113, v114, v115
	v_cvt_pk_bf16_f32 v114, v104, v105
	v_or_b32_e32 v104, 16, v144
	v_ashrrev_i32_e32 v105, 31, v104
	v_lshlrev_b64 v[104:105], 12, v[104:105]
	v_cvt_pk_bf16_f32 v115, v106, v107
	global_store_dwordx4 v[138:139], v[112:115], off offset:256
	s_mov_b64 s[2:3], 0x80000
	s_mov_b32 s66, s63
	v_lshl_add_u64 v[112:113], v[146:147], 0, v[104:105]
	v_cvt_pk_bf16_f32 v104, v116, v117
	v_cvt_pk_bf16_f32 v105, v118, v119
	v_cvt_pk_bf16_f32 v106, v108, v109
	v_cvt_pk_bf16_f32 v107, v110, v111
	global_store_dwordx4 v[112:113], v[104:107], off
	v_cvt_pk_bf16_f32 v96, v96, v97
	v_cvt_pk_bf16_f32 v97, v98, v99
	v_cvt_pk_bf16_f32 v98, v88, v89
	v_or_b32_e32 v88, 32, v144
	v_ashrrev_i32_e32 v89, 31, v88
	v_lshlrev_b64 v[88:89], 12, v[88:89]
	v_cvt_pk_bf16_f32 v99, v90, v91
	global_store_dwordx4 v[112:113], v[96:99], off offset:256
	s_mov_b32 s69, s34
	s_mov_b32 s74, s35
	v_lshl_add_u64 v[96:97], v[146:147], 0, v[88:89]
	v_cvt_pk_bf16_f32 v88, v100, v101
	v_cvt_pk_bf16_f32 v89, v102, v103
	v_cvt_pk_bf16_f32 v90, v92, v93
	v_cvt_pk_bf16_f32 v91, v94, v95
	global_store_dwordx4 v[96:97], v[88:91], off
	v_cvt_pk_bf16_f32 v80, v80, v81
	v_cvt_pk_bf16_f32 v81, v82, v83
	v_cvt_pk_bf16_f32 v82, v72, v73
	v_or_b32_e32 v72, 48, v144
	v_ashrrev_i32_e32 v73, 31, v72
	v_lshlrev_b64 v[72:73], 12, v[72:73]
	v_cvt_pk_bf16_f32 v83, v74, v75
	global_store_dwordx4 v[96:97], v[80:83], off offset:256
	s_mov_b32 s71, s67
	s_mov_b64 s[4:5], s[36:37]
	v_lshl_add_u64 v[80:81], v[146:147], 0, v[72:73]
	v_cvt_pk_bf16_f32 v72, v84, v85
	v_cvt_pk_bf16_f32 v73, v86, v87
	v_cvt_pk_bf16_f32 v74, v76, v77
	v_cvt_pk_bf16_f32 v75, v78, v79
	global_store_dwordx4 v[80:81], v[72:75], off
	v_cvt_pk_bf16_f32 v68, v68, v69
	v_cvt_pk_bf16_f32 v69, v70, v71
	v_cvt_pk_bf16_f32 v70, v64, v65
	v_lshl_add_u64 v[64:65], v[138:139], 0, s[2:3]
	s_mov_b32 s2, 0x80000
	v_cvt_pk_bf16_f32 v71, v66, v67
	global_store_dwordx4 v[80:81], v[68:71], off offset:256
	v_cvt_pk_bf16_f32 v60, v60, v61
	v_cvt_pk_bf16_f32 v61, v62, v63
	v_cvt_pk_bf16_f32 v62, v56, v57
	v_add_co_u32_e32 v56, vcc, s2, v138
	v_cvt_pk_bf16_f32 v63, v58, v59
	s_mov_b64 s[2:3], 0x90000
	s_nop 0
	v_addc_co_u32_e32 v57, vcc, 0, v139, vcc
	global_store_dwordx4 v[56:57], v[60:63], off
	v_cvt_pk_bf16_f32 v48, v48, v49
	v_cvt_pk_bf16_f32 v49, v50, v51
	v_cvt_pk_bf16_f32 v50, v40, v41
	v_cvt_pk_bf16_f32 v51, v42, v43
	global_store_dwordx4 v[64:65], v[48:51], off offset:256
	v_cvt_pk_bf16_f32 v40, v52, v53
	v_cvt_pk_bf16_f32 v41, v54, v55
	v_cvt_pk_bf16_f32 v42, v44, v45
	v_cvt_pk_bf16_f32 v43, v46, v47
	s_mov_b64 s[78:79], 0x2000
	s_nop 0
	v_lshl_add_u64 v[48:49], v[138:139], 0, s[2:3]
	s_mov_b32 s2, 0x90000
	v_add_co_u32_e32 v44, vcc, s2, v138
	s_mov_b64 s[2:3], 0xa0000
	s_nop 0
	v_addc_co_u32_e32 v45, vcc, 0, v139, vcc
	global_store_dwordx4 v[44:45], v[40:43], off
	v_cvt_pk_bf16_f32 v32, v32, v33
	v_cvt_pk_bf16_f32 v33, v34, v35
	v_cvt_pk_bf16_f32 v34, v24, v25
	v_cvt_pk_bf16_f32 v35, v26, v27
	global_store_dwordx4 v[48:49], v[32:35], off offset:256
	v_cvt_pk_bf16_f32 v24, v36, v37
	v_cvt_pk_bf16_f32 v25, v38, v39
	v_cvt_pk_bf16_f32 v26, v28, v29
	v_cvt_pk_bf16_f32 v27, v30, v31
	s_nop 1
	v_lshl_add_u64 v[32:33], v[138:139], 0, s[2:3]
	s_mov_b32 s2, 0xa0000
	v_add_co_u32_e32 v28, vcc, s2, v138
	s_mov_b64 s[2:3], 0xb0000
	s_nop 0
	v_addc_co_u32_e32 v29, vcc, 0, v139, vcc
	global_store_dwordx4 v[28:29], v[24:27], off
	v_cvt_pk_bf16_f32 v16, v16, v17
	v_cvt_pk_bf16_f32 v17, v18, v19
	v_cvt_pk_bf16_f32 v18, v8, v9
	v_cvt_pk_bf16_f32 v19, v10, v11
	global_store_dwordx4 v[32:33], v[16:19], off offset:256
	v_cvt_pk_bf16_f32 v8, v20, v21
	v_cvt_pk_bf16_f32 v9, v22, v23
	v_cvt_pk_bf16_f32 v10, v12, v13
	v_cvt_pk_bf16_f32 v11, v14, v15
	s_nop 1
	v_lshl_add_u64 v[16:17], v[138:139], 0, s[2:3]
	s_mov_b32 s2, 0xb0000
	v_add_co_u32_e32 v12, vcc, s2, v138
	s_mov_b64 s[2:3], s[28:29]
	s_nop 0
	v_addc_co_u32_e32 v13, vcc, 0, v139, vcc
	s_and_b64 vcc, exec, s[14:15]
	global_store_dwordx4 v[12:13], v[8:11], off
	v_cvt_pk_bf16_f32 v4, v4, v5
	v_cvt_pk_bf16_f32 v5, v6, v7
	v_cvt_pk_bf16_f32 v6, v0, v1
	v_cvt_pk_bf16_f32 v7, v2, v3
	global_store_dwordx4 v[16:17], v[4:7], off offset:256
	s_cbranch_vccz .LBB0_232
	s_waitcnt vmcnt(0)
	s_cmpk_gt_u32 s40, 0xff
	s_cbranch_scc1 .LBB0_246
	s_barrier

.LBB0_252:
	v_and_b32_e32 v140, 63, v0
	v_and_b32_e32 v7, 48, v0
	v_lshlrev_b32_e32 v8, 6, v0
	s_movk_i32 s1, 0x3c0
	v_lshlrev_b32_e32 v0, 2, v0
	s_sext_i32_i16 s67, s0
	s_lshl_b32 s0, s15, 13
	v_and_or_b32 v7, v8, s1, v7
	v_and_b32_e32 v0, 32, v0
	v_bitop3_b32 v8, v7, s0, v0 bitop3:0xde
	s_lshl_b32 s0, s14, 5
	s_and_b32 s64, s0, 0x60
	s_lshl_b32 s0, s64, 7
	v_bitop3_b32 v141, s0, v7, v0 bitop3:0xf6
	v_lshlrev_b32_e32 v0, 15, v5
	v_and_b32_e32 v0, 0xffff0000, v0
	v_lshl_add_u32 v0, v4, 12, v0
	v_and_b32_e32 v4, 1, v5
	v_lshl_or_b32 v0, v4, 6, v0
	v_lshl_add_u32 v134, v6, 1, v0
	v_lshlrev_b32_e32 v0, 15, v1
	v_and_b32_e32 v0, 0xffff0000, v0
	s_waitcnt vmcnt(8)
	s_barrier
	s_waitcnt vmcnt(6)
	v_lshl_add_u32 v0, v2, 12, v0
	v_and_b32_e32 v1, 1, v1
	v_lshl_or_b32 v0, v1, 6, v0
	s_lshl_b32 s63, s15, 6
	v_mov_b32_e32 v135, v193
	v_lshl_add_u32 v136, v3, 1, v0
	v_mov_b32_e32 v137, v193
	s_mov_b32 s66, 0
	v_add_u32_e32 v142, 0, v8
	s_mov_b64 s[36:37], s[4:5]
	s_mov_b64 s[34:35], s[2:3]
	s_barrier

.LBB0_256:
	s_add_u32 s4, s2, 0xfff80080
	s_addc_u32 s5, s3, -1
	s_add_i32 s9, 0, 0x10000
	s_cmp_eq_u32 s69, 28
	s_cselect_b32 s49, s35, s5
	s_cselect_b32 s48, s34, s4
	s_cselect_b32 s5, s37, s29
	s_cselect_b32 s4, s36, s15
	v_lshl_add_u64 v[138:139], s[2:3], 0, v[134:135]
	s_add_i32 m0, s39, 0xc000
	s_nop 0
	global_load_lds_dwordx4 v[138:139], off
	v_lshl_add_u64 v[138:139], s[2:3], 0, v[136:137]
	s_add_i32 m0, s39, 0xe000
	s_nop 0
	global_load_lds_dwordx4 v[138:139], off
	v_add_u32_e32 v138, 0x10000, v141
	ds_read_b128 v[144:147], v138
	ds_read_b128 v[148:151], v138 offset:1024
	ds_read_b128 v[152:155], v138 offset:2048
	ds_read_b128 v[156:159], v138 offset:3072
	ds_read_b128 v[160:163], v142
	ds_read_b128 v[164:167], v142 offset:1024
	ds_read_b128 v[168:171], v142 offset:2048
	ds_read_b128 v[172:175], v142 offset:3072
	ds_read_b128 v[176:179], v142 offset:4096
	ds_read_b128 v[180:183], v142 offset:5120
	ds_read_b128 v[184:187], v142 offset:6144
	ds_read_b128 v[188:191], v142 offset:7168
	v_add_u32_e32 v138, 0x14000, v141
	ds_read_b128 v[194:197], v138
	ds_read_b128 v[198:201], v138 offset:1024
	ds_read_b128 v[202:205], v138 offset:2048
	ds_read_b128 v[206:209], v138 offset:3072
	s_waitcnt vmcnt(8)
	s_waitcnt lgkmcnt(0)
	s_barrier
	s_setprio 1
	v_mfma_f32_16x16x32_bf16 v[124:127], v[144:147], v[160:163], v[124:127]
	v_mfma_f32_16x16x32_bf16 v[120:123], v[152:155], v[160:163], v[120:123]
	v_mfma_f32_16x16x32_bf16 v[108:111], v[144:147], v[168:171], v[108:111]
	v_mfma_f32_16x16x32_bf16 v[104:107], v[152:155], v[168:171], v[104:107]
	v_mfma_f32_16x16x32_bf16 v[92:95], v[144:147], v[176:179], v[92:95]
	v_mfma_f32_16x16x32_bf16 v[88:91], v[152:155], v[176:179], v[88:91]
	v_mfma_f32_16x16x32_bf16 v[76:79], v[144:147], v[184:187], v[76:79]
	v_mfma_f32_16x16x32_bf16 v[72:75], v[152:155], v[184:187], v[72:75]
	v_mfma_f32_16x16x32_bf16 v[124:127], v[148:151], v[164:167], v[124:127]
	v_mfma_f32_16x16x32_bf16 v[120:123], v[156:159], v[164:167], v[120:123]
	v_mfma_f32_16x16x32_bf16 v[108:111], v[148:151], v[172:175], v[108:111]
	v_mfma_f32_16x16x32_bf16 v[104:107], v[156:159], v[172:175], v[104:107]
	v_mfma_f32_16x16x32_bf16 v[92:95], v[148:151], v[180:183], v[92:95]
	v_mfma_f32_16x16x32_bf16 v[88:91], v[156:159], v[180:183], v[88:91]
	v_mfma_f32_16x16x32_bf16 v[76:79], v[148:151], v[188:191], v[76:79]
	v_mfma_f32_16x16x32_bf16 v[72:75], v[156:159], v[188:191], v[72:75]
	v_mfma_f32_16x16x32_bf16 v[116:119], v[194:197], v[160:163], v[116:119]
	v_mfma_f32_16x16x32_bf16 v[112:115], v[202:205], v[160:163], v[112:115]
	v_mfma_f32_16x16x32_bf16 v[100:103], v[194:197], v[168:171], v[100:103]
	v_mfma_f32_16x16x32_bf16 v[96:99], v[202:205], v[168:171], v[96:99]
	v_mfma_f32_16x16x32_bf16 v[84:87], v[194:197], v[176:179], v[84:87]
	v_mfma_f32_16x16x32_bf16 v[80:83], v[202:205], v[176:179], v[80:83]
	v_mfma_f32_16x16x32_bf16 v[68:71], v[194:197], v[184:187], v[68:71]
	v_mfma_f32_16x16x32_bf16 v[64:67], v[202:205], v[184:187], v[64:67]
	v_mfma_f32_16x16x32_bf16 v[116:119], v[198:201], v[164:167], v[116:119]
	v_mfma_f32_16x16x32_bf16 v[112:115], v[206:209], v[164:167], v[112:115]
	v_mfma_f32_16x16x32_bf16 v[100:103], v[198:201], v[172:175], v[100:103]
	v_mfma_f32_16x16x32_bf16 v[96:99], v[206:209], v[172:175], v[96:99]
	v_mfma_f32_16x16x32_bf16 v[84:87], v[198:201], v[180:183], v[84:87]
	v_mfma_f32_16x16x32_bf16 v[80:83], v[206:209], v[180:183], v[80:83]
	v_mfma_f32_16x16x32_bf16 v[68:71], v[198:201], v[188:191], v[68:71]
	v_mfma_f32_16x16x32_bf16 v[64:67], v[206:209], v[188:191], v[64:67]
	s_setprio 0
	s_barrier
	s_add_i32 s71, 0, 0x14000
	s_add_i32 s9, s9, s50
	v_lshl_add_u64 v[138:139], s[4:5], 0, v[192:193]
	s_mov_b32 m0, s9
	v_lshl_add_u64 v[210:211], s[4:5], 0, v[128:129]
	global_load_lds_dwordx4 v[138:139], off
	s_add_i32 m0, s9, 0x2000
	s_nop 0
	global_load_lds_dwordx4 v[210:211], off
	s_mov_b32 m0, s39
	v_lshl_add_u64 v[212:213], s[48:49], 0, v[132:133]
	global_load_lds_dwordx4 v[212:213], off
	v_lshl_add_u64 v[214:215], s[48:49], 0, v[130:131]
	s_mov_b32 m0, s54
	s_nop 0
	global_load_lds_dwordx4 v[214:215], off
	s_add_u32 s46, s4, 0x80000
	s_addc_u32 s47, s5, 0
	s_add_i32 s9, s71, s50
	v_lshl_add_u64 v[160:161], s[46:47], 0, v[192:193]
	s_mov_b32 m0, s9
	s_nop 0
	global_load_lds_dwordx4 v[160:161], off
	v_lshl_add_u64 v[162:163], s[46:47], 0, v[128:129]
	s_add_i32 m0, s9, 0x2000
	s_nop 0
	global_load_lds_dwordx4 v[162:163], off
	ds_read_b128 v[160:163], v142 offset:16384
	ds_read_b128 v[164:167], v142 offset:17408
	ds_read_b128 v[168:171], v142 offset:18432
	ds_read_b128 v[172:175], v142 offset:19456
	ds_read_b128 v[176:179], v142 offset:20480
	ds_read_b128 v[180:183], v142 offset:21504
	ds_read_b128 v[184:187], v142 offset:22528
	ds_read_b128 v[188:191], v142 offset:23552
	s_waitcnt vmcnt(8)
	s_waitcnt lgkmcnt(0)
	s_barrier
	s_setprio 1
	v_mfma_f32_16x16x32_bf16 v[60:63], v[144:147], v[160:163], v[60:63]
	v_mfma_f32_16x16x32_bf16 v[56:59], v[152:155], v[160:163], v[56:59]
	v_mfma_f32_16x16x32_bf16 v[44:47], v[144:147], v[168:171], v[44:47]
	v_mfma_f32_16x16x32_bf16 v[40:43], v[152:155], v[168:171], v[40:43]
	v_mfma_f32_16x16x32_bf16 v[28:31], v[144:147], v[176:179], v[28:31]
	v_mfma_f32_16x16x32_bf16 v[24:27], v[152:155], v[176:179], v[24:27]
	v_mfma_f32_16x16x32_bf16 v[12:15], v[144:147], v[184:187], v[12:15]
	v_mfma_f32_16x16x32_bf16 v[8:11], v[152:155], v[184:187], v[8:11]
	v_mfma_f32_16x16x32_bf16 v[60:63], v[148:151], v[164:167], v[60:63]
	v_mfma_f32_16x16x32_bf16 v[56:59], v[156:159], v[164:167], v[56:59]
	v_mfma_f32_16x16x32_bf16 v[44:47], v[148:151], v[172:175], v[44:47]
	v_mfma_f32_16x16x32_bf16 v[40:43], v[156:159], v[172:175], v[40:43]
	v_mfma_f32_16x16x32_bf16 v[28:31], v[148:151], v[180:183], v[28:31]
	v_mfma_f32_16x16x32_bf16 v[24:27], v[156:159], v[180:183], v[24:27]
	v_mfma_f32_16x16x32_bf16 v[12:15], v[148:151], v[188:191], v[12:15]
	v_mfma_f32_16x16x32_bf16 v[8:11], v[156:159], v[188:191], v[8:11]
	v_mfma_f32_16x16x32_bf16 v[52:55], v[194:197], v[160:163], v[52:55]
	v_mfma_f32_16x16x32_bf16 v[48:51], v[202:205], v[160:163], v[48:51]
	v_mfma_f32_16x16x32_bf16 v[36:39], v[194:197], v[168:171], v[36:39]
	v_mfma_f32_16x16x32_bf16 v[32:35], v[202:205], v[168:171], v[32:35]
	v_mfma_f32_16x16x32_bf16 v[20:23], v[194:197], v[176:179], v[20:23]
	v_mfma_f32_16x16x32_bf16 v[16:19], v[202:205], v[176:179], v[16:19]
	v_mfma_f32_16x16x32_bf16 v[4:7], v[194:197], v[184:187], v[4:7]
	v_mfma_f32_16x16x32_bf16 v[0:3], v[202:205], v[184:187], v[0:3]
	v_mfma_f32_16x16x32_bf16 v[52:55], v[198:201], v[164:167], v[52:55]
	v_mfma_f32_16x16x32_bf16 v[48:51], v[206:209], v[164:167], v[48:51]
	v_mfma_f32_16x16x32_bf16 v[36:39], v[198:201], v[172:175], v[36:39]
	v_mfma_f32_16x16x32_bf16 v[32:35], v[206:209], v[172:175], v[32:35]
	v_mfma_f32_16x16x32_bf16 v[20:23], v[198:201], v[180:183], v[20:23]
	v_mfma_f32_16x16x32_bf16 v[16:19], v[206:209], v[180:183], v[16:19]
	v_mfma_f32_16x16x32_bf16 v[4:7], v[198:201], v[188:191], v[4:7]
	v_mfma_f32_16x16x32_bf16 v[0:3], v[206:209], v[188:191], v[0:3]
	s_setprio 0
	s_barrier
	s_add_i32 s9, 0, 0x18000
	s_add_u32 s46, s48, 0x80000
	s_addc_u32 s47, s49, 0
	s_mov_b32 m0, s55
	v_lshl_add_u64 v[194:195], s[46:47], 0, v[132:133]
	global_load_lds_dwordx4 v[194:195], off
	v_lshl_add_u64 v[194:195], s[46:47], 0, v[130:131]
	s_mov_b32 m0, s58
	s_nop 0
	global_load_lds_dwordx4 v[194:195], off
	v_add_u32_e32 v143, 0x18000, v141
	ds_read_b128 v[144:147], v143
	ds_read_b128 v[148:151], v143 offset:1024
	ds_read_b128 v[152:155], v143 offset:2048
	ds_read_b128 v[156:159], v143 offset:3072
	ds_read_b128 v[160:163], v142 offset:32768
	ds_read_b128 v[164:167], v142 offset:33792
	ds_read_b128 v[168:171], v142 offset:34816
	ds_read_b128 v[172:175], v142 offset:35840
	ds_read_b128 v[176:179], v142 offset:36864
	ds_read_b128 v[180:183], v142 offset:37888
	ds_read_b128 v[184:187], v142 offset:38912
	ds_read_b128 v[188:191], v142 offset:39936
	v_add_u32_e32 v143, 0x1c000, v141
	ds_read_b128 v[194:197], v143
	ds_read_b128 v[198:201], v143 offset:1024
	ds_read_b128 v[202:205], v143 offset:2048
	ds_read_b128 v[206:209], v143 offset:3072
	s_waitcnt vmcnt(8)
	s_waitcnt lgkmcnt(0)
	s_barrier
	s_setprio 1
	v_mfma_f32_16x16x32_bf16 v[124:127], v[144:147], v[160:163], v[124:127]
	v_mfma_f32_16x16x32_bf16 v[120:123], v[152:155], v[160:163], v[120:123]
	v_mfma_f32_16x16x32_bf16 v[108:111], v[144:147], v[168:171], v[108:111]
	v_mfma_f32_16x16x32_bf16 v[104:107], v[152:155], v[168:171], v[104:107]
	v_mfma_f32_16x16x32_bf16 v[92:95], v[144:147], v[176:179], v[92:95]
	v_mfma_f32_16x16x32_bf16 v[88:91], v[152:155], v[176:179], v[88:91]
	v_mfma_f32_16x16x32_bf16 v[76:79], v[144:147], v[184:187], v[76:79]
	v_mfma_f32_16x16x32_bf16 v[72:75], v[152:155], v[184:187], v[72:75]
	v_mfma_f32_16x16x32_bf16 v[124:127], v[148:151], v[164:167], v[124:127]
	v_mfma_f32_16x16x32_bf16 v[120:123], v[156:159], v[164:167], v[120:123]
	v_mfma_f32_16x16x32_bf16 v[108:111], v[148:151], v[172:175], v[108:111]
	v_mfma_f32_16x16x32_bf16 v[104:107], v[156:159], v[172:175], v[104:107]
	v_mfma_f32_16x16x32_bf16 v[92:95], v[148:151], v[180:183], v[92:95]
	v_mfma_f32_16x16x32_bf16 v[88:91], v[156:159], v[180:183], v[88:91]
	v_mfma_f32_16x16x32_bf16 v[76:79], v[148:151], v[188:191], v[76:79]
	v_mfma_f32_16x16x32_bf16 v[72:75], v[156:159], v[188:191], v[72:75]
	v_mfma_f32_16x16x32_bf16 v[116:119], v[194:197], v[160:163], v[116:119]
	v_mfma_f32_16x16x32_bf16 v[112:115], v[202:205], v[160:163], v[112:115]
	v_mfma_f32_16x16x32_bf16 v[100:103], v[194:197], v[168:171], v[100:103]
	v_mfma_f32_16x16x32_bf16 v[96:99], v[202:205], v[168:171], v[96:99]
	v_mfma_f32_16x16x32_bf16 v[84:87], v[194:197], v[176:179], v[84:87]
	v_mfma_f32_16x16x32_bf16 v[80:83], v[202:205], v[176:179], v[80:83]
	v_mfma_f32_16x16x32_bf16 v[68:71], v[194:197], v[184:187], v[68:71]
	v_mfma_f32_16x16x32_bf16 v[64:67], v[202:205], v[184:187], v[64:67]
	v_mfma_f32_16x16x32_bf16 v[116:119], v[198:201], v[164:167], v[116:119]
	v_mfma_f32_16x16x32_bf16 v[112:115], v[206:209], v[164:167], v[112:115]
	v_mfma_f32_16x16x32_bf16 v[100:103], v[198:201], v[172:175], v[100:103]
	v_mfma_f32_16x16x32_bf16 v[96:99], v[206:209], v[172:175], v[96:99]
	v_mfma_f32_16x16x32_bf16 v[84:87], v[198:201], v[180:183], v[84:87]
	v_mfma_f32_16x16x32_bf16 v[80:83], v[206:209], v[180:183], v[80:83]
	v_mfma_f32_16x16x32_bf16 v[68:71], v[198:201], v[188:191], v[68:71]
	v_mfma_f32_16x16x32_bf16 v[64:67], v[206:209], v[188:191], v[64:67]
	s_setprio 0
	s_barrier
	s_add_i32 s46, 0, 0x1c000
	s_add_i32 s9, s9, s50
	v_lshl_add_u64 v[138:139], v[138:139], 0, s[72:73]
	s_mov_b32 m0, s9
	s_nop 0
	global_load_lds_dwordx4 v[138:139], off
	v_lshl_add_u64 v[138:139], v[210:211], 0, s[72:73]
	s_add_i32 m0, s9, 0x2000
	s_nop 0
	global_load_lds_dwordx4 v[138:139], off
	s_mov_b32 m0, s59
	v_lshl_add_u64 v[138:139], v[212:213], 0, s[72:73]
	global_load_lds_dwordx4 v[138:139], off
	v_lshl_add_u64 v[138:139], v[214:215], 0, s[72:73]
	s_mov_b32 m0, s62
	s_nop 0
	global_load_lds_dwordx4 v[138:139], off
	s_add_u32 s4, s4, 0x80080
	s_addc_u32 s5, s5, 0
	s_add_i32 s9, s46, s50
	v_lshl_add_u64 v[138:139], s[4:5], 0, v[192:193]
	s_mov_b32 m0, s9
	s_nop 0
	global_load_lds_dwordx4 v[138:139], off
	v_lshl_add_u64 v[138:139], s[4:5], 0, v[128:129]
	s_add_i32 m0, s9, 0x2000
	s_nop 0
	global_load_lds_dwordx4 v[138:139], off
	ds_read_b128 v[160:163], v142 offset:49152
	ds_read_b128 v[164:167], v142 offset:50176
	ds_read_b128 v[168:171], v142 offset:51200
	ds_read_b128 v[172:175], v142 offset:52224
	ds_read_b128 v[176:179], v142 offset:53248
	ds_read_b128 v[180:183], v142 offset:54272
	ds_read_b128 v[184:187], v142 offset:55296
	ds_read_b128 v[188:191], v142 offset:56320
	s_waitcnt vmcnt(8)
	s_waitcnt lgkmcnt(0)
	s_barrier
	s_setprio 1
	v_mfma_f32_16x16x32_bf16 v[60:63], v[144:147], v[160:163], v[60:63]
	v_mfma_f32_16x16x32_bf16 v[56:59], v[152:155], v[160:163], v[56:59]
	v_mfma_f32_16x16x32_bf16 v[44:47], v[144:147], v[168:171], v[44:47]
	v_mfma_f32_16x16x32_bf16 v[40:43], v[152:155], v[168:171], v[40:43]
	v_mfma_f32_16x16x32_bf16 v[28:31], v[144:147], v[176:179], v[28:31]
	v_mfma_f32_16x16x32_bf16 v[24:27], v[152:155], v[176:179], v[24:27]
	v_mfma_f32_16x16x32_bf16 v[12:15], v[144:147], v[184:187], v[12:15]
	v_mfma_f32_16x16x32_bf16 v[8:11], v[152:155], v[184:187], v[8:11]
	v_mfma_f32_16x16x32_bf16 v[60:63], v[148:151], v[164:167], v[60:63]
	v_mfma_f32_16x16x32_bf16 v[56:59], v[156:159], v[164:167], v[56:59]
	v_mfma_f32_16x16x32_bf16 v[44:47], v[148:151], v[172:175], v[44:47]
	v_mfma_f32_16x16x32_bf16 v[40:43], v[156:159], v[172:175], v[40:43]
	v_mfma_f32_16x16x32_bf16 v[28:31], v[148:151], v[180:183], v[28:31]
	v_mfma_f32_16x16x32_bf16 v[24:27], v[156:159], v[180:183], v[24:27]
	v_mfma_f32_16x16x32_bf16 v[12:15], v[148:151], v[188:191], v[12:15]
	v_mfma_f32_16x16x32_bf16 v[8:11], v[156:159], v[188:191], v[8:11]
	v_mfma_f32_16x16x32_bf16 v[52:55], v[194:197], v[160:163], v[52:55]
	v_mfma_f32_16x16x32_bf16 v[48:51], v[202:205], v[160:163], v[48:51]
	v_mfma_f32_16x16x32_bf16 v[36:39], v[194:197], v[168:171], v[36:39]
	v_mfma_f32_16x16x32_bf16 v[32:35], v[202:205], v[168:171], v[32:35]
	v_mfma_f32_16x16x32_bf16 v[20:23], v[194:197], v[176:179], v[20:23]
	v_mfma_f32_16x16x32_bf16 v[16:19], v[202:205], v[176:179], v[16:19]
	v_mfma_f32_16x16x32_bf16 v[4:7], v[194:197], v[184:187], v[4:7]
	v_mfma_f32_16x16x32_bf16 v[0:3], v[202:205], v[184:187], v[0:3]
	v_mfma_f32_16x16x32_bf16 v[52:55], v[198:201], v[164:167], v[52:55]
	v_mfma_f32_16x16x32_bf16 v[48:51], v[206:209], v[164:167], v[48:51]
	v_mfma_f32_16x16x32_bf16 v[36:39], v[198:201], v[172:175], v[36:39]
	v_mfma_f32_16x16x32_bf16 v[32:35], v[206:209], v[172:175], v[32:35]
	v_mfma_f32_16x16x32_bf16 v[20:23], v[198:201], v[180:183], v[20:23]
	v_mfma_f32_16x16x32_bf16 v[16:19], v[206:209], v[180:183], v[16:19]
	v_mfma_f32_16x16x32_bf16 v[4:7], v[198:201], v[188:191], v[4:7]
	v_mfma_f32_16x16x32_bf16 v[0:3], v[206:209], v[188:191], v[0:3]
	s_setprio 0
	s_add_i32 s69, s69, 2
	s_add_u32 s2, s2, 0x100
	s_addc_u32 s3, s3, 0
	s_add_u32 s15, s15, 0x100
	s_addc_u32 s29, s29, 0
	s_cmp_gt_u32 s69, 29
	s_barrier
	s_cbranch_scc0 .LBB0_256
	s_lshl_b32 s2, s38, 8
	v_mov_b32 v138, v140
	s_add_i32 s2, s2, s63
	v_and_or_b32 v144, v138, 15, s2
	s_lshl_b32 s2, s67, 8
	v_ashrrev_i32_e32 v138, 1, v138
	v_max_f32_e32 v120, v120, v120
	s_or_b32 s2, s2, s64
	v_and_b32_e32 v138, -8, v138
	v_max_f32_e32 v120, 0, v120
	v_max_f32_e32 v121, v121, v121
	v_max_f32_e32 v122, v122, v122
	v_add_u32_e32 v138, s2, v138
	v_ashrrev_i32_e32 v145, 31, v144
	v_readlane_b32 s2, v252, 63
	v_mul_f32_e32 v143, v120, v120
	v_max_f32_e32 v120, v125, v125
	v_max_f32_e32 v121, 0, v121
	v_max_f32_e32 v122, 0, v122
	v_ashrrev_i32_e32 v139, 31, v138
	v_lshlrev_b64 v[146:147], 14, v[144:145]
	v_readlane_b32 s3, v253, 0
	v_max_f32_e32 v124, v124, v124
	v_max_f32_e32 v120, 0, v120
	v_mul_f32_e32 v125, v121, v121
	v_max_f32_e32 v121, v126, v126
	v_mul_f32_e32 v126, v122, v122
	v_max_f32_e32 v122, v127, v127
	v_max_f32_e32 v123, v123, v123
	v_lshl_add_u64 v[146:147], s[2:3], 0, v[146:147]
	v_lshlrev_b64 v[148:149], 1, v[138:139]
	v_max_f32_e32 v124, 0, v124
	v_mul_f32_e32 v120, v120, v120
	v_max_f32_e32 v121, 0, v121
	v_max_f32_e32 v122, 0, v122
	v_max_f32_e32 v123, 0, v123
	v_max_f32_e32 v112, v112, v112
	v_lshl_add_u64 v[138:139], v[146:147], 0, v[148:149]
	v_mul_f32_e32 v124, v124, v124
	v_mul_f32_e32 v121, v121, v121
	v_mul_f32_e32 v122, v122, v122
	v_mul_f32_e32 v123, v123, v123
	v_cvt_pk_bf16_f32 v120, v124, v120
	v_max_f32_e32 v112, 0, v112
	v_max_f32_e32 v113, v113, v113
	v_max_f32_e32 v114, v114, v114
	v_cvt_pk_bf16_f32 v121, v121, v122
	v_cvt_pk_bf16_f32 v122, v143, v125
	v_cvt_pk_bf16_f32 v123, v126, v123
	global_store_dwordx4 v[138:139], v[120:123], off
	v_max_f32_e32 v113, 0, v113
	v_max_f32_e32 v114, 0, v114
	v_mul_f32_e32 v120, v112, v112
	v_max_f32_e32 v112, v117, v117
	v_max_f32_e32 v116, v116, v116
	v_max_f32_e32 v112, 0, v112
	v_mul_f32_e32 v117, v113, v113
	v_max_f32_e32 v113, v118, v118
	v_mul_f32_e32 v118, v114, v114
	v_max_f32_e32 v114, v119, v119
	v_max_f32_e32 v115, v115, v115
	v_max_f32_e32 v116, 0, v116
	v_mul_f32_e32 v112, v112, v112
	v_max_f32_e32 v113, 0, v113
	v_max_f32_e32 v114, 0, v114
	v_max_f32_e32 v115, 0, v115
	v_mul_f32_e32 v116, v116, v116
	v_mul_f32_e32 v113, v113, v113
	v_mul_f32_e32 v114, v114, v114
	v_mul_f32_e32 v115, v115, v115
	v_cvt_pk_bf16_f32 v112, v116, v112
	v_max_f32_e32 v104, v104, v104
	v_cvt_pk_bf16_f32 v113, v113, v114
	v_cvt_pk_bf16_f32 v114, v120, v117
	v_cvt_pk_bf16_f32 v115, v118, v115
	global_store_dwordx4 v[138:139], v[112:115], off offset:256
	v_max_f32_e32 v104, 0, v104
	v_max_f32_e32 v105, v105, v105
	v_or_b32_e32 v112, 16, v144
	v_max_f32_e32 v106, v106, v106
	v_ashrrev_i32_e32 v113, 31, v112
	v_mul_f32_e32 v114, v104, v104
	v_max_f32_e32 v104, v109, v109
	v_max_f32_e32 v105, 0, v105
	v_max_f32_e32 v106, 0, v106
	v_lshlrev_b64 v[112:113], 14, v[112:113]
	v_max_f32_e32 v108, v108, v108
	v_max_f32_e32 v104, 0, v104
	v_mul_f32_e32 v109, v105, v105
	v_max_f32_e32 v105, v110, v110
	v_mul_f32_e32 v110, v106, v106
	v_max_f32_e32 v106, v111, v111
	v_max_f32_e32 v107, v107, v107
	v_lshl_add_u64 v[112:113], s[2:3], 0, v[112:113]
	v_max_f32_e32 v108, 0, v108
	v_mul_f32_e32 v104, v104, v104
	v_max_f32_e32 v105, 0, v105
	v_max_f32_e32 v106, 0, v106
	v_max_f32_e32 v107, 0, v107
	v_max_f32_e32 v96, v96, v96
	v_lshl_add_u64 v[112:113], v[112:113], 0, v[148:149]
	v_mul_f32_e32 v108, v108, v108
	v_mul_f32_e32 v105, v105, v105
	v_mul_f32_e32 v106, v106, v106
	v_mul_f32_e32 v107, v107, v107
	v_cvt_pk_bf16_f32 v104, v108, v104
	v_max_f32_e32 v96, 0, v96
	v_max_f32_e32 v97, v97, v97
	v_max_f32_e32 v98, v98, v98
	v_cvt_pk_bf16_f32 v105, v105, v106
	v_cvt_pk_bf16_f32 v106, v114, v109
	v_cvt_pk_bf16_f32 v107, v110, v107
	global_store_dwordx4 v[112:113], v[104:107], off
	v_max_f32_e32 v97, 0, v97
	v_max_f32_e32 v98, 0, v98
	v_mul_f32_e32 v104, v96, v96
	v_max_f32_e32 v96, v101, v101
	v_max_f32_e32 v100, v100, v100
	v_max_f32_e32 v96, 0, v96
	v_mul_f32_e32 v101, v97, v97
	v_max_f32_e32 v97, v102, v102
	v_mul_f32_e32 v102, v98, v98
	v_max_f32_e32 v98, v103, v103
	v_max_f32_e32 v99, v99, v99
	v_max_f32_e32 v100, 0, v100
	v_mul_f32_e32 v96, v96, v96
	v_max_f32_e32 v97, 0, v97
	v_max_f32_e32 v98, 0, v98
	v_max_f32_e32 v99, 0, v99
	v_mul_f32_e32 v100, v100, v100
	v_mul_f32_e32 v97, v97, v97
	v_mul_f32_e32 v98, v98, v98
	v_mul_f32_e32 v99, v99, v99
	v_cvt_pk_bf16_f32 v96, v100, v96
	v_max_f32_e32 v88, v88, v88
	v_cvt_pk_bf16_f32 v97, v97, v98
	v_cvt_pk_bf16_f32 v98, v104, v101
	v_cvt_pk_bf16_f32 v99, v102, v99
	global_store_dwordx4 v[112:113], v[96:99], off offset:256
	v_max_f32_e32 v88, 0, v88
	v_max_f32_e32 v89, v89, v89
	v_or_b32_e32 v96, 32, v144
	v_max_f32_e32 v90, v90, v90
	v_ashrrev_i32_e32 v97, 31, v96
	v_mul_f32_e32 v98, v88, v88
	v_max_f32_e32 v88, v93, v93
	v_max_f32_e32 v89, 0, v89
	v_max_f32_e32 v90, 0, v90
	v_lshlrev_b64 v[96:97], 14, v[96:97]
	v_max_f32_e32 v92, v92, v92
	v_max_f32_e32 v88, 0, v88
	v_mul_f32_e32 v93, v89, v89
	v_max_f32_e32 v89, v94, v94
	v_mul_f32_e32 v94, v90, v90
	v_max_f32_e32 v90, v95, v95
	v_max_f32_e32 v91, v91, v91
	v_lshl_add_u64 v[96:97], s[2:3], 0, v[96:97]
	v_max_f32_e32 v92, 0, v92
	v_mul_f32_e32 v88, v88, v88
	v_max_f32_e32 v89, 0, v89
	v_max_f32_e32 v90, 0, v90
	v_max_f32_e32 v91, 0, v91
	v_max_f32_e32 v80, v80, v80
	v_lshl_add_u64 v[96:97], v[96:97], 0, v[148:149]
	v_mul_f32_e32 v92, v92, v92
	v_mul_f32_e32 v89, v89, v89
	v_mul_f32_e32 v90, v90, v90
	v_mul_f32_e32 v91, v91, v91
	v_cvt_pk_bf16_f32 v88, v92, v88
	v_max_f32_e32 v80, 0, v80
	v_max_f32_e32 v81, v81, v81
	v_max_f32_e32 v82, v82, v82
	v_cvt_pk_bf16_f32 v89, v89, v90
	v_cvt_pk_bf16_f32 v90, v98, v93
	v_cvt_pk_bf16_f32 v91, v94, v91
	global_store_dwordx4 v[96:97], v[88:91], off
	v_max_f32_e32 v81, 0, v81
	v_max_f32_e32 v82, 0, v82
	v_mul_f32_e32 v88, v80, v80
	v_max_f32_e32 v80, v85, v85
	v_max_f32_e32 v84, v84, v84
	v_max_f32_e32 v80, 0, v80
	v_mul_f32_e32 v85, v81, v81
	v_max_f32_e32 v81, v86, v86
	v_mul_f32_e32 v86, v82, v82
	v_max_f32_e32 v82, v87, v87
	v_max_f32_e32 v83, v83, v83
	v_max_f32_e32 v84, 0, v84
	v_mul_f32_e32 v80, v80, v80
	v_max_f32_e32 v81, 0, v81
	v_max_f32_e32 v82, 0, v82
	v_max_f32_e32 v83, 0, v83
	v_mul_f32_e32 v84, v84, v84
	v_mul_f32_e32 v81, v81, v81
	v_mul_f32_e32 v82, v82, v82
	v_mul_f32_e32 v83, v83, v83
	v_cvt_pk_bf16_f32 v80, v84, v80
	v_max_f32_e32 v72, v72, v72
	v_cvt_pk_bf16_f32 v81, v81, v82
	v_cvt_pk_bf16_f32 v82, v88, v85
	v_cvt_pk_bf16_f32 v83, v86, v83
	global_store_dwordx4 v[96:97], v[80:83], off offset:256
	v_max_f32_e32 v72, 0, v72
	v_max_f32_e32 v73, v73, v73
	v_or_b32_e32 v80, 48, v144
	v_max_f32_e32 v74, v74, v74
	v_ashrrev_i32_e32 v81, 31, v80
	v_mul_f32_e32 v82, v72, v72
	v_max_f32_e32 v72, v77, v77
	v_max_f32_e32 v73, 0, v73
	v_max_f32_e32 v74, 0, v74
	v_lshlrev_b64 v[80:81], 14, v[80:81]
	v_max_f32_e32 v76, v76, v76
	v_max_f32_e32 v72, 0, v72
	v_mul_f32_e32 v77, v73, v73
	v_max_f32_e32 v73, v78, v78
	v_mul_f32_e32 v78, v74, v74
	v_max_f32_e32 v74, v79, v79
	v_max_f32_e32 v75, v75, v75
	v_lshl_add_u64 v[80:81], s[2:3], 0, v[80:81]
	v_max_f32_e32 v76, 0, v76
	v_mul_f32_e32 v72, v72, v72
	v_max_f32_e32 v73, 0, v73
	v_max_f32_e32 v74, 0, v74
	v_max_f32_e32 v75, 0, v75
	v_max_f32_e32 v64, v64, v64
	v_max_f32_e32 v65, v65, v65
	v_max_f32_e32 v66, v66, v66
	v_lshl_add_u64 v[80:81], v[80:81], 0, v[148:149]
	v_mul_f32_e32 v76, v76, v76
	v_mul_f32_e32 v73, v73, v73
	v_mul_f32_e32 v74, v74, v74
	v_mul_f32_e32 v75, v75, v75
	v_cvt_pk_bf16_f32 v72, v76, v72
	v_max_f32_e32 v64, 0, v64
	v_max_f32_e32 v65, 0, v65
	v_max_f32_e32 v66, 0, v66
	v_cvt_pk_bf16_f32 v73, v73, v74
	v_cvt_pk_bf16_f32 v74, v82, v77
	v_cvt_pk_bf16_f32 v75, v78, v75
	global_store_dwordx4 v[80:81], v[72:75], off
	v_max_f32_e32 v68, v68, v68
	v_max_f32_e32 v67, v67, v67
	v_mul_f32_e32 v72, v64, v64
	v_max_f32_e32 v64, v69, v69
	v_mul_f32_e32 v69, v65, v65
	v_max_f32_e32 v65, v70, v70
	v_mul_f32_e32 v70, v66, v66
	v_max_f32_e32 v66, v71, v71
	v_max_f32_e32 v64, 0, v64
	v_max_f32_e32 v65, 0, v65
	v_max_f32_e32 v66, 0, v66
	v_max_f32_e32 v68, 0, v68
	v_mul_f32_e32 v64, v64, v64
	v_mul_f32_e32 v65, v65, v65
	v_max_f32_e32 v67, 0, v67
	v_mul_f32_e32 v66, v66, v66
	v_max_f32_e32 v56, v56, v56
	v_mul_f32_e32 v68, v68, v68
	v_mul_f32_e32 v67, v67, v67
	v_cvt_pk_bf16_f32 v64, v68, v64
	v_cvt_pk_bf16_f32 v65, v65, v66
	v_cvt_pk_bf16_f32 v66, v72, v69
	v_max_f32_e32 v56, 0, v56
	v_max_f32_e32 v57, v57, v57
	v_max_f32_e32 v58, v58, v58
	v_cvt_pk_bf16_f32 v67, v70, v67
	global_store_dwordx4 v[80:81], v[64:67], off offset:256
	v_max_f32_e32 v60, v60, v60
	v_max_f32_e32 v57, 0, v57
	v_mul_f32_e32 v66, v56, v56
	v_max_f32_e32 v56, v61, v61
	v_max_f32_e32 v58, 0, v58
	s_mov_b64 s[2:3], 0x200000
	v_max_f32_e32 v60, 0, v60
	v_max_f32_e32 v56, 0, v56
	v_mul_f32_e32 v61, v57, v57
	v_max_f32_e32 v57, v62, v62
	v_mul_f32_e32 v62, v58, v58
	v_max_f32_e32 v58, v63, v63
	v_lshl_add_u64 v[64:65], v[138:139], 0, s[2:3]
	v_mul_f32_e32 v60, v60, v60
	v_mul_f32_e32 v56, v56, v56
	v_max_f32_e32 v57, 0, v57
	v_max_f32_e32 v58, 0, v58
	v_max_f32_e32 v59, v59, v59
	s_mov_b32 s2, 0x200000
	v_mul_f32_e32 v57, v57, v57
	v_max_f32_e32 v59, 0, v59
	v_mul_f32_e32 v58, v58, v58
	v_cvt_pk_bf16_f32 v56, v60, v56
	v_add_co_u32_e32 v60, vcc, s2, v138
	v_max_f32_e32 v48, v48, v48
	v_max_f32_e32 v49, v49, v49
	v_max_f32_e32 v50, v50, v50
	v_mul_f32_e32 v59, v59, v59
	v_cvt_pk_bf16_f32 v57, v57, v58
	v_cvt_pk_bf16_f32 v58, v66, v61
	v_addc_co_u32_e32 v61, vcc, 0, v139, vcc
	v_max_f32_e32 v48, 0, v48
	v_max_f32_e32 v49, 0, v49
	v_max_f32_e32 v50, 0, v50
	v_cvt_pk_bf16_f32 v59, v62, v59
	global_store_dwordx4 v[60:61], v[56:59], off
	v_max_f32_e32 v52, v52, v52
	v_max_f32_e32 v51, v51, v51
	v_mul_f32_e32 v56, v48, v48
	v_max_f32_e32 v48, v53, v53
	v_mul_f32_e32 v53, v49, v49
	v_max_f32_e32 v49, v54, v54
	v_mul_f32_e32 v54, v50, v50
	v_max_f32_e32 v50, v55, v55
	v_max_f32_e32 v48, 0, v48
	v_max_f32_e32 v49, 0, v49
	v_max_f32_e32 v50, 0, v50
	v_max_f32_e32 v52, 0, v52
	v_mul_f32_e32 v48, v48, v48
	v_mul_f32_e32 v49, v49, v49
	v_max_f32_e32 v51, 0, v51
	v_mul_f32_e32 v50, v50, v50
	v_max_f32_e32 v40, v40, v40
	v_mul_f32_e32 v52, v52, v52
	v_mul_f32_e32 v51, v51, v51
	v_cvt_pk_bf16_f32 v48, v52, v48
	v_cvt_pk_bf16_f32 v49, v49, v50
	v_cvt_pk_bf16_f32 v50, v56, v53
	v_max_f32_e32 v40, 0, v40
	v_max_f32_e32 v41, v41, v41
	v_max_f32_e32 v42, v42, v42
	v_cvt_pk_bf16_f32 v51, v54, v51
	global_store_dwordx4 v[64:65], v[48:51], off offset:256
	v_max_f32_e32 v44, v44, v44
	v_max_f32_e32 v41, 0, v41
	v_mul_f32_e32 v50, v40, v40
	v_max_f32_e32 v40, v45, v45
	v_max_f32_e32 v42, 0, v42
	s_mov_b64 s[2:3], 0x240000
	v_max_f32_e32 v44, 0, v44
	v_max_f32_e32 v40, 0, v40
	v_mul_f32_e32 v45, v41, v41
	v_max_f32_e32 v41, v46, v46
	v_mul_f32_e32 v46, v42, v42
	v_max_f32_e32 v42, v47, v47
	v_lshl_add_u64 v[48:49], v[138:139], 0, s[2:3]
	v_mul_f32_e32 v44, v44, v44
	v_mul_f32_e32 v40, v40, v40
	v_max_f32_e32 v41, 0, v41
	v_max_f32_e32 v42, 0, v42
	v_max_f32_e32 v43, v43, v43
	s_mov_b32 s2, 0x240000
	v_mul_f32_e32 v41, v41, v41
	v_max_f32_e32 v43, 0, v43
	v_mul_f32_e32 v42, v42, v42
	v_cvt_pk_bf16_f32 v40, v44, v40
	v_add_co_u32_e32 v44, vcc, s2, v138
	v_max_f32_e32 v32, v32, v32
	v_max_f32_e32 v33, v33, v33
	v_max_f32_e32 v34, v34, v34
	v_mul_f32_e32 v43, v43, v43
	v_cvt_pk_bf16_f32 v41, v41, v42
	v_cvt_pk_bf16_f32 v42, v50, v45
	v_addc_co_u32_e32 v45, vcc, 0, v139, vcc
	v_max_f32_e32 v32, 0, v32
	v_max_f32_e32 v33, 0, v33
	v_max_f32_e32 v34, 0, v34
	v_cvt_pk_bf16_f32 v43, v46, v43
	global_store_dwordx4 v[44:45], v[40:43], off
	v_max_f32_e32 v36, v36, v36
	v_max_f32_e32 v35, v35, v35
	v_mul_f32_e32 v40, v32, v32
	v_max_f32_e32 v32, v37, v37
	v_mul_f32_e32 v37, v33, v33
	v_max_f32_e32 v33, v38, v38
	v_mul_f32_e32 v38, v34, v34
	v_max_f32_e32 v34, v39, v39
	v_max_f32_e32 v32, 0, v32
	v_max_f32_e32 v33, 0, v33
	v_max_f32_e32 v34, 0, v34
	v_max_f32_e32 v36, 0, v36
	v_mul_f32_e32 v32, v32, v32
	v_mul_f32_e32 v33, v33, v33
	v_max_f32_e32 v35, 0, v35
	v_mul_f32_e32 v34, v34, v34
	v_max_f32_e32 v24, v24, v24
	v_mul_f32_e32 v36, v36, v36
	v_mul_f32_e32 v35, v35, v35
	v_cvt_pk_bf16_f32 v32, v36, v32
	v_cvt_pk_bf16_f32 v33, v33, v34
	v_cvt_pk_bf16_f32 v34, v40, v37
	v_max_f32_e32 v24, 0, v24
	v_max_f32_e32 v25, v25, v25
	v_max_f32_e32 v26, v26, v26
	v_cvt_pk_bf16_f32 v35, v38, v35
	global_store_dwordx4 v[48:49], v[32:35], off offset:256
	v_max_f32_e32 v28, v28, v28
	v_max_f32_e32 v25, 0, v25
	v_mul_f32_e32 v34, v24, v24
	v_max_f32_e32 v24, v29, v29
	v_max_f32_e32 v26, 0, v26
	s_mov_b64 s[2:3], 0x280000
	v_max_f32_e32 v28, 0, v28
	v_max_f32_e32 v24, 0, v24
	v_mul_f32_e32 v29, v25, v25
	v_max_f32_e32 v25, v30, v30
	v_mul_f32_e32 v30, v26, v26
	v_max_f32_e32 v26, v31, v31
	v_lshl_add_u64 v[32:33], v[138:139], 0, s[2:3]
	v_mul_f32_e32 v28, v28, v28
	v_mul_f32_e32 v24, v24, v24
	v_max_f32_e32 v25, 0, v25
	v_max_f32_e32 v26, 0, v26
	v_max_f32_e32 v27, v27, v27
	s_mov_b32 s2, 0x280000
	v_mul_f32_e32 v25, v25, v25
	v_max_f32_e32 v27, 0, v27
	v_mul_f32_e32 v26, v26, v26
	v_cvt_pk_bf16_f32 v24, v28, v24
	v_add_co_u32_e32 v28, vcc, s2, v138
	v_max_f32_e32 v16, v16, v16
	v_max_f32_e32 v17, v17, v17
	v_max_f32_e32 v18, v18, v18
	v_mul_f32_e32 v27, v27, v27
	v_cvt_pk_bf16_f32 v25, v25, v26
	v_cvt_pk_bf16_f32 v26, v34, v29
	v_addc_co_u32_e32 v29, vcc, 0, v139, vcc
	v_max_f32_e32 v16, 0, v16
	v_max_f32_e32 v17, 0, v17
	v_max_f32_e32 v18, 0, v18
	v_cvt_pk_bf16_f32 v27, v30, v27
	global_store_dwordx4 v[28:29], v[24:27], off
	v_max_f32_e32 v20, v20, v20
	v_max_f32_e32 v19, v19, v19
	v_mul_f32_e32 v24, v16, v16
	v_max_f32_e32 v16, v21, v21
	v_mul_f32_e32 v21, v17, v17
	v_max_f32_e32 v17, v22, v22
	v_mul_f32_e32 v22, v18, v18
	v_max_f32_e32 v18, v23, v23
	v_max_f32_e32 v16, 0, v16
	v_max_f32_e32 v17, 0, v17
	v_max_f32_e32 v18, 0, v18
	v_max_f32_e32 v20, 0, v20
	v_mul_f32_e32 v16, v16, v16
	v_mul_f32_e32 v17, v17, v17
	v_max_f32_e32 v19, 0, v19
	v_mul_f32_e32 v18, v18, v18
	v_max_f32_e32 v8, v8, v8
	v_mul_f32_e32 v20, v20, v20
	v_mul_f32_e32 v19, v19, v19
	v_cvt_pk_bf16_f32 v16, v20, v16
	v_cvt_pk_bf16_f32 v17, v17, v18
	v_cvt_pk_bf16_f32 v18, v24, v21
	v_max_f32_e32 v8, 0, v8
	v_max_f32_e32 v9, v9, v9
	v_max_f32_e32 v10, v10, v10
	v_cvt_pk_bf16_f32 v19, v22, v19
	global_store_dwordx4 v[32:33], v[16:19], off offset:256
	v_max_f32_e32 v12, v12, v12
	v_max_f32_e32 v9, 0, v9
	v_mul_f32_e32 v18, v8, v8
	v_max_f32_e32 v8, v13, v13
	v_max_f32_e32 v10, 0, v10
	s_mov_b64 s[2:3], 0x2c0000
	v_max_f32_e32 v12, 0, v12
	v_max_f32_e32 v8, 0, v8
	v_mul_f32_e32 v13, v9, v9
	v_max_f32_e32 v9, v14, v14
	v_mul_f32_e32 v14, v10, v10
	v_max_f32_e32 v10, v15, v15
	v_lshl_add_u64 v[16:17], v[138:139], 0, s[2:3]
	v_mul_f32_e32 v12, v12, v12
	v_mul_f32_e32 v8, v8, v8
	v_max_f32_e32 v9, 0, v9
	v_max_f32_e32 v10, 0, v10
	v_max_f32_e32 v11, v11, v11
	s_mov_b32 s2, 0x2c0000
	v_mul_f32_e32 v9, v9, v9
	v_max_f32_e32 v11, 0, v11
	v_mul_f32_e32 v10, v10, v10
	v_cvt_pk_bf16_f32 v8, v12, v8
	v_add_co_u32_e32 v12, vcc, s2, v138
	v_max_f32_e32 v0, v0, v0
	v_max_f32_e32 v1, v1, v1
	v_max_f32_e32 v2, v2, v2
	v_mul_f32_e32 v11, v11, v11
	v_cvt_pk_bf16_f32 v9, v9, v10
	v_cvt_pk_bf16_f32 v10, v18, v13
	v_addc_co_u32_e32 v13, vcc, 0, v139, vcc
	v_max_f32_e32 v0, 0, v0
	v_max_f32_e32 v1, 0, v1
	v_max_f32_e32 v2, 0, v2
	v_cvt_pk_bf16_f32 v11, v14, v11
	global_store_dwordx4 v[12:13], v[8:11], off
	v_max_f32_e32 v3, v3, v3
	v_max_f32_e32 v4, v4, v4
	v_mul_f32_e32 v8, v0, v0
	v_max_f32_e32 v0, v5, v5
	v_mul_f32_e32 v5, v1, v1
	v_max_f32_e32 v1, v6, v6
	v_mul_f32_e32 v6, v2, v2
	v_max_f32_e32 v2, v7, v7
	v_max_f32_e32 v0, 0, v0
	v_max_f32_e32 v1, 0, v1
	v_max_f32_e32 v2, 0, v2
	v_max_f32_e32 v3, 0, v3
	v_max_f32_e32 v4, 0, v4
	v_mul_f32_e32 v0, v0, v0
	v_mul_f32_e32 v1, v1, v1
	v_mul_f32_e32 v2, v2, v2
	v_mul_f32_e32 v3, v3, v3
	s_and_b64 vcc, exec, s[0:1]
	s_mov_b32 s67, s14
	s_mov_b32 s38, s28
	s_mov_b64 s[4:5], s[36:37]
	s_mov_b64 s[2:3], s[34:35]
	v_mul_f32_e32 v4, v4, v4
	v_cvt_pk_bf16_f32 v0, v4, v0
	v_cvt_pk_bf16_f32 v1, v1, v2
	v_cvt_pk_bf16_f32 v2, v8, v5
	v_cvt_pk_bf16_f32 v3, v6, v3
	global_store_dwordx4 v[16:17], v[0:3], off offset:256
	s_cbranch_vccz .LBB0_253
	s_waitcnt vmcnt(0)
	v_readlane_b32 s62, v254, 59
	s_cmpk_gt_u32 s41, 0xff
	v_readlane_b32 s55, v254, 57
	v_readlane_b32 s58, v254, 58
	v_readlane_b32 s63, v254, 60
	v_readlane_b32 s59, v255, 1
	s_movk_i32 s66, 0x3000
	v_readlane_b32 s49, v255, 18
	s_cbranch_scc1 .LBB0_260
	s_barrier

.LBB0_315:
	v_and_b32_e32 v248, 63, v0
	v_and_b32_e32 v7, 48, v0
	v_lshlrev_b32_e32 v8, 6, v0
	s_movk_i32 s10, 0x3c0
	v_lshlrev_b32_e32 v0, 2, v0
	s_and_b32 s9, s0, 3
	s_lshl_b32 s78, s1, 6
	s_lshl_b32 s1, s1, 13
	v_and_or_b32 v7, v8, s10, v7
	v_and_b32_e32 v0, 32, v0
	v_bitop3_b32 v8, v7, s1, v0 bitop3:0xde
	s_lshl_b32 s1, s9, 12
	v_bitop3_b32 v249, v7, s1, v0 bitop3:0xde
	v_lshlrev_b32_e32 v0, 15, v1
	v_and_b32_e32 v0, 0xffff0000, v0
	v_lshl_add_u32 v0, v2, 12, v0
	v_and_b32_e32 v1, 1, v1
	s_lshl_b32 s79, s9, 5
	s_lshl_b64 s[10:11], s[94:95], 2
	v_readlane_b32 s1, v252, 46
	v_lshl_or_b32 v0, v1, 6, v0
	s_add_u32 s83, s1, s10
	v_readlane_b32 s1, v252, 47
	v_lshl_add_u32 v202, v3, 1, v0
	v_lshlrev_b32_e32 v0, 15, v4
	s_addc_u32 s84, s1, s11
	s_lshl_b32 s1, s0, 2
	s_bfe_u32 s86, s0, 0x10001
	s_add_i32 s74, s78, 0x80
	s_ashr_i32 s0, s82, 9
	v_and_b32_e32 v0, 0xffff0000, v0
	s_waitcnt vmcnt(8)
	s_barrier
	s_waitcnt vmcnt(6)
	s_lshl_b32 s10, s0, 8
	s_lshl_b32 s12, s0, 11
	s_ashr_i32 s0, s74, 7
	v_lshl_add_u32 v0, v5, 12, v0
	v_and_b32_e32 v1, 1, v4
	s_lshl_b32 s14, s0, 8
	s_lshl_b32 s28, s0, 11
	v_lshl_or_b32 v0, v1, 6, v0
	s_and_b32 s85, s1, 4
	s_ashr_i32 s11, s10, 31
	s_ashr_i32 s13, s12, 31
	s_ashr_i32 s15, s14, 31
	s_ashr_i32 s29, s28, 31
	v_mov_b32_e32 v203, v193
	v_lshl_add_u32 v204, v6, 1, v0
	v_mov_b32_e32 v205, v193
	s_mov_b32 s31, 0
	v_add_u32_e32 v250, 0, v8
	s_mov_b64 s[52:53], s[4:5]
	s_mov_b64 s[66:67], s[2:3]
	s_movk_i32 s59, 0x900
	s_barrier
	s_branch .LBB0_319

.LBB0_329:
	s_add_u32 s2, s0, 0xfff80080
	s_addc_u32 s3, s1, -1
	s_add_i32 s9, 0, 0x10000
	s_cmp_eq_u32 s40, 28
	s_cselect_b32 s5, s53, s3
	s_cselect_b32 s4, s52, s2
	s_cselect_b32 s3, s67, s37
	s_cselect_b32 s2, s66, s36
	v_lshl_add_u64 v[176:177], s[0:1], 0, v[202:203]
	s_add_i32 m0, s51, 0xc000
	s_nop 0
	global_load_lds_dwordx4 v[176:177], off
	v_lshl_add_u64 v[176:177], s[0:1], 0, v[204:205]
	s_add_i32 m0, s51, 0xe000
	s_nop 0
	global_load_lds_dwordx4 v[176:177], off
	v_add_u32_e32 v140, 0x10000, v249
	ds_read_b128 v[128:131], v140
	ds_read_b128 v[132:135], v140 offset:1024
	ds_read_b128 v[136:139], v140 offset:2048
	ds_read_b128 v[140:143], v140 offset:3072
	ds_read_b128 v[144:147], v250
	ds_read_b128 v[148:151], v250 offset:1024
	ds_read_b128 v[152:155], v250 offset:2048
	ds_read_b128 v[156:159], v250 offset:3072
	ds_read_b128 v[160:163], v250 offset:4096
	ds_read_b128 v[164:167], v250 offset:5120
	ds_read_b128 v[168:171], v250 offset:6144
	ds_read_b128 v[172:175], v250 offset:7168
	v_add_u32_e32 v188, 0x14000, v249
	ds_read_b128 v[176:179], v188
	ds_read_b128 v[180:183], v188 offset:1024
	ds_read_b128 v[184:187], v188 offset:2048
	ds_read_b128 v[188:191], v188 offset:3072
	s_waitcnt vmcnt(8)
	s_waitcnt lgkmcnt(0)
	s_barrier
	s_setprio 1
	v_mfma_f32_16x16x32_bf16 v[124:127], v[128:131], v[144:147], v[124:127]
	v_mfma_f32_16x16x32_bf16 v[120:123], v[136:139], v[144:147], v[120:123]
	v_mfma_f32_16x16x32_bf16 v[108:111], v[128:131], v[152:155], v[108:111]
	v_mfma_f32_16x16x32_bf16 v[104:107], v[136:139], v[152:155], v[104:107]
	v_mfma_f32_16x16x32_bf16 v[92:95], v[128:131], v[160:163], v[92:95]
	v_mfma_f32_16x16x32_bf16 v[88:91], v[136:139], v[160:163], v[88:91]
	v_mfma_f32_16x16x32_bf16 v[76:79], v[128:131], v[168:171], v[76:79]
	v_mfma_f32_16x16x32_bf16 v[72:75], v[136:139], v[168:171], v[72:75]
	v_mfma_f32_16x16x32_bf16 v[124:127], v[132:135], v[148:151], v[124:127]
	v_mfma_f32_16x16x32_bf16 v[120:123], v[140:143], v[148:151], v[120:123]
	v_mfma_f32_16x16x32_bf16 v[108:111], v[132:135], v[156:159], v[108:111]
	v_mfma_f32_16x16x32_bf16 v[104:107], v[140:143], v[156:159], v[104:107]
	v_mfma_f32_16x16x32_bf16 v[92:95], v[132:135], v[164:167], v[92:95]
	v_mfma_f32_16x16x32_bf16 v[88:91], v[140:143], v[164:167], v[88:91]
	v_mfma_f32_16x16x32_bf16 v[76:79], v[132:135], v[172:175], v[76:79]
	v_mfma_f32_16x16x32_bf16 v[72:75], v[140:143], v[172:175], v[72:75]
	v_mfma_f32_16x16x32_bf16 v[116:119], v[176:179], v[144:147], v[116:119]
	v_mfma_f32_16x16x32_bf16 v[112:115], v[184:187], v[144:147], v[112:115]
	v_mfma_f32_16x16x32_bf16 v[100:103], v[176:179], v[152:155], v[100:103]
	v_mfma_f32_16x16x32_bf16 v[96:99], v[184:187], v[152:155], v[96:99]
	v_mfma_f32_16x16x32_bf16 v[84:87], v[176:179], v[160:163], v[84:87]
	v_mfma_f32_16x16x32_bf16 v[80:83], v[184:187], v[160:163], v[80:83]
	v_mfma_f32_16x16x32_bf16 v[68:71], v[176:179], v[168:171], v[68:71]
	v_mfma_f32_16x16x32_bf16 v[64:67], v[184:187], v[168:171], v[64:67]
	v_mfma_f32_16x16x32_bf16 v[116:119], v[180:183], v[148:151], v[116:119]
	v_mfma_f32_16x16x32_bf16 v[112:115], v[188:191], v[148:151], v[112:115]
	v_mfma_f32_16x16x32_bf16 v[100:103], v[180:183], v[156:159], v[100:103]
	v_mfma_f32_16x16x32_bf16 v[96:99], v[188:191], v[156:159], v[96:99]
	v_mfma_f32_16x16x32_bf16 v[84:87], v[180:183], v[164:167], v[84:87]
	v_mfma_f32_16x16x32_bf16 v[80:83], v[188:191], v[164:167], v[80:83]
	v_mfma_f32_16x16x32_bf16 v[68:71], v[180:183], v[172:175], v[68:71]
	v_mfma_f32_16x16x32_bf16 v[64:67], v[188:191], v[172:175], v[64:67]
	s_setprio 0
	s_barrier
	s_add_i32 s41, 0, 0x14000
	s_add_i32 s9, s9, s50
	v_lshl_add_u64 v[206:207], s[2:3], 0, v[196:197]
	s_mov_b32 m0, s9
	s_nop 0
	global_load_lds_dwordx4 v[206:207], off
	v_lshl_add_u64 v[208:209], s[2:3], 0, v[200:201]
	s_add_i32 m0, s9, 0x2000
	s_nop 0
	global_load_lds_dwordx4 v[208:209], off
	s_mov_b32 m0, s51
	v_lshl_add_u64 v[210:211], s[4:5], 0, v[194:195]
	global_load_lds_dwordx4 v[210:211], off
	v_lshl_add_u64 v[212:213], s[4:5], 0, v[198:199]
	s_mov_b32 m0, s62
	s_nop 0
	global_load_lds_dwordx4 v[212:213], off
	s_add_u32 s46, s2, 0x80000
	s_addc_u32 s47, s3, 0
	s_add_i32 s9, s41, s50
	v_lshl_add_u64 v[144:145], s[46:47], 0, v[196:197]
	s_mov_b32 m0, s9
	s_nop 0
	global_load_lds_dwordx4 v[144:145], off
	v_lshl_add_u64 v[146:147], s[46:47], 0, v[200:201]
	s_add_i32 m0, s9, 0x2000
	s_nop 0
	global_load_lds_dwordx4 v[146:147], off
	ds_read_b128 v[144:147], v250 offset:16384
	ds_read_b128 v[148:151], v250 offset:17408
	ds_read_b128 v[152:155], v250 offset:18432
	ds_read_b128 v[156:159], v250 offset:19456
	ds_read_b128 v[160:163], v250 offset:20480
	ds_read_b128 v[164:167], v250 offset:21504
	ds_read_b128 v[168:171], v250 offset:22528
	ds_read_b128 v[172:175], v250 offset:23552
	s_waitcnt vmcnt(8)
	s_waitcnt lgkmcnt(0)
	s_barrier
	s_setprio 1
	v_mfma_f32_16x16x32_bf16 v[60:63], v[128:131], v[144:147], v[60:63]
	v_mfma_f32_16x16x32_bf16 v[56:59], v[136:139], v[144:147], v[56:59]
	v_mfma_f32_16x16x32_bf16 v[44:47], v[128:131], v[152:155], v[44:47]
	v_mfma_f32_16x16x32_bf16 v[40:43], v[136:139], v[152:155], v[40:43]
	v_mfma_f32_16x16x32_bf16 v[28:31], v[128:131], v[160:163], v[28:31]
	v_mfma_f32_16x16x32_bf16 v[24:27], v[136:139], v[160:163], v[24:27]
	v_mfma_f32_16x16x32_bf16 v[12:15], v[128:131], v[168:171], v[12:15]
	v_mfma_f32_16x16x32_bf16 v[8:11], v[136:139], v[168:171], v[8:11]
	v_mfma_f32_16x16x32_bf16 v[60:63], v[132:135], v[148:151], v[60:63]
	v_mfma_f32_16x16x32_bf16 v[56:59], v[140:143], v[148:151], v[56:59]
	v_mfma_f32_16x16x32_bf16 v[44:47], v[132:135], v[156:159], v[44:47]
	v_mfma_f32_16x16x32_bf16 v[40:43], v[140:143], v[156:159], v[40:43]
	v_mfma_f32_16x16x32_bf16 v[28:31], v[132:135], v[164:167], v[28:31]
	v_mfma_f32_16x16x32_bf16 v[24:27], v[140:143], v[164:167], v[24:27]
	v_mfma_f32_16x16x32_bf16 v[12:15], v[132:135], v[172:175], v[12:15]
	v_mfma_f32_16x16x32_bf16 v[8:11], v[140:143], v[172:175], v[8:11]
	v_mfma_f32_16x16x32_bf16 v[52:55], v[176:179], v[144:147], v[52:55]
	v_mfma_f32_16x16x32_bf16 v[48:51], v[184:187], v[144:147], v[48:51]
	v_mfma_f32_16x16x32_bf16 v[36:39], v[176:179], v[152:155], v[36:39]
	v_mfma_f32_16x16x32_bf16 v[32:35], v[184:187], v[152:155], v[32:35]
	v_mfma_f32_16x16x32_bf16 v[20:23], v[176:179], v[160:163], v[20:23]
	v_mfma_f32_16x16x32_bf16 v[16:19], v[184:187], v[160:163], v[16:19]
	v_mfma_f32_16x16x32_bf16 v[4:7], v[176:179], v[168:171], v[4:7]
	v_mfma_f32_16x16x32_bf16 v[0:3], v[184:187], v[168:171], v[0:3]
	v_mfma_f32_16x16x32_bf16 v[52:55], v[180:183], v[148:151], v[52:55]
	v_mfma_f32_16x16x32_bf16 v[48:51], v[188:191], v[148:151], v[48:51]
	v_mfma_f32_16x16x32_bf16 v[36:39], v[180:183], v[156:159], v[36:39]
	v_mfma_f32_16x16x32_bf16 v[32:35], v[188:191], v[156:159], v[32:35]
	v_mfma_f32_16x16x32_bf16 v[20:23], v[180:183], v[164:167], v[20:23]
	v_mfma_f32_16x16x32_bf16 v[16:19], v[188:191], v[164:167], v[16:19]
	v_mfma_f32_16x16x32_bf16 v[4:7], v[180:183], v[172:175], v[4:7]
	v_mfma_f32_16x16x32_bf16 v[0:3], v[188:191], v[172:175], v[0:3]
	s_setprio 0
	s_barrier
	s_add_i32 s9, 0, 0x18000
	s_add_u32 s4, s4, 0x80000
	s_addc_u32 s5, s5, 0
	s_mov_b32 m0, s63
	v_lshl_add_u64 v[176:177], s[4:5], 0, v[194:195]
	global_load_lds_dwordx4 v[176:177], off
	v_lshl_add_u64 v[176:177], s[4:5], 0, v[198:199]
	s_mov_b32 m0, s69
	s_nop 0
	global_load_lds_dwordx4 v[176:177], off
	v_add_u32_e32 v140, 0x18000, v249
	ds_read_b128 v[128:131], v140
	ds_read_b128 v[132:135], v140 offset:1024
	ds_read_b128 v[136:139], v140 offset:2048
	ds_read_b128 v[140:143], v140 offset:3072
	ds_read_b128 v[144:147], v250 offset:32768
	ds_read_b128 v[148:151], v250 offset:33792
	ds_read_b128 v[152:155], v250 offset:34816
	ds_read_b128 v[156:159], v250 offset:35840
	ds_read_b128 v[160:163], v250 offset:36864
	ds_read_b128 v[164:167], v250 offset:37888
	ds_read_b128 v[168:171], v250 offset:38912
	ds_read_b128 v[172:175], v250 offset:39936
	v_add_u32_e32 v188, 0x1c000, v249
	ds_read_b128 v[176:179], v188
	ds_read_b128 v[180:183], v188 offset:1024
	ds_read_b128 v[184:187], v188 offset:2048
	ds_read_b128 v[188:191], v188 offset:3072
	s_waitcnt vmcnt(8)
	s_waitcnt lgkmcnt(0)
	s_barrier
	s_setprio 1
	v_mfma_f32_16x16x32_bf16 v[124:127], v[128:131], v[144:147], v[124:127]
	v_mfma_f32_16x16x32_bf16 v[120:123], v[136:139], v[144:147], v[120:123]
	v_mfma_f32_16x16x32_bf16 v[108:111], v[128:131], v[152:155], v[108:111]
	v_mfma_f32_16x16x32_bf16 v[104:107], v[136:139], v[152:155], v[104:107]
	v_mfma_f32_16x16x32_bf16 v[92:95], v[128:131], v[160:163], v[92:95]
	v_mfma_f32_16x16x32_bf16 v[88:91], v[136:139], v[160:163], v[88:91]
	v_mfma_f32_16x16x32_bf16 v[76:79], v[128:131], v[168:171], v[76:79]
	v_mfma_f32_16x16x32_bf16 v[72:75], v[136:139], v[168:171], v[72:75]
	v_mfma_f32_16x16x32_bf16 v[124:127], v[132:135], v[148:151], v[124:127]
	v_mfma_f32_16x16x32_bf16 v[120:123], v[140:143], v[148:151], v[120:123]
	v_mfma_f32_16x16x32_bf16 v[108:111], v[132:135], v[156:159], v[108:111]
	v_mfma_f32_16x16x32_bf16 v[104:107], v[140:143], v[156:159], v[104:107]
	v_mfma_f32_16x16x32_bf16 v[92:95], v[132:135], v[164:167], v[92:95]
	v_mfma_f32_16x16x32_bf16 v[88:91], v[140:143], v[164:167], v[88:91]
	v_mfma_f32_16x16x32_bf16 v[76:79], v[132:135], v[172:175], v[76:79]
	v_mfma_f32_16x16x32_bf16 v[72:75], v[140:143], v[172:175], v[72:75]
	v_mfma_f32_16x16x32_bf16 v[116:119], v[176:179], v[144:147], v[116:119]
	v_mfma_f32_16x16x32_bf16 v[112:115], v[184:187], v[144:147], v[112:115]
	v_mfma_f32_16x16x32_bf16 v[100:103], v[176:179], v[152:155], v[100:103]
	v_mfma_f32_16x16x32_bf16 v[96:99], v[184:187], v[152:155], v[96:99]
	v_mfma_f32_16x16x32_bf16 v[84:87], v[176:179], v[160:163], v[84:87]
	v_mfma_f32_16x16x32_bf16 v[80:83], v[184:187], v[160:163], v[80:83]
	v_mfma_f32_16x16x32_bf16 v[68:71], v[176:179], v[168:171], v[68:71]
	v_mfma_f32_16x16x32_bf16 v[64:67], v[184:187], v[168:171], v[64:67]
	v_mfma_f32_16x16x32_bf16 v[116:119], v[180:183], v[148:151], v[116:119]
	v_mfma_f32_16x16x32_bf16 v[112:115], v[188:191], v[148:151], v[112:115]
	v_mfma_f32_16x16x32_bf16 v[100:103], v[180:183], v[156:159], v[100:103]
	v_mfma_f32_16x16x32_bf16 v[96:99], v[188:191], v[156:159], v[96:99]
	v_mfma_f32_16x16x32_bf16 v[84:87], v[180:183], v[164:167], v[84:87]
	v_mfma_f32_16x16x32_bf16 v[80:83], v[188:191], v[164:167], v[80:83]
	v_mfma_f32_16x16x32_bf16 v[68:71], v[180:183], v[172:175], v[68:71]
	v_mfma_f32_16x16x32_bf16 v[64:67], v[188:191], v[172:175], v[64:67]
	s_setprio 0
	s_barrier
	s_add_i32 s4, 0, 0x1c000
	s_add_i32 s5, s9, s50
	v_lshl_add_u64 v[206:207], v[206:207], 0, s[72:73]
	s_mov_b32 m0, s5
	s_nop 0
	global_load_lds_dwordx4 v[206:207], off
	v_lshl_add_u64 v[206:207], v[208:209], 0, s[72:73]
	s_add_i32 m0, s5, 0x2000
	s_nop 0
	global_load_lds_dwordx4 v[206:207], off
	s_mov_b32 m0, s71
	v_lshl_add_u64 v[206:207], v[210:211], 0, s[72:73]
	global_load_lds_dwordx4 v[206:207], off
	v_lshl_add_u64 v[206:207], v[212:213], 0, s[72:73]
	s_mov_b32 m0, s75
	s_nop 0
	global_load_lds_dwordx4 v[206:207], off
	s_add_u32 s2, s2, 0x80080
	s_addc_u32 s3, s3, 0
	s_add_i32 s4, s4, s50
	v_lshl_add_u64 v[144:145], s[2:3], 0, v[196:197]
	s_mov_b32 m0, s4
	s_nop 0
	global_load_lds_dwordx4 v[144:145], off
	v_lshl_add_u64 v[146:147], s[2:3], 0, v[200:201]
	s_add_i32 m0, s4, 0x2000
	s_nop 0
	global_load_lds_dwordx4 v[146:147], off
	ds_read_b128 v[144:147], v250 offset:49152
	ds_read_b128 v[148:151], v250 offset:50176
	ds_read_b128 v[152:155], v250 offset:51200
	ds_read_b128 v[156:159], v250 offset:52224
	ds_read_b128 v[160:163], v250 offset:53248
	ds_read_b128 v[164:167], v250 offset:54272
	ds_read_b128 v[168:171], v250 offset:55296
	ds_read_b128 v[172:175], v250 offset:56320
	s_waitcnt vmcnt(8)
	s_waitcnt lgkmcnt(0)
	s_barrier
	s_setprio 1
	v_mfma_f32_16x16x32_bf16 v[60:63], v[128:131], v[144:147], v[60:63]
	v_mfma_f32_16x16x32_bf16 v[56:59], v[136:139], v[144:147], v[56:59]
	v_mfma_f32_16x16x32_bf16 v[44:47], v[128:131], v[152:155], v[44:47]
	v_mfma_f32_16x16x32_bf16 v[40:43], v[136:139], v[152:155], v[40:43]
	v_mfma_f32_16x16x32_bf16 v[28:31], v[128:131], v[160:163], v[28:31]
	v_mfma_f32_16x16x32_bf16 v[24:27], v[136:139], v[160:163], v[24:27]
	v_mfma_f32_16x16x32_bf16 v[12:15], v[128:131], v[168:171], v[12:15]
	v_mfma_f32_16x16x32_bf16 v[8:11], v[136:139], v[168:171], v[8:11]
	v_mfma_f32_16x16x32_bf16 v[60:63], v[132:135], v[148:151], v[60:63]
	v_mfma_f32_16x16x32_bf16 v[56:59], v[140:143], v[148:151], v[56:59]
	v_mfma_f32_16x16x32_bf16 v[44:47], v[132:135], v[156:159], v[44:47]
	v_mfma_f32_16x16x32_bf16 v[40:43], v[140:143], v[156:159], v[40:43]
	v_mfma_f32_16x16x32_bf16 v[28:31], v[132:135], v[164:167], v[28:31]
	v_mfma_f32_16x16x32_bf16 v[24:27], v[140:143], v[164:167], v[24:27]
	v_mfma_f32_16x16x32_bf16 v[12:15], v[132:135], v[172:175], v[12:15]
	v_mfma_f32_16x16x32_bf16 v[8:11], v[140:143], v[172:175], v[8:11]
	v_mfma_f32_16x16x32_bf16 v[52:55], v[176:179], v[144:147], v[52:55]
	v_mfma_f32_16x16x32_bf16 v[48:51], v[184:187], v[144:147], v[48:51]
	v_mfma_f32_16x16x32_bf16 v[36:39], v[176:179], v[152:155], v[36:39]
	v_mfma_f32_16x16x32_bf16 v[32:35], v[184:187], v[152:155], v[32:35]
	v_mfma_f32_16x16x32_bf16 v[20:23], v[176:179], v[160:163], v[20:23]
	v_mfma_f32_16x16x32_bf16 v[16:19], v[184:187], v[160:163], v[16:19]
	v_mfma_f32_16x16x32_bf16 v[4:7], v[176:179], v[168:171], v[4:7]
	v_mfma_f32_16x16x32_bf16 v[0:3], v[184:187], v[168:171], v[0:3]
	v_mfma_f32_16x16x32_bf16 v[52:55], v[180:183], v[148:151], v[52:55]
	v_mfma_f32_16x16x32_bf16 v[48:51], v[188:191], v[148:151], v[48:51]
	v_mfma_f32_16x16x32_bf16 v[36:39], v[180:183], v[156:159], v[36:39]
	v_mfma_f32_16x16x32_bf16 v[32:35], v[188:191], v[156:159], v[32:35]
	v_mfma_f32_16x16x32_bf16 v[20:23], v[180:183], v[164:167], v[20:23]
	v_mfma_f32_16x16x32_bf16 v[16:19], v[188:191], v[164:167], v[16:19]
	v_mfma_f32_16x16x32_bf16 v[4:7], v[180:183], v[172:175], v[4:7]
	v_mfma_f32_16x16x32_bf16 v[0:3], v[188:191], v[172:175], v[0:3]
	s_setprio 0
	s_add_i32 s40, s40, 2
	s_add_u32 s0, s0, 0x100
	s_addc_u32 s1, s1, 0
	s_add_u32 s36, s36, 0x100
	s_addc_u32 s37, s37, 0
	s_cmp_gt_u32 s40, 29
	s_barrier
	s_cbranch_scc0 .LBB0_329
	v_mov_b32 v128, v248
	s_cmp_gt_u32 s38, 1
	v_and_b32_e32 v246, 15, v128
	v_ashrrev_i32_e32 v247, 4, v128
	s_mov_b64 s[0:1], -1
	s_cbranch_scc0 .LBB0_413
	s_and_b32 s4, s39, 3
	s_cmp_lg_u32 s38, 2
	s_cbranch_scc0 .LBB0_400
	s_lshl_b32 s40, s49, 8
	v_or_b32_e32 v128, s78, v246
	v_add_u32_e32 v134, s40, v128
	v_min_i32_e32 v130, 0x2000, v134
	v_lshlrev_b32_e32 v130, 8, v130
	v_add_lshl_u32 v206, v247, s85, 2
	v_readlane_b32 s0, v251, 61
	v_and_b32_e32 v192, 0x7cf00, v130
	v_or_b32_e32 v130, 16, v134
	v_ashrrev_i32_e32 v207, 31, v206
	v_readlane_b32 s1, v251, 62
	v_min_i32_e32 v130, 0x2000, v130
	v_or_b32_e32 v132, 32, v134
	v_lshl_add_u64 v[128:129], v[206:207], 2, s[0:1]
	v_lshlrev_b32_e32 v130, 8, v130
	v_min_i32_e32 v132, 0x2000, v132
	v_lshl_add_u64 v[210:211], v[128:129], 0, v[192:193]
	v_and_b32_e32 v192, 0x7ff00, v130
	v_lshlrev_b32_e32 v132, 8, v132
	v_lshl_add_u64 v[130:131], v[128:129], 0, v[192:193]
	v_and_b32_e32 v192, 0x7ff00, v132
	global_load_dwordx4 v[188:191], v[210:211], off offset:128
	global_load_dwordx4 v[176:179], v[130:131], off
	v_lshl_add_u64 v[132:133], v[128:129], 0, v[192:193]
	global_load_dwordx4 v[180:183], v[130:131], off offset:128
	global_load_dwordx4 v[168:171], v[132:133], off
	v_or_b32_e32 v130, 48, v134
	v_min_i32_e32 v130, 0x2000, v130
	v_lshlrev_b32_e32 v130, 8, v130
	v_and_b32_e32 v192, 0x7ff00, v130
	v_lshl_add_u64 v[130:131], v[128:129], 0, v[192:193]
	global_load_dwordx4 v[172:175], v[132:133], off offset:128
	global_load_dwordx4 v[160:163], v[130:131], off
	v_add_u32_e32 v132, 0x80, v134
	v_min_i32_e32 v132, 0x2000, v132
	v_lshlrev_b32_e32 v132, 8, v132
	v_and_b32_e32 v192, 0x7ff00, v132
	v_lshl_add_u64 v[132:133], v[128:129], 0, v[192:193]
	global_load_dwordx4 v[164:167], v[130:131], off offset:128
	global_load_dwordx4 v[152:155], v[132:133], off
	v_add_u32_e32 v130, 0x90, v134
	v_min_i32_e32 v130, 0x2000, v130
	v_lshlrev_b32_e32 v130, 8, v130
	v_and_b32_e32 v192, 0x7ff00, v130
	v_lshl_add_u64 v[130:131], v[128:129], 0, v[192:193]
	global_load_dwordx4 v[156:159], v[132:133], off offset:128
	global_load_dwordx4 v[144:147], v[130:131], off
	v_add_u32_e32 v132, 0xa0, v134
	v_min_i32_e32 v132, 0x2000, v132
	v_lshlrev_b32_e32 v132, 8, v132
	v_and_b32_e32 v192, 0x7ff00, v132
	v_lshl_add_u64 v[132:133], v[128:129], 0, v[192:193]
	global_load_dwordx4 v[148:151], v[130:131], off offset:128
	global_load_dwordx4 v[136:139], v[132:133], off
	v_add_u32_e32 v130, 0xb0, v134
	v_min_i32_e32 v130, 0x2000, v130
	v_lshlrev_b32_e32 v130, 8, v130
	v_and_b32_e32 v192, 0x7ff00, v130
	v_lshl_add_u64 v[128:129], v[128:129], 0, v[192:193]
	global_load_dwordx4 v[140:143], v[132:133], off offset:128
	s_nop 0
	global_load_dwordx4 v[132:135], v[128:129], off
	s_nop 0
	global_load_dwordx4 v[128:131], v[128:129], off offset:128
	s_add_i32 s2, s40, s78
	v_or_b32_e32 v208, s2, v246
	v_mov_b32_e32 v184, 1.0
	v_cmp_gt_i32_e32 vcc, s33, v208
	v_mov_b32_e32 v185, v184
	v_mov_b32_e32 v186, v184
	v_mov_b32_e32 v187, v184
	s_and_saveexec_b64 s[0:1], vcc
	s_cbranch_execz .LBB0_334
	global_load_dwordx4 v[184:187], v[210:211], off
